# DeltaNet forward-substitution block: LDS row reads hoisted with rotating destination quads (same math); early DMA issue in MT=6 loops
# speedup vs baseline: 1.1469x; 1.0263x over previous
.LBB0_412:
	s_ashr_i32 s0, s22, 6
	s_mul_i32 s0, s0, s17
	s_add_i32 s0, s0, s15
	s_cmp_gt_i32 s0, 31
	s_mov_b32 s6, 2
	s_cbranch_scc1 .LBB0_499
	s_ashr_i32 s1, s0, 31
	s_lshr_b32 s1, s1, 29
	s_add_i32 s5, s0, s1
	s_and_b32 s1, s5, -8
	s_and_b32 s4, s22, 7
	s_or_b32 s4, s1, s4
	s_sub_i32 s1, s0, s1
	s_lshl_b32 s6, s1, 3
	s_bfe_u32 s1, s22, 0x30003
	s_or_b32 s7, s6, s1
	s_cmp_gt_i32 s4, 31
	s_cselect_b64 s[10:11], -1, 0
	s_cmp_gt_i32 s7, 56
	s_cselect_b64 s[12:13], -1, 0
	s_or_b64 s[10:11], s[10:11], s[12:13]
	s_mov_b32 s6, 4
	s_and_b64 vcc, exec, s[10:11]
	s_cbranch_vccnz .LBB0_499
	s_ashr_i32 s23, s5, 3
	s_and_b32 s5, s16, 7
	s_lshl_b32 s4, s4, 8
	s_lshl_b32 s24, s5, 8
	s_ashr_i32 s5, s4, 31
	s_lshl_b64 s[12:13], s[4:5], 11
	v_lshl_add_u64 v[0:1], v[186:187], 0, s[12:13]
	v_add_co_u32_e32 v2, vcc, 0x10000, v0
	s_lshl_b32 s10, s7, 7
	s_nop 0
	v_addc_co_u32_e32 v3, vcc, 0, v1, vcc
	s_nop 0
	v_readfirstlane_b32 s98, v0
	v_readfirstlane_b32 s99, v1
	v_add_co_u32_e32 v2, vcc, 0x20000, v0
	s_ashr_i32 s11, s10, 31
	s_nop 0
	v_addc_co_u32_e32 v3, vcc, 0, v1, vcc
	v_add_co_u32_e32 v4, vcc, 0x30000, v0
	s_lshl_b64 s[6:7], s[10:11], 11
	s_nop 0
	v_addc_co_u32_e32 v5, vcc, 0, v1, vcc
	v_add_co_u32_e32 v2, vcc, 0x40000, v0
	s_mov_b32 s5, 0x10000
	s_nop 0
	v_addc_co_u32_e32 v3, vcc, 0, v1, vcc
	v_add_co_u32_e32 v4, vcc, 0x50000, v0
	s_lshl_b32 s0, s0, 3
	s_nop 0
	v_addc_co_u32_e32 v5, vcc, 0, v1, vcc
	v_add_co_u32_e32 v2, vcc, 0x60000, v0
	s_or_b32 s0, s0, s1
	s_nop 0
	v_addc_co_u32_e32 v3, vcc, 0, v1, vcc
	v_add_co_u32_e32 v0, vcc, 0x70000, v0
	s_lshl_b32 s1, s23, 6
	s_nop 0
	v_addc_co_u32_e32 v1, vcc, 0, v1, vcc
	v_lshl_add_u64 v[0:1], v[188:189], 0, s[6:7]
	v_add_co_u32_e32 v2, vcc, s5, v0
	s_mov_b32 s5, 0x20000
	s_nop 0
	v_addc_co_u32_e32 v3, vcc, 0, v1, vcc
	s_nop 0
	v_readfirstlane_b32 s100, v0
	v_readfirstlane_b32 s101, v1
	v_add_co_u32_e32 v2, vcc, s5, v0
	s_mov_b32 s5, 0x30000
	s_nop 0
	v_addc_co_u32_e32 v3, vcc, 0, v1, vcc
	v_add_co_u32_e32 v0, vcc, s5, v0
	s_lshl_b32 s5, s23, 11
	s_nop 0
	v_addc_co_u32_e32 v1, vcc, 0, v1, vcc
	s_sub_i32 s0, s0, s1
	s_or_b32 s6, s5, s24
	s_lshl_b32 s0, s0, 7
	s_ashr_i32 s7, s6, 31
	s_ashr_i32 s1, s0, 31
	s_lshl_b64 s[6:7], s[6:7], 11
	s_lshl_b64 s[0:1], s[0:1], 11
	v_mov_b32_e32 v124, 0
	v_lshl_add_u64 v[192:193], v[190:191], 0, s[6:7]
	v_lshl_add_u64 v[194:195], v[190:191], 0, s[0:1]
	s_mov_b64 s[0:1], 0
	v_mov_b32_e32 v125, v124
	v_mov_b32_e32 v126, v124
	v_mov_b32_e32 v127, v124
	v_mov_b32_e32 v80, v124
	v_mov_b32_e32 v81, v124
	v_mov_b32_e32 v82, v124
	v_mov_b32_e32 v83, v124
	v_mov_b32_e32 v88, v124
	v_mov_b32_e32 v89, v124
	v_mov_b32_e32 v90, v124
	v_mov_b32_e32 v91, v124
	v_mov_b32_e32 v92, v124
	v_mov_b32_e32 v93, v124
	v_mov_b32_e32 v94, v124
	v_mov_b32_e32 v95, v124
	v_mov_b32_e32 v100, v124
	v_mov_b32_e32 v101, v124
	v_mov_b32_e32 v102, v124
	v_mov_b32_e32 v103, v124
	v_mov_b32_e32 v104, v124
	v_mov_b32_e32 v105, v124
	v_mov_b32_e32 v106, v124
	v_mov_b32_e32 v107, v124
	v_mov_b32_e32 v48, v124
	v_mov_b32_e32 v49, v124
	v_mov_b32_e32 v50, v124
	v_mov_b32_e32 v51, v124
	v_mov_b32_e32 v40, v124
	v_mov_b32_e32 v41, v124
	v_mov_b32_e32 v42, v124
	v_mov_b32_e32 v43, v124
	v_mov_b32_e32 v52, v124
	v_mov_b32_e32 v53, v124
	v_mov_b32_e32 v54, v124
	v_mov_b32_e32 v55, v124
	v_mov_b32_e32 v44, v124
	v_mov_b32_e32 v45, v124
	v_mov_b32_e32 v46, v124
	v_mov_b32_e32 v47, v124
	v_mov_b32_e32 v32, v124
	v_mov_b32_e32 v33, v124
	v_mov_b32_e32 v34, v124
	v_mov_b32_e32 v35, v124
	v_mov_b32_e32 v12, v124
	v_mov_b32_e32 v13, v124
	v_mov_b32_e32 v14, v124
	v_mov_b32_e32 v15, v124
	v_mov_b32_e32 v36, v124
	v_mov_b32_e32 v37, v124
	v_mov_b32_e32 v38, v124
	v_mov_b32_e32 v39, v124
	v_mov_b32_e32 v16, v124
	v_mov_b32_e32 v17, v124
	v_mov_b32_e32 v18, v124
	v_mov_b32_e32 v19, v124
	v_mov_b32_e32 v8, v124
	v_mov_b32_e32 v9, v124
	v_mov_b32_e32 v10, v124
	v_mov_b32_e32 v11, v124
	v_mov_b32_e32 v0, v124
	v_mov_b32_e32 v1, v124
	v_mov_b32_e32 v2, v124
	v_mov_b32_e32 v3, v124
	v_mov_b32_e32 v20, v124
	v_mov_b32_e32 v21, v124
	v_mov_b32_e32 v22, v124
	v_mov_b32_e32 v23, v124
	v_mov_b32_e32 v24, v124
	v_mov_b32_e32 v25, v124
	v_mov_b32_e32 v26, v124
	v_mov_b32_e32 v27, v124
	v_mov_b32_e32 v4, v124
	v_mov_b32_e32 v5, v124
	v_mov_b32_e32 v6, v124
	v_mov_b32_e32 v7, v124
	v_mov_b32_e32 v28, v124
	v_mov_b32_e32 v29, v124
	v_mov_b32_e32 v30, v124
	v_mov_b32_e32 v31, v124
	v_mov_b32_e32 v56, v124
	v_mov_b32_e32 v57, v124
	v_mov_b32_e32 v58, v124
	v_mov_b32_e32 v59, v124
	v_mov_b32_e32 v60, v124
	v_mov_b32_e32 v61, v124
	v_mov_b32_e32 v62, v124
	v_mov_b32_e32 v63, v124
	v_mov_b32_e32 v64, v124
	v_mov_b32_e32 v65, v124
	v_mov_b32_e32 v66, v124
	v_mov_b32_e32 v67, v124
	v_mov_b32_e32 v68, v124
	v_mov_b32_e32 v69, v124
	v_mov_b32_e32 v70, v124
	v_mov_b32_e32 v71, v124
	v_mov_b32_e32 v72, v124
	v_mov_b32_e32 v73, v124
	v_mov_b32_e32 v74, v124
	v_mov_b32_e32 v75, v124
	v_mov_b32_e32 v76, v124
	v_mov_b32_e32 v77, v124
	v_mov_b32_e32 v78, v124
	v_mov_b32_e32 v79, v124
	v_mov_b32_e32 v84, v124
	v_mov_b32_e32 v85, v124
	v_mov_b32_e32 v86, v124
	v_mov_b32_e32 v87, v124
	v_mov_b32_e32 v96, v124
	v_mov_b32_e32 v97, v124
	v_mov_b32_e32 v98, v124
	v_mov_b32_e32 v99, v124
	v_mov_b32_e32 v108, v124
	v_mov_b32_e32 v109, v124
	v_mov_b32_e32 v110, v124
	v_mov_b32_e32 v111, v124
	v_mov_b32_e32 v112, v124
	v_mov_b32_e32 v113, v124
	v_mov_b32_e32 v114, v124
	v_mov_b32_e32 v115, v124
	v_mov_b32_e32 v116, v124
	v_mov_b32_e32 v117, v124
	v_mov_b32_e32 v118, v124
	v_mov_b32_e32 v119, v124
	v_mov_b32_e32 v120, v124
	v_mov_b32_e32 v121, v124
	v_mov_b32_e32 v122, v124
	v_mov_b32_e32 v123, v124
	v_mov_b32_e32 v194, 0
	ds_read_b64 v[192:193], v194
	v_and_b32_e32 v195, 63, v196
	v_lshrrev_b32_e32 v242, 3, v195
	v_and_b32_e32 v239, 7, v195
	v_xor_b32_e32 v239, v239, v242
	v_lshlrev_b32_e32 v239, 4, v239
	v_mul_u32_u24_e32 v242, 2048, v242
	v_add_u32_e32 v252, v242, v239
	v_add_u32_e32 v251, 65536, v252
	v_add_u32_e32 v248, 131072, v252
	v_add_u32_e32 v249, 196608, v252
	v_add_u32_e32 v250, 262144, v252
	v_add_u32_e32 v247, 327680, v252
	v_add_u32_e32 v244, 393216, v252
	v_add_u32_e32 v245, 458752, v252
	v_lshrrev_b32_e32 v242, 6, v196
	v_lshrrev_b32_e32 v239, 1, v242
	v_and_b32_e32 v242, 1, v242
	v_and_b32_e32 v236, 15, v195
	v_lshrrev_b32_e32 v237, 4, v195
	v_and_b32_e32 v238, 7, v236
	v_xor_b32_e32 v237, v237, v238
	v_lshlrev_b32_e32 v237, 4, v237
	v_lshlrev_b32_e32 v239, 7, v239
	v_add_u32_e32 v239, v239, v236
	v_lshl_add_u32 v246, v239, 7, v237
	v_xor_b32_e32 v243, 64, v246
	v_lshlrev_b32_e32 v242, 6, v242
	v_add_u32_e32 v242, v242, v236
	v_lshl_add_u32 v240, v242, 7, v237
	v_add_u32_e32 v240, 65536, v240
	v_xor_b32_e32 v241, 64, v240
	v_lshrrev_b32_e32 v242, 6, v196
	v_lshlrev_b32_e32 v242, 10, v242
	s_nop 0
	v_readfirstlane_b32 s0, v242
	s_waitcnt lgkmcnt(0)
	s_barrier
	s_add_u32 m0, s0, 0
	s_nop 0
	global_load_lds_dwordx4 v252, s[98:99]
	s_add_u32 m0, s0, 4096
	s_nop 0
	global_load_lds_dwordx4 v251, s[98:99]
	s_add_u32 m0, s0, 8192
	s_nop 0
	global_load_lds_dwordx4 v248, s[98:99]
	s_add_u32 m0, s0, 12288
	s_nop 0
	global_load_lds_dwordx4 v249, s[98:99]
	s_add_u32 m0, s0, 16384
	s_nop 0
	global_load_lds_dwordx4 v250, s[98:99]
	s_add_u32 m0, s0, 20480
	s_nop 0
	global_load_lds_dwordx4 v247, s[98:99]
	s_add_u32 m0, s0, 24576
	s_nop 0
	global_load_lds_dwordx4 v244, s[98:99]
	s_add_u32 m0, s0, 28672
	s_nop 0
	global_load_lds_dwordx4 v245, s[98:99]
	s_add_u32 m0, s0, 65536
	s_nop 0
	global_load_lds_dwordx4 v252, s[100:101]
	s_add_u32 m0, s0, 69632
	s_nop 0
	global_load_lds_dwordx4 v251, s[100:101]
	s_add_u32 m0, s0, 73728
	s_nop 0
	global_load_lds_dwordx4 v248, s[100:101]
	s_add_u32 m0, s0, 77824
	s_nop 0
	global_load_lds_dwordx4 v249, s[100:101]
	s_add_u32 s98, s98, 0x80
	s_addc_u32 s99, s99, 0
	s_add_u32 s100, s100, 0x80
	s_addc_u32 s101, s101, 0
	s_mov_b32 s1, 7
.Lg8p3_loop:
	s_waitcnt vmcnt(0) lgkmcnt(0)
	s_barrier
	s_add_u32 m0, s0, 32768
	ds_read_b128 v[128:131], v240 offset:0
	global_load_lds_dwordx4 v252, s[98:99]
	s_add_u32 m0, s0, 36864
	ds_read_b128 v[136:139], v240 offset:2048
	global_load_lds_dwordx4 v251, s[98:99]
	s_add_u32 m0, s0, 40960
	ds_read_b128 v[144:147], v240 offset:4096
	global_load_lds_dwordx4 v248, s[98:99]
	s_add_u32 m0, s0, 45056
	ds_read_b128 v[152:155], v240 offset:6144
	global_load_lds_dwordx4 v249, s[98:99]
	s_add_u32 m0, s0, 49152
	ds_read_b128 v[132:135], v241 offset:0
	global_load_lds_dwordx4 v250, s[98:99]
	s_add_u32 m0, s0, 53248
	ds_read_b128 v[140:143], v241 offset:2048
	global_load_lds_dwordx4 v247, s[98:99]
	s_add_u32 m0, s0, 57344
	ds_read_b128 v[148:151], v241 offset:4096
	global_load_lds_dwordx4 v244, s[98:99]
	s_add_u32 m0, s0, 61440
	ds_read_b128 v[156:159], v241 offset:6144
	global_load_lds_dwordx4 v245, s[98:99]
	ds_read_b128 v[160:163], v246 offset:0
	ds_read_b128 v[164:167], v246 offset:2048
	ds_read_b128 v[168:171], v246 offset:4096
	ds_read_b128 v[172:175], v246 offset:6144
	s_waitcnt lgkmcnt(4)
	s_barrier
	s_waitcnt lgkmcnt(3)
	s_add_u32 m0, s0, 65536
	v_mfma_f32_16x16x32_bf16 v[120:123], v[128:131], v[160:163], v[120:123]
	ds_read_b128 v[176:179], v246 offset:8192
	global_load_lds_dwordx4 v252, s[100:101]
	v_mfma_f32_16x16x32_bf16 v[116:119], v[136:139], v[160:163], v[116:119]
	s_add_u32 m0, s0, 69632
	v_mfma_f32_16x16x32_bf16 v[112:115], v[144:147], v[160:163], v[112:115]
	global_load_lds_dwordx4 v251, s[100:101]
	v_mfma_f32_16x16x32_bf16 v[108:111], v[152:155], v[160:163], v[108:111]
	s_waitcnt lgkmcnt(3)
	s_add_u32 m0, s0, 73728
	v_mfma_f32_16x16x32_bf16 v[96:99], v[128:131], v[164:167], v[96:99]
	ds_read_b128 v[180:183], v246 offset:10240
	global_load_lds_dwordx4 v248, s[100:101]
	v_mfma_f32_16x16x32_bf16 v[84:87], v[136:139], v[164:167], v[84:87]
	s_add_u32 m0, s0, 77824
	v_mfma_f32_16x16x32_bf16 v[76:79], v[144:147], v[164:167], v[76:79]
	global_load_lds_dwordx4 v249, s[100:101]
	v_mfma_f32_16x16x32_bf16 v[72:75], v[152:155], v[164:167], v[72:75]
	s_waitcnt lgkmcnt(3)
	v_mfma_f32_16x16x32_bf16 v[68:71], v[128:131], v[168:171], v[68:71]
	ds_read_b128 v[160:163], v246 offset:12288
	v_mfma_f32_16x16x32_bf16 v[64:67], v[136:139], v[168:171], v[64:67]
	v_mfma_f32_16x16x32_bf16 v[60:63], v[144:147], v[168:171], v[60:63]
	v_mfma_f32_16x16x32_bf16 v[56:59], v[152:155], v[168:171], v[56:59]
	s_waitcnt lgkmcnt(3)
	v_mfma_f32_16x16x32_bf16 v[28:31], v[128:131], v[172:175], v[28:31]
	ds_read_b128 v[164:167], v246 offset:14336
	v_mfma_f32_16x16x32_bf16 v[4:7], v[136:139], v[172:175], v[4:7]
	v_mfma_f32_16x16x32_bf16 v[24:27], v[144:147], v[172:175], v[24:27]
	v_mfma_f32_16x16x32_bf16 v[20:23], v[152:155], v[172:175], v[20:23]
	s_waitcnt lgkmcnt(3)
	v_mfma_f32_16x16x32_bf16 v[0:3], v[128:131], v[176:179], v[0:3]
	ds_read_b128 v[168:171], v243 offset:0
	v_mfma_f32_16x16x32_bf16 v[8:11], v[136:139], v[176:179], v[8:11]
	v_mfma_f32_16x16x32_bf16 v[16:19], v[144:147], v[176:179], v[16:19]
	v_mfma_f32_16x16x32_bf16 v[36:39], v[152:155], v[176:179], v[36:39]
	s_waitcnt lgkmcnt(3)
	v_mfma_f32_16x16x32_bf16 v[12:15], v[128:131], v[180:183], v[12:15]
	ds_read_b128 v[172:175], v243 offset:2048
	v_mfma_f32_16x16x32_bf16 v[32:35], v[136:139], v[180:183], v[32:35]
	v_mfma_f32_16x16x32_bf16 v[44:47], v[144:147], v[180:183], v[44:47]
	v_mfma_f32_16x16x32_bf16 v[52:55], v[152:155], v[180:183], v[52:55]
	s_waitcnt lgkmcnt(3)
	v_mfma_f32_16x16x32_bf16 v[40:43], v[128:131], v[160:163], v[40:43]
	ds_read_b128 v[176:179], v243 offset:4096
	v_mfma_f32_16x16x32_bf16 v[48:51], v[136:139], v[160:163], v[48:51]
	v_mfma_f32_16x16x32_bf16 v[104:107], v[144:147], v[160:163], v[104:107]
	v_mfma_f32_16x16x32_bf16 v[100:103], v[152:155], v[160:163], v[100:103]
	s_waitcnt lgkmcnt(3)
	v_mfma_f32_16x16x32_bf16 v[92:95], v[128:131], v[164:167], v[92:95]
	ds_read_b128 v[180:183], v243 offset:6144
	v_mfma_f32_16x16x32_bf16 v[88:91], v[136:139], v[164:167], v[88:91]
	v_mfma_f32_16x16x32_bf16 v[80:83], v[144:147], v[164:167], v[80:83]
	v_mfma_f32_16x16x32_bf16 v[124:127], v[152:155], v[164:167], v[124:127]
	s_waitcnt lgkmcnt(3)
	v_mfma_f32_16x16x32_bf16 v[120:123], v[132:135], v[168:171], v[120:123]
	ds_read_b128 v[160:163], v243 offset:8192
	v_mfma_f32_16x16x32_bf16 v[116:119], v[140:143], v[168:171], v[116:119]
	v_mfma_f32_16x16x32_bf16 v[112:115], v[148:151], v[168:171], v[112:115]
	v_mfma_f32_16x16x32_bf16 v[108:111], v[156:159], v[168:171], v[108:111]
	s_waitcnt lgkmcnt(3)
	v_mfma_f32_16x16x32_bf16 v[96:99], v[132:135], v[172:175], v[96:99]
	ds_read_b128 v[164:167], v243 offset:10240
	v_mfma_f32_16x16x32_bf16 v[84:87], v[140:143], v[172:175], v[84:87]
	v_mfma_f32_16x16x32_bf16 v[76:79], v[148:151], v[172:175], v[76:79]
	v_mfma_f32_16x16x32_bf16 v[72:75], v[156:159], v[172:175], v[72:75]
	s_waitcnt lgkmcnt(3)
	v_mfma_f32_16x16x32_bf16 v[68:71], v[132:135], v[176:179], v[68:71]
	ds_read_b128 v[168:171], v243 offset:12288
	v_mfma_f32_16x16x32_bf16 v[64:67], v[140:143], v[176:179], v[64:67]
	v_mfma_f32_16x16x32_bf16 v[60:63], v[148:151], v[176:179], v[60:63]
	v_mfma_f32_16x16x32_bf16 v[56:59], v[156:159], v[176:179], v[56:59]
	s_waitcnt lgkmcnt(3)
	v_mfma_f32_16x16x32_bf16 v[28:31], v[132:135], v[180:183], v[28:31]
	ds_read_b128 v[172:175], v243 offset:14336
	v_mfma_f32_16x16x32_bf16 v[4:7], v[140:143], v[180:183], v[4:7]
	v_mfma_f32_16x16x32_bf16 v[24:27], v[148:151], v[180:183], v[24:27]
	v_mfma_f32_16x16x32_bf16 v[20:23], v[156:159], v[180:183], v[20:23]
	s_waitcnt lgkmcnt(3)
	v_mfma_f32_16x16x32_bf16 v[0:3], v[132:135], v[160:163], v[0:3]
	v_mfma_f32_16x16x32_bf16 v[8:11], v[140:143], v[160:163], v[8:11]
	v_mfma_f32_16x16x32_bf16 v[16:19], v[148:151], v[160:163], v[16:19]
	v_mfma_f32_16x16x32_bf16 v[36:39], v[156:159], v[160:163], v[36:39]
	s_waitcnt lgkmcnt(2)
	v_mfma_f32_16x16x32_bf16 v[12:15], v[132:135], v[164:167], v[12:15]
	v_mfma_f32_16x16x32_bf16 v[32:35], v[140:143], v[164:167], v[32:35]
	v_mfma_f32_16x16x32_bf16 v[44:47], v[148:151], v[164:167], v[44:47]
	v_mfma_f32_16x16x32_bf16 v[52:55], v[156:159], v[164:167], v[52:55]
	s_waitcnt lgkmcnt(1)
	v_mfma_f32_16x16x32_bf16 v[40:43], v[132:135], v[168:171], v[40:43]
	v_mfma_f32_16x16x32_bf16 v[48:51], v[140:143], v[168:171], v[48:51]
	v_mfma_f32_16x16x32_bf16 v[104:107], v[148:151], v[168:171], v[104:107]
	v_mfma_f32_16x16x32_bf16 v[100:103], v[156:159], v[168:171], v[100:103]
	s_waitcnt lgkmcnt(0)
	v_mfma_f32_16x16x32_bf16 v[92:95], v[132:135], v[172:175], v[92:95]
	v_mfma_f32_16x16x32_bf16 v[88:91], v[140:143], v[172:175], v[88:91]
	v_mfma_f32_16x16x32_bf16 v[80:83], v[148:151], v[172:175], v[80:83]
	v_mfma_f32_16x16x32_bf16 v[124:127], v[156:159], v[172:175], v[124:127]
	s_add_u32 s98, s98, 0x80
	s_addc_u32 s99, s99, 0
	s_add_u32 s100, s100, 0x80
	s_addc_u32 s101, s101, 0
	s_waitcnt vmcnt(0) lgkmcnt(0)
	s_barrier
	s_add_u32 m0, s0, 0
	ds_read_b128 v[128:131], v240 offset:0
	global_load_lds_dwordx4 v252, s[98:99]
	s_add_u32 m0, s0, 4096
	ds_read_b128 v[136:139], v240 offset:2048
	global_load_lds_dwordx4 v251, s[98:99]
	s_add_u32 m0, s0, 8192
	ds_read_b128 v[144:147], v240 offset:4096
	global_load_lds_dwordx4 v248, s[98:99]
	s_add_u32 m0, s0, 12288
	ds_read_b128 v[152:155], v240 offset:6144
	global_load_lds_dwordx4 v249, s[98:99]
	s_add_u32 m0, s0, 16384
	ds_read_b128 v[132:135], v241 offset:0
	global_load_lds_dwordx4 v250, s[98:99]
	s_add_u32 m0, s0, 20480
	ds_read_b128 v[140:143], v241 offset:2048
	global_load_lds_dwordx4 v247, s[98:99]
	s_add_u32 m0, s0, 24576
	ds_read_b128 v[148:151], v241 offset:4096
	global_load_lds_dwordx4 v244, s[98:99]
	s_add_u32 m0, s0, 28672
	ds_read_b128 v[156:159], v241 offset:6144
	global_load_lds_dwordx4 v245, s[98:99]
	ds_read_b128 v[160:163], v246 offset:32768
	ds_read_b128 v[164:167], v246 offset:34816
	ds_read_b128 v[168:171], v246 offset:36864
	ds_read_b128 v[172:175], v246 offset:38912
	s_waitcnt lgkmcnt(4)
	s_barrier
	s_waitcnt lgkmcnt(3)
	s_add_u32 m0, s0, 65536
	v_mfma_f32_16x16x32_bf16 v[120:123], v[128:131], v[160:163], v[120:123]
	ds_read_b128 v[176:179], v246 offset:40960
	global_load_lds_dwordx4 v252, s[100:101]
	v_mfma_f32_16x16x32_bf16 v[116:119], v[136:139], v[160:163], v[116:119]
	s_add_u32 m0, s0, 69632
	v_mfma_f32_16x16x32_bf16 v[112:115], v[144:147], v[160:163], v[112:115]
	global_load_lds_dwordx4 v251, s[100:101]
	v_mfma_f32_16x16x32_bf16 v[108:111], v[152:155], v[160:163], v[108:111]
	s_waitcnt lgkmcnt(3)
	s_add_u32 m0, s0, 73728
	v_mfma_f32_16x16x32_bf16 v[96:99], v[128:131], v[164:167], v[96:99]
	ds_read_b128 v[180:183], v246 offset:43008
	global_load_lds_dwordx4 v248, s[100:101]
	v_mfma_f32_16x16x32_bf16 v[84:87], v[136:139], v[164:167], v[84:87]
	s_add_u32 m0, s0, 77824
	v_mfma_f32_16x16x32_bf16 v[76:79], v[144:147], v[164:167], v[76:79]
	global_load_lds_dwordx4 v249, s[100:101]
	v_mfma_f32_16x16x32_bf16 v[72:75], v[152:155], v[164:167], v[72:75]
	s_waitcnt lgkmcnt(3)
	v_mfma_f32_16x16x32_bf16 v[68:71], v[128:131], v[168:171], v[68:71]
	ds_read_b128 v[160:163], v246 offset:45056
	v_mfma_f32_16x16x32_bf16 v[64:67], v[136:139], v[168:171], v[64:67]
	v_mfma_f32_16x16x32_bf16 v[60:63], v[144:147], v[168:171], v[60:63]
	v_mfma_f32_16x16x32_bf16 v[56:59], v[152:155], v[168:171], v[56:59]
	s_waitcnt lgkmcnt(3)
	v_mfma_f32_16x16x32_bf16 v[28:31], v[128:131], v[172:175], v[28:31]
	ds_read_b128 v[164:167], v246 offset:47104
	v_mfma_f32_16x16x32_bf16 v[4:7], v[136:139], v[172:175], v[4:7]
	v_mfma_f32_16x16x32_bf16 v[24:27], v[144:147], v[172:175], v[24:27]
	v_mfma_f32_16x16x32_bf16 v[20:23], v[152:155], v[172:175], v[20:23]
	s_waitcnt lgkmcnt(3)
	v_mfma_f32_16x16x32_bf16 v[0:3], v[128:131], v[176:179], v[0:3]
	ds_read_b128 v[168:171], v243 offset:32768
	v_mfma_f32_16x16x32_bf16 v[8:11], v[136:139], v[176:179], v[8:11]
	v_mfma_f32_16x16x32_bf16 v[16:19], v[144:147], v[176:179], v[16:19]
	v_mfma_f32_16x16x32_bf16 v[36:39], v[152:155], v[176:179], v[36:39]
	s_waitcnt lgkmcnt(3)
	v_mfma_f32_16x16x32_bf16 v[12:15], v[128:131], v[180:183], v[12:15]
	ds_read_b128 v[172:175], v243 offset:34816
	v_mfma_f32_16x16x32_bf16 v[32:35], v[136:139], v[180:183], v[32:35]
	v_mfma_f32_16x16x32_bf16 v[44:47], v[144:147], v[180:183], v[44:47]
	v_mfma_f32_16x16x32_bf16 v[52:55], v[152:155], v[180:183], v[52:55]
	s_waitcnt lgkmcnt(3)
	v_mfma_f32_16x16x32_bf16 v[40:43], v[128:131], v[160:163], v[40:43]
	ds_read_b128 v[176:179], v243 offset:36864
	v_mfma_f32_16x16x32_bf16 v[48:51], v[136:139], v[160:163], v[48:51]
	v_mfma_f32_16x16x32_bf16 v[104:107], v[144:147], v[160:163], v[104:107]
	v_mfma_f32_16x16x32_bf16 v[100:103], v[152:155], v[160:163], v[100:103]
	s_waitcnt lgkmcnt(3)
	v_mfma_f32_16x16x32_bf16 v[92:95], v[128:131], v[164:167], v[92:95]
	ds_read_b128 v[180:183], v243 offset:38912
	v_mfma_f32_16x16x32_bf16 v[88:91], v[136:139], v[164:167], v[88:91]
	v_mfma_f32_16x16x32_bf16 v[80:83], v[144:147], v[164:167], v[80:83]
	v_mfma_f32_16x16x32_bf16 v[124:127], v[152:155], v[164:167], v[124:127]
	s_waitcnt lgkmcnt(3)
	v_mfma_f32_16x16x32_bf16 v[120:123], v[132:135], v[168:171], v[120:123]
	ds_read_b128 v[160:163], v243 offset:40960
	v_mfma_f32_16x16x32_bf16 v[116:119], v[140:143], v[168:171], v[116:119]
	v_mfma_f32_16x16x32_bf16 v[112:115], v[148:151], v[168:171], v[112:115]
	v_mfma_f32_16x16x32_bf16 v[108:111], v[156:159], v[168:171], v[108:111]
	s_waitcnt lgkmcnt(3)
	v_mfma_f32_16x16x32_bf16 v[96:99], v[132:135], v[172:175], v[96:99]
	ds_read_b128 v[164:167], v243 offset:43008
	v_mfma_f32_16x16x32_bf16 v[84:87], v[140:143], v[172:175], v[84:87]
	v_mfma_f32_16x16x32_bf16 v[76:79], v[148:151], v[172:175], v[76:79]
	v_mfma_f32_16x16x32_bf16 v[72:75], v[156:159], v[172:175], v[72:75]
	s_waitcnt lgkmcnt(3)
	v_mfma_f32_16x16x32_bf16 v[68:71], v[132:135], v[176:179], v[68:71]
	ds_read_b128 v[168:171], v243 offset:45056
	v_mfma_f32_16x16x32_bf16 v[64:67], v[140:143], v[176:179], v[64:67]
	v_mfma_f32_16x16x32_bf16 v[60:63], v[148:151], v[176:179], v[60:63]
	v_mfma_f32_16x16x32_bf16 v[56:59], v[156:159], v[176:179], v[56:59]
	s_waitcnt lgkmcnt(3)
	v_mfma_f32_16x16x32_bf16 v[28:31], v[132:135], v[180:183], v[28:31]
	ds_read_b128 v[172:175], v243 offset:47104
	v_mfma_f32_16x16x32_bf16 v[4:7], v[140:143], v[180:183], v[4:7]
	v_mfma_f32_16x16x32_bf16 v[24:27], v[148:151], v[180:183], v[24:27]
	v_mfma_f32_16x16x32_bf16 v[20:23], v[156:159], v[180:183], v[20:23]
	s_waitcnt lgkmcnt(3)
	v_mfma_f32_16x16x32_bf16 v[0:3], v[132:135], v[160:163], v[0:3]
	v_mfma_f32_16x16x32_bf16 v[8:11], v[140:143], v[160:163], v[8:11]
	v_mfma_f32_16x16x32_bf16 v[16:19], v[148:151], v[160:163], v[16:19]
	v_mfma_f32_16x16x32_bf16 v[36:39], v[156:159], v[160:163], v[36:39]
	s_waitcnt lgkmcnt(2)
	v_mfma_f32_16x16x32_bf16 v[12:15], v[132:135], v[164:167], v[12:15]
	v_mfma_f32_16x16x32_bf16 v[32:35], v[140:143], v[164:167], v[32:35]
	v_mfma_f32_16x16x32_bf16 v[44:47], v[148:151], v[164:167], v[44:47]
	v_mfma_f32_16x16x32_bf16 v[52:55], v[156:159], v[164:167], v[52:55]
	s_waitcnt lgkmcnt(1)
	v_mfma_f32_16x16x32_bf16 v[40:43], v[132:135], v[168:171], v[40:43]
	v_mfma_f32_16x16x32_bf16 v[48:51], v[140:143], v[168:171], v[48:51]
	v_mfma_f32_16x16x32_bf16 v[104:107], v[148:151], v[168:171], v[104:107]
	v_mfma_f32_16x16x32_bf16 v[100:103], v[156:159], v[168:171], v[100:103]
	s_waitcnt lgkmcnt(0)
	v_mfma_f32_16x16x32_bf16 v[92:95], v[132:135], v[172:175], v[92:95]
	v_mfma_f32_16x16x32_bf16 v[88:91], v[140:143], v[172:175], v[88:91]
	v_mfma_f32_16x16x32_bf16 v[80:83], v[148:151], v[172:175], v[80:83]
	v_mfma_f32_16x16x32_bf16 v[124:127], v[156:159], v[172:175], v[124:127]
	s_add_u32 s98, s98, 0x80
	s_addc_u32 s99, s99, 0
	s_add_u32 s100, s100, 0x80
	s_addc_u32 s101, s101, 0
	s_sub_u32 s1, s1, 1
	s_cmp_lg_u32 s1, 0
	s_cbranch_scc1 .Lg8p3_loop
	s_waitcnt vmcnt(0) lgkmcnt(0)
	s_barrier
	s_add_u32 m0, s0, 32768
	ds_read_b128 v[128:131], v240 offset:0
	global_load_lds_dwordx4 v252, s[98:99]
	s_add_u32 m0, s0, 36864
	ds_read_b128 v[136:139], v240 offset:2048
	global_load_lds_dwordx4 v251, s[98:99]
	s_add_u32 m0, s0, 40960
	ds_read_b128 v[144:147], v240 offset:4096
	global_load_lds_dwordx4 v248, s[98:99]
	s_add_u32 m0, s0, 45056
	ds_read_b128 v[152:155], v240 offset:6144
	global_load_lds_dwordx4 v249, s[98:99]
	s_add_u32 m0, s0, 49152
	ds_read_b128 v[132:135], v241 offset:0
	global_load_lds_dwordx4 v250, s[98:99]
	s_add_u32 m0, s0, 53248
	ds_read_b128 v[140:143], v241 offset:2048
	global_load_lds_dwordx4 v247, s[98:99]
	s_add_u32 m0, s0, 57344
	ds_read_b128 v[148:151], v241 offset:4096
	global_load_lds_dwordx4 v244, s[98:99]
	s_add_u32 m0, s0, 61440
	ds_read_b128 v[156:159], v241 offset:6144
	global_load_lds_dwordx4 v245, s[98:99]
	ds_read_b128 v[160:163], v246 offset:0
	ds_read_b128 v[164:167], v246 offset:2048
	ds_read_b128 v[168:171], v246 offset:4096
	ds_read_b128 v[172:175], v246 offset:6144
	s_waitcnt lgkmcnt(4)
	s_barrier
	s_waitcnt lgkmcnt(3)
	s_add_u32 m0, s0, 65536
	v_mfma_f32_16x16x32_bf16 v[120:123], v[128:131], v[160:163], v[120:123]
	ds_read_b128 v[176:179], v246 offset:8192
	global_load_lds_dwordx4 v252, s[100:101]
	v_mfma_f32_16x16x32_bf16 v[116:119], v[136:139], v[160:163], v[116:119]
	s_add_u32 m0, s0, 69632
	v_mfma_f32_16x16x32_bf16 v[112:115], v[144:147], v[160:163], v[112:115]
	global_load_lds_dwordx4 v251, s[100:101]
	v_mfma_f32_16x16x32_bf16 v[108:111], v[152:155], v[160:163], v[108:111]
	s_waitcnt lgkmcnt(3)
	s_add_u32 m0, s0, 73728
	v_mfma_f32_16x16x32_bf16 v[96:99], v[128:131], v[164:167], v[96:99]
	ds_read_b128 v[180:183], v246 offset:10240
	global_load_lds_dwordx4 v248, s[100:101]
	v_mfma_f32_16x16x32_bf16 v[84:87], v[136:139], v[164:167], v[84:87]
	s_add_u32 m0, s0, 77824
	v_mfma_f32_16x16x32_bf16 v[76:79], v[144:147], v[164:167], v[76:79]
	global_load_lds_dwordx4 v249, s[100:101]
	v_mfma_f32_16x16x32_bf16 v[72:75], v[152:155], v[164:167], v[72:75]
	s_waitcnt lgkmcnt(3)
	v_mfma_f32_16x16x32_bf16 v[68:71], v[128:131], v[168:171], v[68:71]
	ds_read_b128 v[160:163], v246 offset:12288
	v_mfma_f32_16x16x32_bf16 v[64:67], v[136:139], v[168:171], v[64:67]
	v_mfma_f32_16x16x32_bf16 v[60:63], v[144:147], v[168:171], v[60:63]
	v_mfma_f32_16x16x32_bf16 v[56:59], v[152:155], v[168:171], v[56:59]
	s_waitcnt lgkmcnt(3)
	v_mfma_f32_16x16x32_bf16 v[28:31], v[128:131], v[172:175], v[28:31]
	ds_read_b128 v[164:167], v246 offset:14336
	v_mfma_f32_16x16x32_bf16 v[4:7], v[136:139], v[172:175], v[4:7]
	v_mfma_f32_16x16x32_bf16 v[24:27], v[144:147], v[172:175], v[24:27]
	v_mfma_f32_16x16x32_bf16 v[20:23], v[152:155], v[172:175], v[20:23]
	s_waitcnt lgkmcnt(3)
	v_mfma_f32_16x16x32_bf16 v[0:3], v[128:131], v[176:179], v[0:3]
	ds_read_b128 v[168:171], v243 offset:0
	v_mfma_f32_16x16x32_bf16 v[8:11], v[136:139], v[176:179], v[8:11]
	v_mfma_f32_16x16x32_bf16 v[16:19], v[144:147], v[176:179], v[16:19]
	v_mfma_f32_16x16x32_bf16 v[36:39], v[152:155], v[176:179], v[36:39]
	s_waitcnt lgkmcnt(3)
	v_mfma_f32_16x16x32_bf16 v[12:15], v[128:131], v[180:183], v[12:15]
	ds_read_b128 v[172:175], v243 offset:2048
	v_mfma_f32_16x16x32_bf16 v[32:35], v[136:139], v[180:183], v[32:35]
	v_mfma_f32_16x16x32_bf16 v[44:47], v[144:147], v[180:183], v[44:47]
	v_mfma_f32_16x16x32_bf16 v[52:55], v[152:155], v[180:183], v[52:55]
	s_waitcnt lgkmcnt(3)
	v_mfma_f32_16x16x32_bf16 v[40:43], v[128:131], v[160:163], v[40:43]
	ds_read_b128 v[176:179], v243 offset:4096
	v_mfma_f32_16x16x32_bf16 v[48:51], v[136:139], v[160:163], v[48:51]
	v_mfma_f32_16x16x32_bf16 v[104:107], v[144:147], v[160:163], v[104:107]
	v_mfma_f32_16x16x32_bf16 v[100:103], v[152:155], v[160:163], v[100:103]
	s_waitcnt lgkmcnt(3)
	v_mfma_f32_16x16x32_bf16 v[92:95], v[128:131], v[164:167], v[92:95]
	ds_read_b128 v[180:183], v243 offset:6144
	v_mfma_f32_16x16x32_bf16 v[88:91], v[136:139], v[164:167], v[88:91]
	v_mfma_f32_16x16x32_bf16 v[80:83], v[144:147], v[164:167], v[80:83]
	v_mfma_f32_16x16x32_bf16 v[124:127], v[152:155], v[164:167], v[124:127]
	s_waitcnt lgkmcnt(3)
	v_mfma_f32_16x16x32_bf16 v[120:123], v[132:135], v[168:171], v[120:123]
	ds_read_b128 v[160:163], v243 offset:8192
	v_mfma_f32_16x16x32_bf16 v[116:119], v[140:143], v[168:171], v[116:119]
	v_mfma_f32_16x16x32_bf16 v[112:115], v[148:151], v[168:171], v[112:115]
	v_mfma_f32_16x16x32_bf16 v[108:111], v[156:159], v[168:171], v[108:111]
	s_waitcnt lgkmcnt(3)
	v_mfma_f32_16x16x32_bf16 v[96:99], v[132:135], v[172:175], v[96:99]
	ds_read_b128 v[164:167], v243 offset:10240
	v_mfma_f32_16x16x32_bf16 v[84:87], v[140:143], v[172:175], v[84:87]
	v_mfma_f32_16x16x32_bf16 v[76:79], v[148:151], v[172:175], v[76:79]
	v_mfma_f32_16x16x32_bf16 v[72:75], v[156:159], v[172:175], v[72:75]
	s_waitcnt lgkmcnt(3)
	v_mfma_f32_16x16x32_bf16 v[68:71], v[132:135], v[176:179], v[68:71]
	ds_read_b128 v[168:171], v243 offset:12288
	v_mfma_f32_16x16x32_bf16 v[64:67], v[140:143], v[176:179], v[64:67]
	v_mfma_f32_16x16x32_bf16 v[60:63], v[148:151], v[176:179], v[60:63]
	v_mfma_f32_16x16x32_bf16 v[56:59], v[156:159], v[176:179], v[56:59]
	s_waitcnt lgkmcnt(3)
	v_mfma_f32_16x16x32_bf16 v[28:31], v[132:135], v[180:183], v[28:31]
	ds_read_b128 v[172:175], v243 offset:14336
	v_mfma_f32_16x16x32_bf16 v[4:7], v[140:143], v[180:183], v[4:7]
	v_mfma_f32_16x16x32_bf16 v[24:27], v[148:151], v[180:183], v[24:27]
	v_mfma_f32_16x16x32_bf16 v[20:23], v[156:159], v[180:183], v[20:23]
	s_waitcnt lgkmcnt(3)
	v_mfma_f32_16x16x32_bf16 v[0:3], v[132:135], v[160:163], v[0:3]
	v_mfma_f32_16x16x32_bf16 v[8:11], v[140:143], v[160:163], v[8:11]
	v_mfma_f32_16x16x32_bf16 v[16:19], v[148:151], v[160:163], v[16:19]
	v_mfma_f32_16x16x32_bf16 v[36:39], v[156:159], v[160:163], v[36:39]
	s_waitcnt lgkmcnt(2)
	v_mfma_f32_16x16x32_bf16 v[12:15], v[132:135], v[164:167], v[12:15]
	v_mfma_f32_16x16x32_bf16 v[32:35], v[140:143], v[164:167], v[32:35]
	v_mfma_f32_16x16x32_bf16 v[44:47], v[148:151], v[164:167], v[44:47]
	v_mfma_f32_16x16x32_bf16 v[52:55], v[156:159], v[164:167], v[52:55]
	s_waitcnt lgkmcnt(1)
	v_mfma_f32_16x16x32_bf16 v[40:43], v[132:135], v[168:171], v[40:43]
	v_mfma_f32_16x16x32_bf16 v[48:51], v[140:143], v[168:171], v[48:51]
	v_mfma_f32_16x16x32_bf16 v[104:107], v[148:151], v[168:171], v[104:107]
	v_mfma_f32_16x16x32_bf16 v[100:103], v[156:159], v[168:171], v[100:103]
	s_waitcnt lgkmcnt(0)
	v_mfma_f32_16x16x32_bf16 v[92:95], v[132:135], v[172:175], v[92:95]
	v_mfma_f32_16x16x32_bf16 v[88:91], v[140:143], v[172:175], v[88:91]
	v_mfma_f32_16x16x32_bf16 v[80:83], v[148:151], v[172:175], v[80:83]
	v_mfma_f32_16x16x32_bf16 v[124:127], v[156:159], v[172:175], v[124:127]
	s_add_u32 s98, s98, 0x80
	s_addc_u32 s99, s99, 0
	s_add_u32 s100, s100, 0x80
	s_addc_u32 s101, s101, 0
	s_waitcnt vmcnt(0) lgkmcnt(0)
	s_barrier
	ds_read_b128 v[128:131], v240 offset:0
	ds_read_b128 v[136:139], v240 offset:2048
	ds_read_b128 v[144:147], v240 offset:4096
	ds_read_b128 v[152:155], v240 offset:6144
	ds_read_b128 v[132:135], v241 offset:0
	ds_read_b128 v[140:143], v241 offset:2048
	ds_read_b128 v[148:151], v241 offset:4096
	ds_read_b128 v[156:159], v241 offset:6144
	ds_read_b128 v[160:163], v246 offset:32768
	ds_read_b128 v[164:167], v246 offset:34816
	ds_read_b128 v[168:171], v246 offset:36864
	ds_read_b128 v[172:175], v246 offset:38912
	s_waitcnt lgkmcnt(4)
	s_waitcnt lgkmcnt(3)
	v_mfma_f32_16x16x32_bf16 v[120:123], v[128:131], v[160:163], v[120:123]
	ds_read_b128 v[176:179], v246 offset:40960
	v_mfma_f32_16x16x32_bf16 v[116:119], v[136:139], v[160:163], v[116:119]
	v_mfma_f32_16x16x32_bf16 v[112:115], v[144:147], v[160:163], v[112:115]
	v_mfma_f32_16x16x32_bf16 v[108:111], v[152:155], v[160:163], v[108:111]
	s_waitcnt lgkmcnt(3)
	v_mfma_f32_16x16x32_bf16 v[96:99], v[128:131], v[164:167], v[96:99]
	ds_read_b128 v[180:183], v246 offset:43008
	v_mfma_f32_16x16x32_bf16 v[84:87], v[136:139], v[164:167], v[84:87]
	v_mfma_f32_16x16x32_bf16 v[76:79], v[144:147], v[164:167], v[76:79]
	v_mfma_f32_16x16x32_bf16 v[72:75], v[152:155], v[164:167], v[72:75]
	s_waitcnt lgkmcnt(3)
	v_mfma_f32_16x16x32_bf16 v[68:71], v[128:131], v[168:171], v[68:71]
	ds_read_b128 v[160:163], v246 offset:45056
	v_mfma_f32_16x16x32_bf16 v[64:67], v[136:139], v[168:171], v[64:67]
	v_mfma_f32_16x16x32_bf16 v[60:63], v[144:147], v[168:171], v[60:63]
	v_mfma_f32_16x16x32_bf16 v[56:59], v[152:155], v[168:171], v[56:59]
	s_waitcnt lgkmcnt(3)
	v_mfma_f32_16x16x32_bf16 v[28:31], v[128:131], v[172:175], v[28:31]
	ds_read_b128 v[164:167], v246 offset:47104
	v_mfma_f32_16x16x32_bf16 v[4:7], v[136:139], v[172:175], v[4:7]
	v_mfma_f32_16x16x32_bf16 v[24:27], v[144:147], v[172:175], v[24:27]
	v_mfma_f32_16x16x32_bf16 v[20:23], v[152:155], v[172:175], v[20:23]
	s_waitcnt lgkmcnt(3)
	v_mfma_f32_16x16x32_bf16 v[0:3], v[128:131], v[176:179], v[0:3]
	ds_read_b128 v[168:171], v243 offset:32768
	v_mfma_f32_16x16x32_bf16 v[8:11], v[136:139], v[176:179], v[8:11]
	v_mfma_f32_16x16x32_bf16 v[16:19], v[144:147], v[176:179], v[16:19]
	v_mfma_f32_16x16x32_bf16 v[36:39], v[152:155], v[176:179], v[36:39]
	s_waitcnt lgkmcnt(3)
	v_mfma_f32_16x16x32_bf16 v[12:15], v[128:131], v[180:183], v[12:15]
	ds_read_b128 v[172:175], v243 offset:34816
	v_mfma_f32_16x16x32_bf16 v[32:35], v[136:139], v[180:183], v[32:35]
	v_mfma_f32_16x16x32_bf16 v[44:47], v[144:147], v[180:183], v[44:47]
	v_mfma_f32_16x16x32_bf16 v[52:55], v[152:155], v[180:183], v[52:55]
	s_waitcnt lgkmcnt(3)
	v_mfma_f32_16x16x32_bf16 v[40:43], v[128:131], v[160:163], v[40:43]
	ds_read_b128 v[176:179], v243 offset:36864
	v_mfma_f32_16x16x32_bf16 v[48:51], v[136:139], v[160:163], v[48:51]
	v_mfma_f32_16x16x32_bf16 v[104:107], v[144:147], v[160:163], v[104:107]
	v_mfma_f32_16x16x32_bf16 v[100:103], v[152:155], v[160:163], v[100:103]
	s_waitcnt lgkmcnt(3)
	v_mfma_f32_16x16x32_bf16 v[92:95], v[128:131], v[164:167], v[92:95]
	ds_read_b128 v[180:183], v243 offset:38912
	v_mfma_f32_16x16x32_bf16 v[88:91], v[136:139], v[164:167], v[88:91]
	v_mfma_f32_16x16x32_bf16 v[80:83], v[144:147], v[164:167], v[80:83]
	v_mfma_f32_16x16x32_bf16 v[124:127], v[152:155], v[164:167], v[124:127]
	s_waitcnt lgkmcnt(3)
	v_mfma_f32_16x16x32_bf16 v[120:123], v[132:135], v[168:171], v[120:123]
	ds_read_b128 v[160:163], v243 offset:40960
	v_mfma_f32_16x16x32_bf16 v[116:119], v[140:143], v[168:171], v[116:119]
	v_mfma_f32_16x16x32_bf16 v[112:115], v[148:151], v[168:171], v[112:115]
	v_mfma_f32_16x16x32_bf16 v[108:111], v[156:159], v[168:171], v[108:111]
	s_waitcnt lgkmcnt(3)
	v_mfma_f32_16x16x32_bf16 v[96:99], v[132:135], v[172:175], v[96:99]
	ds_read_b128 v[164:167], v243 offset:43008
	v_mfma_f32_16x16x32_bf16 v[84:87], v[140:143], v[172:175], v[84:87]
	v_mfma_f32_16x16x32_bf16 v[76:79], v[148:151], v[172:175], v[76:79]
	v_mfma_f32_16x16x32_bf16 v[72:75], v[156:159], v[172:175], v[72:75]
	s_waitcnt lgkmcnt(3)
	v_mfma_f32_16x16x32_bf16 v[68:71], v[132:135], v[176:179], v[68:71]
	ds_read_b128 v[168:171], v243 offset:45056
	v_mfma_f32_16x16x32_bf16 v[64:67], v[140:143], v[176:179], v[64:67]
	v_mfma_f32_16x16x32_bf16 v[60:63], v[148:151], v[176:179], v[60:63]
	v_mfma_f32_16x16x32_bf16 v[56:59], v[156:159], v[176:179], v[56:59]
	s_waitcnt lgkmcnt(3)
	v_mfma_f32_16x16x32_bf16 v[28:31], v[132:135], v[180:183], v[28:31]
	ds_read_b128 v[172:175], v243 offset:47104
	v_mfma_f32_16x16x32_bf16 v[4:7], v[140:143], v[180:183], v[4:7]
	v_mfma_f32_16x16x32_bf16 v[24:27], v[148:151], v[180:183], v[24:27]
	v_mfma_f32_16x16x32_bf16 v[20:23], v[156:159], v[180:183], v[20:23]
	s_waitcnt lgkmcnt(3)
	v_mfma_f32_16x16x32_bf16 v[0:3], v[132:135], v[160:163], v[0:3]
	v_mfma_f32_16x16x32_bf16 v[8:11], v[140:143], v[160:163], v[8:11]
	v_mfma_f32_16x16x32_bf16 v[16:19], v[148:151], v[160:163], v[16:19]
	v_mfma_f32_16x16x32_bf16 v[36:39], v[156:159], v[160:163], v[36:39]
	s_waitcnt lgkmcnt(2)
	v_mfma_f32_16x16x32_bf16 v[12:15], v[132:135], v[164:167], v[12:15]
	v_mfma_f32_16x16x32_bf16 v[32:35], v[140:143], v[164:167], v[32:35]
	v_mfma_f32_16x16x32_bf16 v[44:47], v[148:151], v[164:167], v[44:47]
	v_mfma_f32_16x16x32_bf16 v[52:55], v[156:159], v[164:167], v[52:55]
	s_waitcnt lgkmcnt(1)
	v_mfma_f32_16x16x32_bf16 v[40:43], v[132:135], v[168:171], v[40:43]
	v_mfma_f32_16x16x32_bf16 v[48:51], v[140:143], v[168:171], v[48:51]
	v_mfma_f32_16x16x32_bf16 v[104:107], v[148:151], v[168:171], v[104:107]
	v_mfma_f32_16x16x32_bf16 v[100:103], v[156:159], v[168:171], v[100:103]
	s_waitcnt lgkmcnt(0)
	v_mfma_f32_16x16x32_bf16 v[92:95], v[132:135], v[172:175], v[92:95]
	v_mfma_f32_16x16x32_bf16 v[88:91], v[140:143], v[172:175], v[88:91]
	v_mfma_f32_16x16x32_bf16 v[80:83], v[148:151], v[172:175], v[80:83]
	v_mfma_f32_16x16x32_bf16 v[124:127], v[156:159], v[172:175], v[124:127]
	s_nop 7
	s_nop 7
	s_barrier
	ds_write_b64 v194, v[192:193]
	s_movk_i32 s0, 0xc00
	v_mov_b32_e32 v172, v84
	v_mov_b32_e32 v173, v85
	v_mov_b32_e32 v174, v86
	v_mov_b32_e32 v175, v87
	v_mov_b32_e32 v176, v76
	v_mov_b32_e32 v177, v77
	v_mov_b32_e32 v178, v78
	v_mov_b32_e32 v179, v79
	v_mov_b32_e32 v180, v72
	v_mov_b32_e32 v181, v73
	v_mov_b32_e32 v182, v74
	v_mov_b32_e32 v183, v75
	v_mov_b32_e32 v168, v56
	v_mov_b32_e32 v169, v57
	v_mov_b32_e32 v170, v58
	v_mov_b32_e32 v171, v59
	v_mov_b32_e32 v76, v64
	v_mov_b32_e32 v77, v65
	v_mov_b32_e32 v78, v66
	v_mov_b32_e32 v79, v67
	v_mov_b32_e32 v64, v4
	v_mov_b32_e32 v65, v5
	v_mov_b32_e32 v66, v6
	v_mov_b32_e32 v67, v7
	v_mov_b32_e32 v72, v68
	v_mov_b32_e32 v73, v69
	v_mov_b32_e32 v74, v70
	v_mov_b32_e32 v75, v71
	v_mov_b32_e32 v84, v60
	v_mov_b32_e32 v85, v61
	v_mov_b32_e32 v86, v62
	v_mov_b32_e32 v87, v63
	v_mov_b32_e32 v60, v28
	v_mov_b32_e32 v61, v29
	v_mov_b32_e32 v62, v30
	v_mov_b32_e32 v63, v31
	v_mov_b32_e32 v68, v24
	v_mov_b32_e32 v69, v25
	v_mov_b32_e32 v70, v26
	v_mov_b32_e32 v71, v27
	v_mov_b32_e32 v164, v20
	v_mov_b32_e32 v165, v21
	v_mov_b32_e32 v166, v22
	v_mov_b32_e32 v167, v23
	v_mov_b32_e32 v56, v0
	v_mov_b32_e32 v57, v1
	v_mov_b32_e32 v58, v2
	v_mov_b32_e32 v59, v3
	v_mov_b32_e32 v20, v12
	v_mov_b32_e32 v21, v13
	v_mov_b32_e32 v22, v14
	v_mov_b32_e32 v23, v15
	v_mov_b32_e32 v24, v32
	v_mov_b32_e32 v25, v33
	v_mov_b32_e32 v26, v34
	v_mov_b32_e32 v27, v35
	v_mov_b32_e32 v28, v44
	v_mov_b32_e32 v29, v45
	v_mov_b32_e32 v30, v46
	v_mov_b32_e32 v31, v47
	v_mov_b32_e32 v32, v52
	v_mov_b32_e32 v33, v53
	v_mov_b32_e32 v34, v54
	v_mov_b32_e32 v35, v55
	v_mov_b32_e32 v156, v8
	v_mov_b32_e32 v157, v9
	v_mov_b32_e32 v158, v10
	v_mov_b32_e32 v159, v11
	v_mov_b32_e32 v8, v40
	v_mov_b32_e32 v9, v41
	v_mov_b32_e32 v10, v42
	v_mov_b32_e32 v11, v43
	v_mov_b32_e32 v160, v16
	v_mov_b32_e32 v161, v17
	v_mov_b32_e32 v162, v18
	v_mov_b32_e32 v163, v19
	v_mov_b32_e32 v12, v48
	v_mov_b32_e32 v13, v49
	v_mov_b32_e32 v14, v50
	v_mov_b32_e32 v15, v51
	v_mov_b32_e32 v16, v104
	v_mov_b32_e32 v17, v105
	v_mov_b32_e32 v18, v106
	v_mov_b32_e32 v19, v107
	v_mov_b32_e32 v136, v100
	v_mov_b32_e32 v137, v101
	v_mov_b32_e32 v138, v102
	v_mov_b32_e32 v139, v103
	v_mov_b32_e32 v0, v92
	v_mov_b32_e32 v1, v93
	v_mov_b32_e32 v2, v94
	v_mov_b32_e32 v3, v95
	v_mov_b32_e32 v4, v88
	v_mov_b32_e32 v5, v89
	v_mov_b32_e32 v6, v90
	v_mov_b32_e32 v7, v91
	v_mov_b32_e32 v128, v80
	v_mov_b32_e32 v129, v81
	v_mov_b32_e32 v130, v82
	v_mov_b32_e32 v131, v83
	v_mov_b32_e32 v132, v120
	v_mov_b32_e32 v133, v121
	v_mov_b32_e32 v134, v122
	v_mov_b32_e32 v135, v123
	v_mov_b32_e32 v120, v116
	v_mov_b32_e32 v121, v117
	v_mov_b32_e32 v122, v118
	v_mov_b32_e32 v123, v119
	v_mov_b32_e32 v116, v112
	v_mov_b32_e32 v117, v113
	v_mov_b32_e32 v118, v114
	v_mov_b32_e32 v119, v115
	v_mov_b32_e32 v112, v108
	v_mov_b32_e32 v113, v109
	v_mov_b32_e32 v114, v110
	v_mov_b32_e32 v115, v111
	v_mov_b32_e32 v108, v96
	v_mov_b32_e32 v109, v97
	v_mov_b32_e32 v110, v98
	v_mov_b32_e32 v111, v99
	v_mov_b32_e32 v104, v172
	v_mov_b32_e32 v105, v173
	v_mov_b32_e32 v106, v174
	v_mov_b32_e32 v107, v175
	v_mov_b32_e32 v100, v176
	v_mov_b32_e32 v101, v177
	v_mov_b32_e32 v102, v178
	v_mov_b32_e32 v103, v179
	v_mov_b32_e32 v96, v180
	v_mov_b32_e32 v97, v181
	v_mov_b32_e32 v98, v182
	v_mov_b32_e32 v99, v183
	v_mov_b32_e32 v92, v72
	v_mov_b32_e32 v93, v73
	v_mov_b32_e32 v94, v74
	v_mov_b32_e32 v95, v75
	v_mov_b32_e32 v88, v76
	v_mov_b32_e32 v89, v77
	v_mov_b32_e32 v90, v78
	v_mov_b32_e32 v91, v79
	v_mov_b32_e32 v80, v168
	v_mov_b32_e32 v81, v169
	v_mov_b32_e32 v82, v170
	v_mov_b32_e32 v83, v171
	v_mov_b32_e32 v76, v60
	v_mov_b32_e32 v77, v61
	v_mov_b32_e32 v78, v62
	v_mov_b32_e32 v79, v63
	v_mov_b32_e32 v72, v64
	v_mov_b32_e32 v73, v65
	v_mov_b32_e32 v74, v66
	v_mov_b32_e32 v75, v67
	v_mov_b32_e32 v64, v164
	v_mov_b32_e32 v65, v165
	v_mov_b32_e32 v66, v166
	v_mov_b32_e32 v67, v167
	v_mov_b32_e32 v60, v56
	v_mov_b32_e32 v61, v57
	v_mov_b32_e32 v62, v58
	v_mov_b32_e32 v63, v59
	v_mov_b32_e32 v56, v156
	v_mov_b32_e32 v57, v157
	v_mov_b32_e32 v58, v158
	v_mov_b32_e32 v59, v159
	v_mov_b32_e32 v52, v160
	v_mov_b32_e32 v53, v161
	v_mov_b32_e32 v54, v162
	v_mov_b32_e32 v55, v163
	v_mov_b32_e32 v48, v36
	v_mov_b32_e32 v49, v37
	v_mov_b32_e32 v50, v38
	v_mov_b32_e32 v51, v39
	v_mov_b32_e32 v44, v20
	v_mov_b32_e32 v45, v21
	v_mov_b32_e32 v46, v22
	v_mov_b32_e32 v47, v23
	v_mov_b32_e32 v40, v24
	v_mov_b32_e32 v41, v25
	v_mov_b32_e32 v42, v26
	v_mov_b32_e32 v43, v27
	v_mov_b32_e32 v36, v28
	v_mov_b32_e32 v37, v29
	v_mov_b32_e32 v38, v30
	v_mov_b32_e32 v39, v31
	v_mov_b32_e32 v28, v8
	v_mov_b32_e32 v29, v9
	v_mov_b32_e32 v30, v10
	v_mov_b32_e32 v31, v11
	v_mov_b32_e32 v8, v136
	v_mov_b32_e32 v9, v137
	v_mov_b32_e32 v10, v138
	v_mov_b32_e32 v11, v139
	v_mov_b32_e32 v24, v12
	v_mov_b32_e32 v25, v13
	v_mov_b32_e32 v26, v14
	v_mov_b32_e32 v27, v15
	v_mov_b32_e32 v20, v16
	v_mov_b32_e32 v21, v17
	v_mov_b32_e32 v22, v18
	v_mov_b32_e32 v23, v19
	v_mov_b32_e32 v16, v0
	v_mov_b32_e32 v17, v1
	v_mov_b32_e32 v18, v2
	v_mov_b32_e32 v19, v3
	v_mov_b32_e32 v12, v4
	v_mov_b32_e32 v13, v5
	v_mov_b32_e32 v14, v6
	v_mov_b32_e32 v15, v7
	v_mov_b32_e32 v4, v128
	v_mov_b32_e32 v5, v129
	v_mov_b32_e32 v6, v130
	v_mov_b32_e32 v7, v131
	v_mov_b32_e32 v0, v124
	v_mov_b32_e32 v1, v125
	v_mov_b32_e32 v2, v126
	v_mov_b32_e32 v3, v127
	s_nop 2
	v_or_b32_e32 v124, s10, v202
	v_cmp_ne_u32_e64 s[0:1], s0, v124
	s_and_saveexec_b64 s[6:7], s[0:1]
	s_xor_b64 s[6:7], exec, s[6:7]
	s_or_saveexec_b64 s[6:7], s[6:7]
	v_add_u32_e32 v126, s4, v201
	v_or_b32_e32 v124, v126, v197
	v_lshlrev_b32_e32 v124, 6, v124
	v_ashrrev_i32_e32 v125, 31, v124
	v_or_b32_e32 v184, s10, v203
	v_lshl_add_u64 v[124:125], v[124:125], 2, s[30:31]
	s_xor_b64 exec, exec, s[6:7]
	s_cbranch_execz .LBB0_418
	v_lshl_add_u64 v[128:129], v[184:185], 2, v[124:125]
	v_add_co_u32_e32 v128, vcc, 0xffffd000, v128
	s_nop 1
	v_addc_co_u32_e32 v129, vcc, -1, v129, vcc
	global_store_dwordx4 v[128:129], v[132:135], off

.LBB0_601:
	s_mov_b64 s[16:17], src_shared_base
	s_cmp_lg_u32 16, -1
	s_cselect_b32 s16, 16, 0
	s_cselect_b32 s17, s17, 0
	s_add_u32 s16, s16, 0x11b80
	s_addc_u32 s17, s17, 0
	s_cmp_lg_u64 s[16:17], 0
	s_cselect_b32 s16, s16, -1
	s_add_i32 s17, 16, 0x11980
	v_mov_b32_e32 v60, s17
	v_mov_b32_e32 v61, s16
	v_cndmask_b32_e64 v60, v60, v61, s[20:21]
	ds_read2_b32 v[60:61], v60 offset1:1
	s_add_i32 s17, s16, 8
	s_add_i32 s18, 16, 0x11988
	v_mov_b32_e32 v62, s18
	v_mov_b32_e32 v63, s17
	v_cndmask_b32_e64 v62, v62, v63, s[20:21]
	s_add_i32 s17, s16, 16
	s_add_i32 s18, 16, 0x11990
	ds_read2_b32 v[66:67], v62 offset1:1
	v_mov_b32_e32 v62, s18
	v_mov_b32_e32 v63, s17
	v_cndmask_b32_e64 v62, v62, v63, s[20:21]
	s_add_i32 s17, s16, 24
	s_add_i32 s18, 16, 0x11998
	s_waitcnt lgkmcnt(1)
	v_pk_mul_f32 v[60:61], v[122:123], v[60:61]
	ds_read2_b32 v[122:123], v62 offset1:1
	v_mov_b32_e32 v62, s18
	v_mov_b32_e32 v63, s17
	v_cndmask_b32_e64 v62, v62, v63, s[20:21]
	s_add_i32 s17, s16, 32
	s_add_i32 s18, 16, 0x119a0
	ds_read2_b32 v[200:201], v62 offset1:1
	v_mov_b32_e32 v62, s18
	v_mov_b32_e32 v63, s17
	v_cndmask_b32_e64 v62, v62, v63, s[20:21]
	s_add_i32 s17, s16, 40
	s_add_i32 s18, 16, 0x119a8
	ds_read2_b32 v[202:203], v62 offset1:1
	v_mov_b32_e32 v62, s18
	v_mov_b32_e32 v63, s17
	v_cndmask_b32_e64 v62, v62, v63, s[20:21]
	s_add_i32 s17, s16, 48
	s_add_i32 s18, 16, 0x119b0
	ds_read2_b32 v[204:205], v62 offset1:1
	v_mov_b32_e32 v62, s18
	v_mov_b32_e32 v63, s17
	v_cndmask_b32_e64 v62, v62, v63, s[20:21]
	s_add_i32 s17, s16, 56
	s_add_i32 s18, 16, 0x119b8
	ds_read2_b32 v[206:207], v62 offset1:1
	v_mov_b32_e32 v62, s18
	v_mov_b32_e32 v63, s17
	v_cndmask_b32_e64 v62, v62, v63, s[20:21]
	s_add_i32 s17, s16, 64
	s_add_i32 s18, 16, 0x119c0
	ds_read2_b32 v[208:209], v62 offset1:1
	v_mov_b32_e32 v62, s18
	v_mov_b32_e32 v63, s17
	v_cndmask_b32_e64 v62, v62, v63, s[20:21]
	s_add_i32 s17, s16, 0x48
	s_add_i32 s18, 16, 0x119c8
	ds_read2_b32 v[210:211], v62 offset1:1
	v_mov_b32_e32 v62, s18
	v_mov_b32_e32 v63, s17
	v_cndmask_b32_e64 v62, v62, v63, s[20:21]
	s_add_i32 s17, s16, 0x50
	s_add_i32 s18, 16, 0x119d0
	ds_read2_b32 v[212:213], v62 offset1:1
	v_mov_b32_e32 v62, s18
	v_mov_b32_e32 v63, s17
	v_cndmask_b32_e64 v62, v62, v63, s[20:21]
	s_add_i32 s17, s16, 0x58
	s_add_i32 s18, 16, 0x119d8
	ds_read2_b32 v[214:215], v62 offset1:1
	v_mov_b32_e32 v62, s18
	v_mov_b32_e32 v63, s17
	v_cndmask_b32_e64 v62, v62, v63, s[20:21]
	s_add_i32 s17, s16, 0x60
	s_add_i32 s18, 16, 0x119e0
	ds_read2_b32 v[216:217], v62 offset1:1
	v_mov_b32_e32 v62, s18
	v_mov_b32_e32 v63, s17
	v_cndmask_b32_e64 v62, v62, v63, s[20:21]
	s_add_i32 s17, s16, 0x68
	s_add_i32 s18, 16, 0x119e8
	ds_read2_b32 v[218:219], v62 offset1:1
	v_mov_b32_e32 v62, s18
	v_mov_b32_e32 v63, s17
	s_add_i32 s17, s16, 0x70
	s_add_i32 s18, 16, 0x119f0
	v_mov_b32_e32 v64, s18
	v_mov_b32_e32 v65, s17
	v_cndmask_b32_e64 v64, v64, v65, s[20:21]
	s_addk_i32 s16, 0x78
	s_add_i32 s17, 16, 0x119f8
	ds_read2_b32 v[152:153], v64 offset1:1
	v_mov_b32_e32 v64, s17
	v_mov_b32_e32 v65, s16
	v_cndmask_b32_e64 v64, v64, v65, s[20:21]
	v_cndmask_b32_e64 v62, v62, v63, s[20:21]
	ds_read2_b32 v[158:159], v64 offset1:1
	v_mov_b32_e32 v64, v1
	ds_read2_b32 v[62:63], v62 offset1:1
	ds_read_b128 v[220:223], v1 offset:45168
	ds_read_b128 v[224:227], v1 offset:45072
	ds_read_b128 v[228:231], v1 offset:45088
	ds_read_b128 v[232:235], v1 offset:45104
	ds_read_b128 v[236:239], v1 offset:45120
	ds_read_b128 v[240:243], v1 offset:45136
	ds_read_b128 v[244:247], v1 offset:45152
	ds_read_b128 v[248:251], v1 offset:45184
	ds_read_b128 v[184:187], v1 offset:45216
	ds_read_b128 v[188:191], v1 offset:45232
	s_waitcnt lgkmcnt(10)
	s_waitcnt lgkmcnt(9)
	v_pk_mul_f32 v[64:65], v[60:61], v[222:223] op_sel_hi:[0,1]
	ds_read_b128 v[192:195], v1 offset:45248
	v_pk_fma_f32 v[64:65], v[150:151], v[62:63], v[64:65] neg_lo:[0,0,1] neg_hi:[0,0,1]
	s_waitcnt lgkmcnt(9)
	v_pk_mul_f32 v[150:151], v[60:61], v[226:227] op_sel_hi:[0,1]
	v_pk_fma_f32 v[62:63], v[60:61], v[224:225], v[60:61] op_sel_hi:[0,1,1] neg_lo:[1,0,0] neg_hi:[1,0,0]
	ds_read_b128 v[224:227], v1 offset:45264
	v_pk_fma_f32 v[154:155], v[120:121], v[66:67], v[150:151] neg_lo:[0,0,1] neg_hi:[0,0,1]
	s_waitcnt lgkmcnt(9)
	v_pk_mul_f32 v[66:67], v[60:61], v[228:229] op_sel_hi:[0,1]
	v_pk_fma_f32 v[150:151], v[124:125], v[122:123], v[66:67] neg_lo:[0,0,1] neg_hi:[0,0,1]
	v_pk_mul_f32 v[66:67], v[60:61], v[230:231] op_sel_hi:[0,1]
	ds_read_b128 v[228:231], v1 offset:45280
	v_pk_fma_f32 v[156:157], v[126:127], v[200:201], v[66:67] neg_lo:[0,0,1] neg_hi:[0,0,1]
	s_waitcnt lgkmcnt(9)
	v_pk_mul_f32 v[66:67], v[60:61], v[232:233] op_sel_hi:[0,1]
	v_pk_fma_f32 v[128:129], v[128:129], v[202:203], v[66:67] neg_lo:[0,0,1] neg_hi:[0,0,1]
	v_pk_mul_f32 v[66:67], v[60:61], v[234:235] op_sel_hi:[0,1]
	ds_read_b128 v[232:235], v1 offset:45296
	v_pk_fma_f32 v[130:131], v[130:131], v[204:205], v[66:67] neg_lo:[0,0,1] neg_hi:[0,0,1]
	s_waitcnt lgkmcnt(9)
	v_pk_mul_f32 v[66:67], v[60:61], v[236:237] op_sel_hi:[0,1]
	v_pk_fma_f32 v[132:133], v[132:133], v[206:207], v[66:67] neg_lo:[0,0,1] neg_hi:[0,0,1]
	v_pk_mul_f32 v[66:67], v[60:61], v[238:239] op_sel_hi:[0,1]
	ds_read_b128 v[236:239], v1 offset:45312
	v_pk_fma_f32 v[134:135], v[134:135], v[208:209], v[66:67] neg_lo:[0,0,1] neg_hi:[0,0,1]
	s_waitcnt lgkmcnt(9)
	v_pk_mul_f32 v[66:67], v[60:61], v[240:241] op_sel_hi:[0,1]
	v_pk_fma_f32 v[124:125], v[136:137], v[210:211], v[66:67] neg_lo:[0,0,1] neg_hi:[0,0,1]
	v_pk_mul_f32 v[66:67], v[60:61], v[242:243] op_sel_hi:[0,1]
	ds_read_b128 v[240:243], v1 offset:45328
	v_pk_fma_f32 v[126:127], v[138:139], v[212:213], v[66:67] neg_lo:[0,0,1] neg_hi:[0,0,1]
	s_waitcnt lgkmcnt(9)
	v_pk_mul_f32 v[66:67], v[60:61], v[244:245] op_sel_hi:[0,1]
	v_pk_fma_f32 v[120:121], v[140:141], v[214:215], v[66:67] neg_lo:[0,0,1] neg_hi:[0,0,1]
	v_pk_mul_f32 v[66:67], v[60:61], v[246:247] op_sel_hi:[0,1]
	ds_read_b128 v[244:247], v1 offset:45360
	v_pk_fma_f32 v[122:123], v[142:143], v[216:217], v[66:67] neg_lo:[0,0,1] neg_hi:[0,0,1]
	v_pk_mul_f32 v[66:67], v[60:61], v[220:221] op_sel_hi:[0,1]
	ds_read_b128 v[220:223], v1 offset:45376
	s_waitcnt lgkmcnt(10)
	v_pk_mul_f32 v[136:137], v[60:61], v[248:249] op_sel_hi:[0,1]
	v_pk_fma_f32 v[66:67], v[148:149], v[218:219], v[66:67] neg_lo:[0,0,1] neg_hi:[0,0,1]
	v_pk_fma_f32 v[148:149], v[144:145], v[152:153], v[136:137] neg_lo:[0,0,1] neg_hi:[0,0,1]
	v_pk_mul_f32 v[60:61], v[60:61], v[250:251] op_sel_hi:[0,1]
	ds_read_b128 v[248:251], v1 offset:45392
	v_pk_fma_f32 v[60:61], v[146:147], v[158:159], v[60:61] neg_lo:[0,0,1] neg_hi:[0,0,1]
	s_waitcnt lgkmcnt(10)
	v_pk_fma_f32 v[138:139], v[62:63], v[186:187], v[154:155] op_sel:[1,0,0] neg_lo:[1,0,0] neg_hi:[1,0,0]
	s_waitcnt lgkmcnt(9)
	v_pk_fma_f32 v[140:141], v[62:63], v[188:189], v[150:151] op_sel:[1,0,0] neg_lo:[1,0,0] neg_hi:[1,0,0]
	s_waitcnt lgkmcnt(8)
	v_pk_fma_f32 v[144:145], v[62:63], v[192:193], v[128:129] op_sel:[1,0,0] neg_lo:[1,0,0] neg_hi:[1,0,0]
	v_pk_fma_f32 v[146:147], v[62:63], v[194:195], v[130:131] op_sel:[1,0,0] neg_lo:[1,0,0] neg_hi:[1,0,0]
	ds_read_b128 v[128:131], v1 offset:45408
	ds_read_b128 v[192:195], v1 offset:45424
	v_pk_fma_f32 v[142:143], v[62:63], v[190:191], v[156:157] op_sel:[1,0,0] neg_lo:[1,0,0] neg_hi:[1,0,0]
	ds_read_b128 v[188:191], v1 offset:45440
	s_waitcnt lgkmcnt(10)
	v_pk_fma_f32 v[132:133], v[62:63], v[224:225], v[132:133] op_sel:[1,0,0] neg_lo:[1,0,0] neg_hi:[1,0,0]
	v_pk_fma_f32 v[134:135], v[62:63], v[226:227], v[134:135] op_sel:[1,0,0] neg_lo:[1,0,0] neg_hi:[1,0,0]
	ds_read_b128 v[224:227], v1 offset:45456
	v_pk_fma_f32 v[136:137], v[62:63], v[184:185], v[62:63] op_sel:[1,0,0] neg_lo:[1,0,0] neg_hi:[1,0,0]
	s_waitcnt lgkmcnt(10)
	v_pk_fma_f32 v[150:151], v[62:63], v[228:229], v[124:125] op_sel:[1,0,0] neg_lo:[1,0,0] neg_hi:[1,0,0]
	v_pk_fma_f32 v[152:153], v[62:63], v[230:231], v[126:127] op_sel:[1,0,0] neg_lo:[1,0,0] neg_hi:[1,0,0]
	ds_read_b128 v[228:231], v1 offset:45472
	ds_read_b128 v[124:127], v1 offset:45520
	s_waitcnt lgkmcnt(11)
	v_pk_fma_f32 v[154:155], v[62:63], v[232:233], v[120:121] op_sel:[1,0,0] neg_lo:[1,0,0] neg_hi:[1,0,0]
	v_pk_fma_f32 v[156:157], v[62:63], v[234:235], v[122:123] op_sel:[1,0,0] neg_lo:[1,0,0] neg_hi:[1,0,0]
	ds_read_b128 v[232:235], v1 offset:45536
	s_waitcnt lgkmcnt(11)
	v_pk_fma_f32 v[158:159], v[62:63], v[236:237], v[66:67] op_sel:[1,0,0] neg_lo:[1,0,0] neg_hi:[1,0,0]
	v_pk_fma_f32 v[182:183], v[62:63], v[238:239], v[64:65] op_sel:[1,0,0] neg_lo:[1,0,0] neg_hi:[1,0,0]
	ds_read_b128 v[236:239], v1 offset:45552
	ds_read_b128 v[64:67], v1 offset:45568
	s_waitcnt lgkmcnt(12)
	v_pk_fma_f32 v[184:185], v[62:63], v[242:243], v[60:61] op_sel:[1,0,0] neg_lo:[1,0,0] neg_hi:[1,0,0]
	v_pk_fma_f32 v[148:149], v[62:63], v[240:241], v[148:149] op_sel:[1,0,0] neg_lo:[1,0,0] neg_hi:[1,0,0]
	ds_read_b128 v[240:243], v1 offset:45584
	ds_read_b128 v[60:63], v1 offset:45600
	s_waitcnt lgkmcnt(13)
	v_pk_fma_f32 v[122:123], v[138:139], v[244:245], v[136:137] op_sel_hi:[0,1,1] neg_lo:[1,0,0] neg_hi:[1,0,0]
	v_pk_fma_f32 v[120:121], v[138:139], v[246:247], v[138:139] op_sel_hi:[0,1,1] neg_lo:[1,0,0] neg_hi:[1,0,0]
	ds_read_b128 v[244:247], v1 offset:45616
	s_waitcnt lgkmcnt(13)
	v_pk_fma_f32 v[136:137], v[138:139], v[220:221], v[140:141] op_sel_hi:[0,1,1] neg_lo:[1,0,0] neg_hi:[1,0,0]
	v_pk_fma_f32 v[140:141], v[138:139], v[222:223], v[142:143] op_sel_hi:[0,1,1] neg_lo:[1,0,0] neg_hi:[1,0,0]
	ds_read_b128 v[220:223], v1 offset:45664
	s_waitcnt lgkmcnt(13)
	v_pk_fma_f32 v[142:143], v[138:139], v[248:249], v[144:145] op_sel_hi:[0,1,1] neg_lo:[1,0,0] neg_hi:[1,0,0]
	v_pk_fma_f32 v[144:145], v[138:139], v[250:251], v[146:147] op_sel_hi:[0,1,1] neg_lo:[1,0,0] neg_hi:[1,0,0]
	ds_read_b128 v[248:251], v1 offset:45680
	s_waitcnt lgkmcnt(12)
	v_pk_fma_f32 v[146:147], v[138:139], v[192:193], v[150:151] op_sel_hi:[0,1,1] neg_lo:[1,0,0] neg_hi:[1,0,0]
	v_pk_fma_f32 v[150:151], v[138:139], v[194:195], v[152:153] op_sel_hi:[0,1,1] neg_lo:[1,0,0] neg_hi:[1,0,0]
	ds_read_b128 v[192:195], v1 offset:45696
	v_pk_fma_f32 v[132:133], v[138:139], v[128:129], v[132:133] op_sel_hi:[0,1,1] neg_lo:[1,0,0] neg_hi:[1,0,0]
	v_pk_fma_f32 v[134:135], v[138:139], v[130:131], v[134:135] op_sel_hi:[0,1,1] neg_lo:[1,0,0] neg_hi:[1,0,0]
	ds_read_b128 v[128:131], v1 offset:45712
	s_waitcnt lgkmcnt(13)
	v_pk_fma_f32 v[152:153], v[138:139], v[188:189], v[154:155] op_sel_hi:[0,1,1] neg_lo:[1,0,0] neg_hi:[1,0,0]
	v_pk_fma_f32 v[154:155], v[138:139], v[190:191], v[156:157] op_sel_hi:[0,1,1] neg_lo:[1,0,0] neg_hi:[1,0,0]
	ds_read_b128 v[188:191], v1 offset:45728
	s_waitcnt lgkmcnt(13)
	v_pk_fma_f32 v[156:157], v[138:139], v[224:225], v[158:159] op_sel_hi:[0,1,1] neg_lo:[1,0,0] neg_hi:[1,0,0]
	v_pk_fma_f32 v[158:159], v[138:139], v[226:227], v[182:183] op_sel_hi:[0,1,1] neg_lo:[1,0,0] neg_hi:[1,0,0]
	ds_read_b128 v[224:227], v1 offset:45744
	s_waitcnt lgkmcnt(13)
	v_pk_fma_f32 v[148:149], v[138:139], v[228:229], v[148:149] op_sel_hi:[0,1,1] neg_lo:[1,0,0] neg_hi:[1,0,0]
	v_pk_fma_f32 v[138:139], v[138:139], v[230:231], v[184:185] op_sel_hi:[0,1,1] neg_lo:[1,0,0] neg_hi:[1,0,0]
	ds_read_b128 v[228:231], v1 offset:45760
	s_waitcnt lgkmcnt(13)
	v_pk_fma_f32 v[136:137], v[120:121], v[124:125], v[136:137] op_sel:[1,0,0] neg_lo:[1,0,0] neg_hi:[1,0,0]
	ds_read_b128 v[184:187], v1 offset:45808
	v_pk_fma_f32 v[140:141], v[120:121], v[126:127], v[140:141] op_sel:[1,0,0] neg_lo:[1,0,0] neg_hi:[1,0,0]
	s_waitcnt lgkmcnt(13)
	v_pk_fma_f32 v[142:143], v[120:121], v[232:233], v[142:143] op_sel:[1,0,0] neg_lo:[1,0,0] neg_hi:[1,0,0]
	ds_read_b128 v[124:127], v1 offset:45824
	v_pk_fma_f32 v[144:145], v[120:121], v[234:235], v[144:145] op_sel:[1,0,0] neg_lo:[1,0,0] neg_hi:[1,0,0]
	s_waitcnt lgkmcnt(13)
	v_pk_fma_f32 v[132:133], v[120:121], v[236:237], v[132:133] op_sel:[1,0,0] neg_lo:[1,0,0] neg_hi:[1,0,0]
	ds_read_b128 v[232:235], v1 offset:45840
	v_pk_fma_f32 v[134:135], v[120:121], v[238:239], v[134:135] op_sel:[1,0,0] neg_lo:[1,0,0] neg_hi:[1,0,0]
	s_waitcnt lgkmcnt(12)
	v_pk_fma_f32 v[152:153], v[120:121], v[240:241], v[152:153] op_sel:[1,0,0] neg_lo:[1,0,0] neg_hi:[1,0,0]
	ds_read_b128 v[236:239], v1 offset:45856
	v_pk_fma_f32 v[154:155], v[120:121], v[242:243], v[154:155] op_sel:[1,0,0] neg_lo:[1,0,0] neg_hi:[1,0,0]
	v_pk_fma_f32 v[146:147], v[120:121], v[64:65], v[146:147] op_sel:[1,0,0] neg_lo:[1,0,0] neg_hi:[1,0,0]
	ds_read_b128 v[240:243], v1 offset:45872
	v_pk_fma_f32 v[150:151], v[120:121], v[66:67], v[150:151] op_sel:[1,0,0] neg_lo:[1,0,0] neg_hi:[1,0,0]
	s_waitcnt lgkmcnt(13)
	v_pk_fma_f32 v[156:157], v[120:121], v[60:61], v[156:157] op_sel:[1,0,0] neg_lo:[1,0,0] neg_hi:[1,0,0]
	ds_read_b128 v[64:67], v1 offset:45888
	v_pk_fma_f32 v[158:159], v[120:121], v[62:63], v[158:159] op_sel:[1,0,0] neg_lo:[1,0,0] neg_hi:[1,0,0]
	s_waitcnt lgkmcnt(13)
	v_pk_fma_f32 v[148:149], v[120:121], v[244:245], v[148:149] op_sel:[1,0,0] neg_lo:[1,0,0] neg_hi:[1,0,0]
	ds_read_b128 v[60:63], v1 offset:45904
	v_pk_fma_f32 v[138:139], v[120:121], v[246:247], v[138:139] op_sel:[1,0,0] neg_lo:[1,0,0] neg_hi:[1,0,0]
	s_waitcnt lgkmcnt(13)
	v_pk_fma_f32 v[182:183], v[136:137], v[220:221], v[136:137] op_sel_hi:[0,1,1] neg_lo:[1,0,0] neg_hi:[1,0,0]
	ds_read_b128 v[244:247], v1 offset:45952
	v_pk_fma_f32 v[140:141], v[136:137], v[222:223], v[140:141] op_sel_hi:[0,1,1] neg_lo:[1,0,0] neg_hi:[1,0,0]
	s_waitcnt lgkmcnt(13)
	v_pk_fma_f32 v[142:143], v[136:137], v[248:249], v[142:143] op_sel_hi:[0,1,1] neg_lo:[1,0,0] neg_hi:[1,0,0]
	ds_read_b128 v[220:223], v1 offset:45968
	v_pk_fma_f32 v[144:145], v[136:137], v[250:251], v[144:145] op_sel_hi:[0,1,1] neg_lo:[1,0,0] neg_hi:[1,0,0]
	s_waitcnt lgkmcnt(13)
	v_pk_fma_f32 v[132:133], v[136:137], v[192:193], v[132:133] op_sel_hi:[0,1,1] neg_lo:[1,0,0] neg_hi:[1,0,0]
	ds_read_b128 v[248:251], v1 offset:45984
	v_pk_fma_f32 v[134:135], v[136:137], v[194:195], v[134:135] op_sel_hi:[0,1,1] neg_lo:[1,0,0] neg_hi:[1,0,0]
	s_waitcnt lgkmcnt(12)
	v_pk_fma_f32 v[152:153], v[136:137], v[188:189], v[152:153] op_sel_hi:[0,1,1] neg_lo:[1,0,0] neg_hi:[1,0,0]
	ds_read_b128 v[192:195], v1 offset:46000
	v_pk_fma_f32 v[154:155], v[136:137], v[190:191], v[154:155] op_sel_hi:[0,1,1] neg_lo:[1,0,0] neg_hi:[1,0,0]
	v_pk_fma_f32 v[146:147], v[136:137], v[128:129], v[146:147] op_sel_hi:[0,1,1] neg_lo:[1,0,0] neg_hi:[1,0,0]
	ds_read_b128 v[188:191], v1 offset:46016
	v_pk_fma_f32 v[150:151], v[136:137], v[130:131], v[150:151] op_sel_hi:[0,1,1] neg_lo:[1,0,0] neg_hi:[1,0,0]
	s_waitcnt lgkmcnt(13)
	v_pk_fma_f32 v[156:157], v[136:137], v[224:225], v[156:157] op_sel_hi:[0,1,1] neg_lo:[1,0,0] neg_hi:[1,0,0]
	ds_read_b128 v[128:131], v1 offset:46032
	v_pk_fma_f32 v[158:159], v[136:137], v[226:227], v[158:159] op_sel_hi:[0,1,1] neg_lo:[1,0,0] neg_hi:[1,0,0]
	s_waitcnt lgkmcnt(13)
	v_pk_fma_f32 v[148:149], v[136:137], v[228:229], v[148:149] op_sel_hi:[0,1,1] neg_lo:[1,0,0] neg_hi:[1,0,0]
	ds_read_b128 v[224:227], v1 offset:46048
	v_pk_fma_f32 v[136:137], v[136:137], v[230:231], v[138:139] op_sel_hi:[0,1,1] neg_lo:[1,0,0] neg_hi:[1,0,0]
	s_waitcnt lgkmcnt(13)
	v_pk_fma_f32 v[138:139], v[182:183], v[184:185], v[182:183] op_sel:[1,0,0] neg_lo:[1,0,0] neg_hi:[1,0,0]
	ds_read_b128 v[228:231], v1 offset:46112
	v_pk_fma_f32 v[140:141], v[182:183], v[186:187], v[140:141] op_sel:[1,0,0] neg_lo:[1,0,0] neg_hi:[1,0,0]
	s_waitcnt lgkmcnt(13)
	v_pk_fma_f32 v[142:143], v[182:183], v[124:125], v[142:143] op_sel:[1,0,0] neg_lo:[1,0,0] neg_hi:[1,0,0]
	v_pk_fma_f32 v[144:145], v[182:183], v[126:127], v[144:145] op_sel:[1,0,0] neg_lo:[1,0,0] neg_hi:[1,0,0]
	s_waitcnt lgkmcnt(12)
	v_pk_fma_f32 v[184:185], v[182:183], v[232:233], v[132:133] op_sel:[1,0,0] neg_lo:[1,0,0] neg_hi:[1,0,0]
	v_pk_fma_f32 v[186:187], v[182:183], v[234:235], v[134:135] op_sel:[1,0,0] neg_lo:[1,0,0] neg_hi:[1,0,0]
	ds_read_b128 v[232:235], v1 offset:46128
	ds_read_b128 v[132:135], v1 offset:46144
	s_waitcnt lgkmcnt(12)
	v_pk_fma_f32 v[152:153], v[182:183], v[240:241], v[152:153] op_sel:[1,0,0] neg_lo:[1,0,0] neg_hi:[1,0,0]
	v_pk_fma_f32 v[154:155], v[182:183], v[242:243], v[154:155] op_sel:[1,0,0] neg_lo:[1,0,0] neg_hi:[1,0,0]
	ds_read_b128 v[240:243], v1 offset:46160
	v_pk_fma_f32 v[146:147], v[182:183], v[236:237], v[146:147] op_sel:[1,0,0] neg_lo:[1,0,0] neg_hi:[1,0,0]
	v_pk_fma_f32 v[150:151], v[182:183], v[238:239], v[150:151] op_sel:[1,0,0] neg_lo:[1,0,0] neg_hi:[1,0,0]
	ds_read_b128 v[236:239], v1 offset:46176
	s_waitcnt lgkmcnt(13)
	v_pk_fma_f32 v[156:157], v[182:183], v[64:65], v[156:157] op_sel:[1,0,0] neg_lo:[1,0,0] neg_hi:[1,0,0]
	v_pk_fma_f32 v[158:159], v[182:183], v[66:67], v[158:159] op_sel:[1,0,0] neg_lo:[1,0,0] neg_hi:[1,0,0]
	ds_read_b128 v[64:67], v1 offset:46192
	s_waitcnt lgkmcnt(13)
	v_pk_fma_f32 v[148:149], v[182:183], v[60:61], v[148:149] op_sel:[1,0,0] neg_lo:[1,0,0] neg_hi:[1,0,0]
	v_pk_fma_f32 v[136:137], v[182:183], v[62:63], v[136:137] op_sel:[1,0,0] neg_lo:[1,0,0] neg_hi:[1,0,0]
	ds_read_b128 v[60:63], v1 offset:46256
	s_waitcnt lgkmcnt(13)
	v_pk_fma_f32 v[124:125], v[140:141], v[244:245], v[138:139] op_sel_hi:[0,1,1] neg_lo:[1,0,0] neg_hi:[1,0,0]
	v_pk_fma_f32 v[126:127], v[140:141], v[246:247], v[140:141] op_sel_hi:[0,1,1] neg_lo:[1,0,0] neg_hi:[1,0,0]
	ds_read_b128 v[244:247], v1 offset:46272
	s_waitcnt lgkmcnt(13)
	v_pk_fma_f32 v[138:139], v[140:141], v[220:221], v[142:143] op_sel_hi:[0,1,1] neg_lo:[1,0,0] neg_hi:[1,0,0]
	v_pk_fma_f32 v[142:143], v[140:141], v[222:223], v[144:145] op_sel_hi:[0,1,1] neg_lo:[1,0,0] neg_hi:[1,0,0]
	ds_read_b128 v[220:223], v1 offset:46288
	s_waitcnt lgkmcnt(13)
	v_pk_fma_f32 v[144:145], v[140:141], v[248:249], v[184:185] op_sel_hi:[0,1,1] neg_lo:[1,0,0] neg_hi:[1,0,0]
	v_pk_fma_f32 v[182:183], v[140:141], v[250:251], v[186:187] op_sel_hi:[0,1,1] neg_lo:[1,0,0] neg_hi:[1,0,0]
	ds_read_b128 v[248:251], v1 offset:46304
	s_waitcnt lgkmcnt(12)
	v_pk_fma_f32 v[152:153], v[140:141], v[188:189], v[152:153] op_sel_hi:[0,1,1] neg_lo:[1,0,0] neg_hi:[1,0,0]
	v_pk_fma_f32 v[154:155], v[140:141], v[190:191], v[154:155] op_sel_hi:[0,1,1] neg_lo:[1,0,0] neg_hi:[1,0,0]
	ds_read_b128 v[188:191], v1 offset:46320
	v_pk_fma_f32 v[146:147], v[140:141], v[192:193], v[146:147] op_sel_hi:[0,1,1] neg_lo:[1,0,0] neg_hi:[1,0,0]
	v_pk_fma_f32 v[150:151], v[140:141], v[194:195], v[150:151] op_sel_hi:[0,1,1] neg_lo:[1,0,0] neg_hi:[1,0,0]
	ds_read_b128 v[192:195], v1 offset:46336
	s_waitcnt lgkmcnt(13)
	v_pk_fma_f32 v[156:157], v[140:141], v[128:129], v[156:157] op_sel_hi:[0,1,1] neg_lo:[1,0,0] neg_hi:[1,0,0]
	v_pk_fma_f32 v[158:159], v[140:141], v[130:131], v[158:159] op_sel_hi:[0,1,1] neg_lo:[1,0,0] neg_hi:[1,0,0]
	ds_read_b128 v[128:131], v1 offset:46400
	s_waitcnt lgkmcnt(13)
	v_pk_fma_f32 v[148:149], v[140:141], v[224:225], v[148:149] op_sel_hi:[0,1,1] neg_lo:[1,0,0] neg_hi:[1,0,0]
	v_pk_fma_f32 v[136:137], v[140:141], v[226:227], v[136:137] op_sel_hi:[0,1,1] neg_lo:[1,0,0] neg_hi:[1,0,0]
	ds_read_b128 v[224:227], v1 offset:46416
	s_waitcnt lgkmcnt(13)
	v_pk_fma_f32 v[138:139], v[126:127], v[228:229], v[138:139] op_sel:[1,0,0] neg_lo:[1,0,0] neg_hi:[1,0,0]
	v_pk_fma_f32 v[140:141], v[126:127], v[230:231], v[142:143] op_sel:[1,0,0] neg_lo:[1,0,0] neg_hi:[1,0,0]
	ds_read_b128 v[228:231], v1 offset:46432
	s_waitcnt lgkmcnt(13)
	v_pk_fma_f32 v[142:143], v[126:127], v[232:233], v[144:145] op_sel:[1,0,0] neg_lo:[1,0,0] neg_hi:[1,0,0]
	v_pk_fma_f32 v[144:145], v[126:127], v[234:235], v[182:183] op_sel:[1,0,0] neg_lo:[1,0,0] neg_hi:[1,0,0]
	ds_read_b128 v[232:235], v1 offset:46448
	s_waitcnt lgkmcnt(13)
	v_pk_fma_f32 v[146:147], v[126:127], v[132:133], v[146:147] op_sel:[1,0,0] neg_lo:[1,0,0] neg_hi:[1,0,0]
	v_pk_fma_f32 v[150:151], v[126:127], v[134:135], v[150:151] op_sel:[1,0,0] neg_lo:[1,0,0] neg_hi:[1,0,0]
	ds_read_b128 v[132:135], v1 offset:46464
	s_waitcnt lgkmcnt(12)
	v_pk_fma_f32 v[156:157], v[126:127], v[236:237], v[156:157] op_sel:[1,0,0] neg_lo:[1,0,0] neg_hi:[1,0,0]
	v_pk_fma_f32 v[158:159], v[126:127], v[238:239], v[158:159] op_sel:[1,0,0] neg_lo:[1,0,0] neg_hi:[1,0,0]
	ds_read_b128 v[236:239], v1 offset:46480
	v_pk_fma_f32 v[152:153], v[126:127], v[240:241], v[152:153] op_sel:[1,0,0] neg_lo:[1,0,0] neg_hi:[1,0,0]
	v_pk_fma_f32 v[154:155], v[126:127], v[242:243], v[154:155] op_sel:[1,0,0] neg_lo:[1,0,0] neg_hi:[1,0,0]
	ds_read_b128 v[240:243], v1 offset:46544
	s_waitcnt lgkmcnt(13)
	v_pk_fma_f32 v[148:149], v[126:127], v[64:65], v[148:149] op_sel:[1,0,0] neg_lo:[1,0,0] neg_hi:[1,0,0]
	v_pk_fma_f32 v[136:137], v[126:127], v[66:67], v[136:137] op_sel:[1,0,0] neg_lo:[1,0,0] neg_hi:[1,0,0]
	ds_read_b128 v[64:67], v1 offset:46560
	s_waitcnt lgkmcnt(13)
	v_pk_fma_f32 v[182:183], v[138:139], v[60:61], v[138:139] op_sel_hi:[0,1,1] neg_lo:[1,0,0] neg_hi:[1,0,0]
	v_pk_fma_f32 v[140:141], v[138:139], v[62:63], v[140:141] op_sel_hi:[0,1,1] neg_lo:[1,0,0] neg_hi:[1,0,0]
	ds_read_b128 v[60:63], v1 offset:46576
	s_waitcnt lgkmcnt(13)
	v_pk_fma_f32 v[142:143], v[138:139], v[244:245], v[142:143] op_sel_hi:[0,1,1] neg_lo:[1,0,0] neg_hi:[1,0,0]
	v_pk_fma_f32 v[144:145], v[138:139], v[246:247], v[144:145] op_sel_hi:[0,1,1] neg_lo:[1,0,0] neg_hi:[1,0,0]
	ds_read_b128 v[244:247], v1 offset:46592
	s_waitcnt lgkmcnt(13)
	v_pk_fma_f32 v[146:147], v[138:139], v[220:221], v[146:147] op_sel_hi:[0,1,1] neg_lo:[1,0,0] neg_hi:[1,0,0]
	v_pk_fma_f32 v[150:151], v[138:139], v[222:223], v[150:151] op_sel_hi:[0,1,1] neg_lo:[1,0,0] neg_hi:[1,0,0]
	ds_read_b128 v[220:223], v1 offset:46608
	s_waitcnt lgkmcnt(12)
	v_pk_fma_f32 v[156:157], v[138:139], v[188:189], v[156:157] op_sel_hi:[0,1,1] neg_lo:[1,0,0] neg_hi:[1,0,0]
	v_pk_fma_f32 v[158:159], v[138:139], v[190:191], v[158:159] op_sel_hi:[0,1,1] neg_lo:[1,0,0] neg_hi:[1,0,0]
	ds_read_b128 v[188:191], v1 offset:46624
	v_pk_fma_f32 v[152:153], v[138:139], v[248:249], v[152:153] op_sel_hi:[0,1,1] neg_lo:[1,0,0] neg_hi:[1,0,0]
	v_pk_fma_f32 v[154:155], v[138:139], v[250:251], v[154:155] op_sel_hi:[0,1,1] neg_lo:[1,0,0] neg_hi:[1,0,0]
	ds_read_b128 v[248:251], v1 offset:46704
	s_waitcnt lgkmcnt(13)
	v_pk_fma_f32 v[148:149], v[138:139], v[192:193], v[148:149] op_sel_hi:[0,1,1] neg_lo:[1,0,0] neg_hi:[1,0,0]
	v_pk_fma_f32 v[136:137], v[138:139], v[194:195], v[136:137] op_sel_hi:[0,1,1] neg_lo:[1,0,0] neg_hi:[1,0,0]
	ds_read_b128 v[192:195], v1 offset:46720
	s_waitcnt lgkmcnt(13)
	v_pk_fma_f32 v[184:185], v[182:183], v[128:129], v[182:183] op_sel:[1,0,0] neg_lo:[1,0,0] neg_hi:[1,0,0]
	v_pk_fma_f32 v[140:141], v[182:183], v[130:131], v[140:141] op_sel:[1,0,0] neg_lo:[1,0,0] neg_hi:[1,0,0]
	s_waitcnt lgkmcnt(12)
	v_pk_fma_f32 v[142:143], v[182:183], v[224:225], v[142:143] op_sel:[1,0,0] neg_lo:[1,0,0] neg_hi:[1,0,0]
	v_pk_fma_f32 v[144:145], v[182:183], v[226:227], v[144:145] op_sel:[1,0,0] neg_lo:[1,0,0] neg_hi:[1,0,0]
	ds_read_b128 v[224:227], v1 offset:46736
	s_waitcnt lgkmcnt(12)
	v_pk_fma_f32 v[146:147], v[182:183], v[228:229], v[146:147] op_sel:[1,0,0] neg_lo:[1,0,0] neg_hi:[1,0,0]
	v_pk_fma_f32 v[150:151], v[182:183], v[230:231], v[150:151] op_sel:[1,0,0] neg_lo:[1,0,0] neg_hi:[1,0,0]
	ds_read_b128 v[228:231], v1 offset:46752
	s_waitcnt lgkmcnt(11)
	v_pk_fma_f32 v[156:157], v[182:183], v[132:133], v[156:157] op_sel:[1,0,0] neg_lo:[1,0,0] neg_hi:[1,0,0]
	v_pk_fma_f32 v[158:159], v[182:183], v[134:135], v[158:159] op_sel:[1,0,0] neg_lo:[1,0,0] neg_hi:[1,0,0]
	ds_read_b128 v[132:135], v1 offset:46768
	v_pk_fma_f32 v[152:153], v[182:183], v[232:233], v[152:153] op_sel:[1,0,0] neg_lo:[1,0,0] neg_hi:[1,0,0]
	v_pk_fma_f32 v[154:155], v[182:183], v[234:235], v[154:155] op_sel:[1,0,0] neg_lo:[1,0,0] neg_hi:[1,0,0]
	ds_read_b128 v[232:235], v1 offset:46848
	s_waitcnt lgkmcnt(12)
	v_pk_fma_f32 v[148:149], v[182:183], v[236:237], v[148:149] op_sel:[1,0,0] neg_lo:[1,0,0] neg_hi:[1,0,0]
	v_pk_fma_f32 v[182:183], v[182:183], v[238:239], v[136:137] op_sel:[1,0,0] neg_lo:[1,0,0] neg_hi:[1,0,0]
	ds_read_b128 v[236:239], v1 offset:46864
	ds_read_b128 v[136:139], v1 offset:46880
	s_waitcnt lgkmcnt(13)
	v_pk_fma_f32 v[128:129], v[140:141], v[240:241], v[184:185] op_sel_hi:[0,1,1] neg_lo:[1,0,0] neg_hi:[1,0,0]
	v_pk_fma_f32 v[130:131], v[140:141], v[242:243], v[140:141] op_sel_hi:[0,1,1] neg_lo:[1,0,0] neg_hi:[1,0,0]
	ds_read_b128 v[240:243], v1 offset:46896
	s_waitcnt lgkmcnt(13)
	v_pk_fma_f32 v[142:143], v[140:141], v[64:65], v[142:143] op_sel_hi:[0,1,1] neg_lo:[1,0,0] neg_hi:[1,0,0]
	v_pk_fma_f32 v[144:145], v[140:141], v[66:67], v[144:145] op_sel_hi:[0,1,1] neg_lo:[1,0,0] neg_hi:[1,0,0]
	ds_read_b128 v[64:67], v1 offset:46912
	s_waitcnt lgkmcnt(13)
	v_pk_fma_f32 v[146:147], v[140:141], v[60:61], v[146:147] op_sel_hi:[0,1,1] neg_lo:[1,0,0] neg_hi:[1,0,0]
	v_pk_fma_f32 v[150:151], v[140:141], v[62:63], v[150:151] op_sel_hi:[0,1,1] neg_lo:[1,0,0] neg_hi:[1,0,0]
	ds_read_b128 v[60:63], v1 offset:46992
	s_waitcnt lgkmcnt(12)
	v_pk_fma_f32 v[156:157], v[140:141], v[220:221], v[156:157] op_sel_hi:[0,1,1] neg_lo:[1,0,0] neg_hi:[1,0,0]
	v_pk_fma_f32 v[158:159], v[140:141], v[222:223], v[158:159] op_sel_hi:[0,1,1] neg_lo:[1,0,0] neg_hi:[1,0,0]
	ds_read_b128 v[220:223], v1 offset:47008
	v_pk_fma_f32 v[152:153], v[140:141], v[244:245], v[152:153] op_sel_hi:[0,1,1] neg_lo:[1,0,0] neg_hi:[1,0,0]
	v_pk_fma_f32 v[154:155], v[140:141], v[246:247], v[154:155] op_sel_hi:[0,1,1] neg_lo:[1,0,0] neg_hi:[1,0,0]
	ds_read_b128 v[244:247], v1 offset:47024
	s_waitcnt lgkmcnt(13)
	v_pk_fma_f32 v[148:149], v[140:141], v[188:189], v[148:149] op_sel_hi:[0,1,1] neg_lo:[1,0,0] neg_hi:[1,0,0]
	v_pk_fma_f32 v[140:141], v[140:141], v[190:191], v[182:183] op_sel_hi:[0,1,1] neg_lo:[1,0,0] neg_hi:[1,0,0]
	ds_read_b128 v[188:191], v1 offset:47040
	s_waitcnt lgkmcnt(13)
	v_pk_fma_f32 v[142:143], v[130:131], v[248:249], v[142:143] op_sel:[1,0,0] neg_lo:[1,0,0] neg_hi:[1,0,0]
	v_pk_fma_f32 v[144:145], v[130:131], v[250:251], v[144:145] op_sel:[1,0,0] neg_lo:[1,0,0] neg_hi:[1,0,0]
	ds_read_b128 v[248:251], v1 offset:47056
	s_waitcnt lgkmcnt(13)
	v_pk_fma_f32 v[146:147], v[130:131], v[192:193], v[146:147] op_sel:[1,0,0] neg_lo:[1,0,0] neg_hi:[1,0,0]
	v_pk_fma_f32 v[150:151], v[130:131], v[194:195], v[150:151] op_sel:[1,0,0] neg_lo:[1,0,0] neg_hi:[1,0,0]
	ds_read_b128 v[192:195], v1 offset:47136
	s_waitcnt lgkmcnt(13)
	v_pk_fma_f32 v[152:153], v[130:131], v[224:225], v[152:153] op_sel:[1,0,0] neg_lo:[1,0,0] neg_hi:[1,0,0]
	v_pk_fma_f32 v[154:155], v[130:131], v[226:227], v[154:155] op_sel:[1,0,0] neg_lo:[1,0,0] neg_hi:[1,0,0]
	ds_read_b128 v[224:227], v1 offset:47152
	s_waitcnt lgkmcnt(12)
	v_pk_fma_f32 v[148:149], v[130:131], v[132:133], v[148:149] op_sel:[1,0,0] neg_lo:[1,0,0] neg_hi:[1,0,0]
	v_pk_fma_f32 v[156:157], v[130:131], v[228:229], v[156:157] op_sel:[1,0,0] neg_lo:[1,0,0] neg_hi:[1,0,0]
	v_pk_fma_f32 v[158:159], v[130:131], v[230:231], v[158:159] op_sel:[1,0,0] neg_lo:[1,0,0] neg_hi:[1,0,0]
	ds_read_b128 v[228:231], v1 offset:47168
	v_pk_fma_f32 v[140:141], v[130:131], v[134:135], v[140:141] op_sel:[1,0,0] neg_lo:[1,0,0] neg_hi:[1,0,0]
	s_waitcnt lgkmcnt(12)
	v_pk_fma_f32 v[182:183], v[142:143], v[232:233], v[142:143] op_sel_hi:[0,1,1] neg_lo:[1,0,0] neg_hi:[1,0,0]
	v_pk_fma_f32 v[144:145], v[142:143], v[234:235], v[144:145] op_sel_hi:[0,1,1] neg_lo:[1,0,0] neg_hi:[1,0,0]
	ds_read_b128 v[232:235], v1 offset:47184
	s_waitcnt lgkmcnt(12)
	v_pk_fma_f32 v[146:147], v[142:143], v[236:237], v[146:147] op_sel_hi:[0,1,1] neg_lo:[1,0,0] neg_hi:[1,0,0]
	v_pk_fma_f32 v[150:151], v[142:143], v[238:239], v[150:151] op_sel_hi:[0,1,1] neg_lo:[1,0,0] neg_hi:[1,0,0]
	ds_read_b128 v[236:239], v1 offset:47200
	s_waitcnt lgkmcnt(12)
	v_pk_fma_f32 v[152:153], v[142:143], v[136:137], v[152:153] op_sel_hi:[0,1,1] neg_lo:[1,0,0] neg_hi:[1,0,0]
	v_pk_fma_f32 v[154:155], v[142:143], v[138:139], v[154:155] op_sel_hi:[0,1,1] neg_lo:[1,0,0] neg_hi:[1,0,0]
	ds_read_b128 v[136:139], v1 offset:47296
	s_waitcnt lgkmcnt(11)
	v_pk_fma_f32 v[148:149], v[142:143], v[64:65], v[148:149] op_sel_hi:[0,1,1] neg_lo:[1,0,0] neg_hi:[1,0,0]
	v_pk_fma_f32 v[156:157], v[142:143], v[240:241], v[156:157] op_sel_hi:[0,1,1] neg_lo:[1,0,0] neg_hi:[1,0,0]
	v_pk_fma_f32 v[158:159], v[142:143], v[242:243], v[158:159] op_sel_hi:[0,1,1] neg_lo:[1,0,0] neg_hi:[1,0,0]
	ds_read_b128 v[240:243], v1 offset:47312
	v_pk_fma_f32 v[140:141], v[142:143], v[66:67], v[140:141] op_sel_hi:[0,1,1] neg_lo:[1,0,0] neg_hi:[1,0,0]
	ds_read_b128 v[64:67], v1 offset:47328
	s_waitcnt lgkmcnt(12)
	v_pk_fma_f32 v[184:185], v[182:183], v[60:61], v[182:183] op_sel:[1,0,0] neg_lo:[1,0,0] neg_hi:[1,0,0]
	v_pk_fma_f32 v[144:145], v[182:183], v[62:63], v[144:145] op_sel:[1,0,0] neg_lo:[1,0,0] neg_hi:[1,0,0]
	ds_read_b128 v[60:63], v1 offset:47344
	s_waitcnt lgkmcnt(12)
	v_pk_fma_f32 v[146:147], v[182:183], v[220:221], v[146:147] op_sel:[1,0,0] neg_lo:[1,0,0] neg_hi:[1,0,0]
	v_pk_fma_f32 v[150:151], v[182:183], v[222:223], v[150:151] op_sel:[1,0,0] neg_lo:[1,0,0] neg_hi:[1,0,0]
	ds_read_b128 v[220:223], v1 offset:47440
	s_waitcnt lgkmcnt(12)
	v_pk_fma_f32 v[152:153], v[182:183], v[244:245], v[152:153] op_sel:[1,0,0] neg_lo:[1,0,0] neg_hi:[1,0,0]
	v_pk_fma_f32 v[154:155], v[182:183], v[246:247], v[154:155] op_sel:[1,0,0] neg_lo:[1,0,0] neg_hi:[1,0,0]
	ds_read_b128 v[244:247], v1 offset:47456
	s_waitcnt lgkmcnt(11)
	v_pk_fma_f32 v[148:149], v[182:183], v[248:249], v[148:149] op_sel:[1,0,0] neg_lo:[1,0,0] neg_hi:[1,0,0]
	v_pk_fma_f32 v[156:157], v[182:183], v[188:189], v[156:157] op_sel:[1,0,0] neg_lo:[1,0,0] neg_hi:[1,0,0]
	v_pk_fma_f32 v[158:159], v[182:183], v[190:191], v[158:159] op_sel:[1,0,0] neg_lo:[1,0,0] neg_hi:[1,0,0]
	ds_read_b128 v[188:191], v1 offset:47472
	v_pk_fma_f32 v[182:183], v[182:183], v[250:251], v[140:141] op_sel:[1,0,0] neg_lo:[1,0,0] neg_hi:[1,0,0]
	ds_read_b128 v[248:251], v1 offset:47488
	ds_read_b128 v[140:143], v1 offset:47584
	s_waitcnt lgkmcnt(13)
	v_pk_fma_f32 v[132:133], v[144:145], v[192:193], v[184:185] op_sel_hi:[0,1,1] neg_lo:[1,0,0] neg_hi:[1,0,0]
	v_pk_fma_f32 v[134:135], v[144:145], v[194:195], v[144:145] op_sel_hi:[0,1,1] neg_lo:[1,0,0] neg_hi:[1,0,0]
	ds_read_b128 v[192:195], v1 offset:47600
	s_waitcnt lgkmcnt(11)
	v_pk_fma_f32 v[156:157], v[144:145], v[232:233], v[156:157] op_sel_hi:[0,1,1] neg_lo:[1,0,0] neg_hi:[1,0,0]
	v_pk_fma_f32 v[146:147], v[144:145], v[224:225], v[146:147] op_sel_hi:[0,1,1] neg_lo:[1,0,0] neg_hi:[1,0,0]
	v_pk_fma_f32 v[150:151], v[144:145], v[226:227], v[150:151] op_sel_hi:[0,1,1] neg_lo:[1,0,0] neg_hi:[1,0,0]
	ds_read_b128 v[224:227], v1 offset:47616
	v_pk_fma_f32 v[152:153], v[144:145], v[228:229], v[152:153] op_sel_hi:[0,1,1] neg_lo:[1,0,0] neg_hi:[1,0,0]
	s_waitcnt lgkmcnt(11)
	v_pk_fma_f32 v[148:149], v[144:145], v[236:237], v[148:149] op_sel_hi:[0,1,1] neg_lo:[1,0,0] neg_hi:[1,0,0]
	v_pk_fma_f32 v[154:155], v[144:145], v[230:231], v[154:155] op_sel_hi:[0,1,1] neg_lo:[1,0,0] neg_hi:[1,0,0]
	ds_read_b128 v[228:231], v1 offset:47632
	v_pk_fma_f32 v[158:159], v[144:145], v[234:235], v[158:159] op_sel_hi:[0,1,1] neg_lo:[1,0,0] neg_hi:[1,0,0]
	ds_read_b128 v[232:235], v1 offset:47728
	v_pk_fma_f32 v[144:145], v[144:145], v[238:239], v[182:183] op_sel_hi:[0,1,1] neg_lo:[1,0,0] neg_hi:[1,0,0]
	ds_read_b128 v[236:239], v1 offset:47744
	s_waitcnt lgkmcnt(13)
	v_pk_fma_f32 v[146:147], v[134:135], v[136:137], v[146:147] op_sel:[1,0,0] neg_lo:[1,0,0] neg_hi:[1,0,0]
	s_waitcnt lgkmcnt(10)
	v_pk_fma_f32 v[148:149], v[134:135], v[60:61], v[148:149] op_sel:[1,0,0] neg_lo:[1,0,0] neg_hi:[1,0,0]
	v_pk_fma_f32 v[150:151], v[134:135], v[138:139], v[150:151] op_sel:[1,0,0] neg_lo:[1,0,0] neg_hi:[1,0,0]
	v_pk_fma_f32 v[152:153], v[134:135], v[240:241], v[152:153] op_sel:[1,0,0] neg_lo:[1,0,0] neg_hi:[1,0,0]
	v_pk_fma_f32 v[154:155], v[134:135], v[242:243], v[154:155] op_sel:[1,0,0] neg_lo:[1,0,0] neg_hi:[1,0,0]
	ds_read_b128 v[240:243], v1 offset:47760
	v_pk_fma_f32 v[156:157], v[134:135], v[64:65], v[156:157] op_sel:[1,0,0] neg_lo:[1,0,0] neg_hi:[1,0,0]
	v_pk_fma_f32 v[158:159], v[134:135], v[66:67], v[158:159] op_sel:[1,0,0] neg_lo:[1,0,0] neg_hi:[1,0,0]
	ds_read_b128 v[64:67], v1 offset:47776
	v_pk_fma_f32 v[144:145], v[134:135], v[62:63], v[144:145] op_sel:[1,0,0] neg_lo:[1,0,0] neg_hi:[1,0,0]
	ds_read_b128 v[60:63], v1 offset:47888
	s_waitcnt lgkmcnt(12)
	v_pk_fma_f32 v[182:183], v[146:147], v[220:221], v[146:147] op_sel_hi:[0,1,1] neg_lo:[1,0,0] neg_hi:[1,0,0]
	s_waitcnt lgkmcnt(9)
	v_pk_fma_f32 v[148:149], v[146:147], v[248:249], v[148:149] op_sel_hi:[0,1,1] neg_lo:[1,0,0] neg_hi:[1,0,0]
	v_pk_fma_f32 v[150:151], v[146:147], v[222:223], v[150:151] op_sel_hi:[0,1,1] neg_lo:[1,0,0] neg_hi:[1,0,0]
	ds_read_b128 v[220:223], v1 offset:47904
	v_pk_fma_f32 v[152:153], v[146:147], v[244:245], v[152:153] op_sel_hi:[0,1,1] neg_lo:[1,0,0] neg_hi:[1,0,0]
	v_pk_fma_f32 v[154:155], v[146:147], v[246:247], v[154:155] op_sel_hi:[0,1,1] neg_lo:[1,0,0] neg_hi:[1,0,0]
	ds_read_b128 v[244:247], v1 offset:47920
	v_pk_fma_f32 v[156:157], v[146:147], v[188:189], v[156:157] op_sel_hi:[0,1,1] neg_lo:[1,0,0] neg_hi:[1,0,0]
	v_pk_fma_f32 v[158:159], v[146:147], v[190:191], v[158:159] op_sel_hi:[0,1,1] neg_lo:[1,0,0] neg_hi:[1,0,0]
	ds_read_b128 v[188:191], v1 offset:48032
	v_pk_fma_f32 v[144:145], v[146:147], v[250:251], v[144:145] op_sel_hi:[0,1,1] neg_lo:[1,0,0] neg_hi:[1,0,0]
	ds_read_b128 v[248:251], v1 offset:48048
	s_waitcnt lgkmcnt(12)
	v_pk_fma_f32 v[184:185], v[182:183], v[140:141], v[182:183] op_sel:[1,0,0] neg_lo:[1,0,0] neg_hi:[1,0,0]
	v_pk_fma_f32 v[150:151], v[182:183], v[142:143], v[150:151] op_sel:[1,0,0] neg_lo:[1,0,0] neg_hi:[1,0,0]
	ds_read_b128 v[140:143], v1 offset:48064
	s_waitcnt lgkmcnt(11)
	v_pk_fma_f32 v[156:157], v[182:183], v[224:225], v[156:157] op_sel:[1,0,0] neg_lo:[1,0,0] neg_hi:[1,0,0]
	v_pk_fma_f32 v[152:153], v[182:183], v[192:193], v[152:153] op_sel:[1,0,0] neg_lo:[1,0,0] neg_hi:[1,0,0]
	v_pk_fma_f32 v[154:155], v[182:183], v[194:195], v[154:155] op_sel:[1,0,0] neg_lo:[1,0,0] neg_hi:[1,0,0]
	ds_read_b128 v[192:195], v1 offset:48176
	v_pk_fma_f32 v[158:159], v[182:183], v[226:227], v[158:159] op_sel:[1,0,0] neg_lo:[1,0,0] neg_hi:[1,0,0]
	ds_read_b128 v[224:227], v1 offset:48192
	s_waitcnt lgkmcnt(12)
	v_pk_fma_f32 v[148:149], v[182:183], v[228:229], v[148:149] op_sel:[1,0,0] neg_lo:[1,0,0] neg_hi:[1,0,0]
	v_pk_fma_f32 v[182:183], v[182:183], v[230:231], v[144:145] op_sel:[1,0,0] neg_lo:[1,0,0] neg_hi:[1,0,0]
	ds_read_b128 v[228:231], v1 offset:48208
	s_waitcnt lgkmcnt(12)
	v_pk_fma_f32 v[136:137], v[150:151], v[232:233], v[184:185] op_sel_hi:[0,1,1] neg_lo:[1,0,0] neg_hi:[1,0,0]
	v_pk_fma_f32 v[138:139], v[150:151], v[234:235], v[150:151] op_sel_hi:[0,1,1] neg_lo:[1,0,0] neg_hi:[1,0,0]
	ds_read_b128 v[232:235], v1 offset:48320
	s_waitcnt lgkmcnt(11)
	v_pk_fma_f32 v[156:157], v[150:151], v[240:241], v[156:157] op_sel_hi:[0,1,1] neg_lo:[1,0,0] neg_hi:[1,0,0]
	v_pk_fma_f32 v[152:153], v[150:151], v[236:237], v[152:153] op_sel_hi:[0,1,1] neg_lo:[1,0,0] neg_hi:[1,0,0]
	v_pk_fma_f32 v[154:155], v[150:151], v[238:239], v[154:155] op_sel_hi:[0,1,1] neg_lo:[1,0,0] neg_hi:[1,0,0]
	ds_read_b128 v[236:239], v1 offset:48336
	v_pk_fma_f32 v[158:159], v[150:151], v[242:243], v[158:159] op_sel_hi:[0,1,1] neg_lo:[1,0,0] neg_hi:[1,0,0]
	ds_read_b128 v[240:243], v1 offset:48352
	s_waitcnt lgkmcnt(12)
	v_pk_fma_f32 v[144:145], v[150:151], v[64:65], v[148:149] op_sel_hi:[0,1,1] neg_lo:[1,0,0] neg_hi:[1,0,0]
	v_pk_fma_f32 v[146:147], v[150:151], v[66:67], v[182:183] op_sel_hi:[0,1,1] neg_lo:[1,0,0] neg_hi:[1,0,0]
	ds_read_b128 v[64:67], v1 offset:48480
	s_waitcnt lgkmcnt(12)
	v_pk_fma_f32 v[148:149], v[138:139], v[60:61], v[152:153] op_sel:[1,0,0] neg_lo:[1,0,0] neg_hi:[1,0,0]
	s_waitcnt lgkmcnt(10)
	v_pk_fma_f32 v[144:145], v[138:139], v[244:245], v[144:145] op_sel:[1,0,0] neg_lo:[1,0,0] neg_hi:[1,0,0]
	v_pk_fma_f32 v[150:151], v[138:139], v[62:63], v[154:155] op_sel:[1,0,0] neg_lo:[1,0,0] neg_hi:[1,0,0]
	ds_read_b128 v[60:63], v1 offset:48496
	v_pk_fma_f32 v[152:153], v[138:139], v[220:221], v[156:157] op_sel:[1,0,0] neg_lo:[1,0,0] neg_hi:[1,0,0]
	v_pk_fma_f32 v[154:155], v[138:139], v[222:223], v[158:159] op_sel:[1,0,0] neg_lo:[1,0,0] neg_hi:[1,0,0]
	ds_read_b128 v[220:223], v1 offset:48624
	v_pk_fma_f32 v[146:147], v[138:139], v[246:247], v[146:147] op_sel:[1,0,0] neg_lo:[1,0,0] neg_hi:[1,0,0]
	ds_read_b128 v[244:247], v1 offset:48640
	s_waitcnt lgkmcnt(12)
	v_pk_fma_f32 v[156:157], v[148:149], v[188:189], v[148:149] op_sel_hi:[0,1,1] neg_lo:[1,0,0] neg_hi:[1,0,0]
	s_waitcnt lgkmcnt(10)
	v_pk_fma_f32 v[144:145], v[148:149], v[140:141], v[144:145] op_sel_hi:[0,1,1] neg_lo:[1,0,0] neg_hi:[1,0,0]
	v_pk_fma_f32 v[150:151], v[148:149], v[190:191], v[150:151] op_sel_hi:[0,1,1] neg_lo:[1,0,0] neg_hi:[1,0,0]
	ds_read_b128 v[188:191], v1 offset:48768
	v_pk_fma_f32 v[152:153], v[148:149], v[248:249], v[152:153] op_sel_hi:[0,1,1] neg_lo:[1,0,0] neg_hi:[1,0,0]
	v_pk_fma_f32 v[154:155], v[148:149], v[250:251], v[154:155] op_sel_hi:[0,1,1] neg_lo:[1,0,0] neg_hi:[1,0,0]
	ds_read_b128 v[248:251], v1 offset:48784
	v_pk_fma_f32 v[146:147], v[148:149], v[142:143], v[146:147] op_sel_hi:[0,1,1] neg_lo:[1,0,0] neg_hi:[1,0,0]
	s_waitcnt lgkmcnt(11)
	v_pk_fma_f32 v[148:149], v[156:157], v[192:193], v[156:157] op_sel:[1,0,0] neg_lo:[1,0,0] neg_hi:[1,0,0]
	v_pk_fma_f32 v[150:151], v[156:157], v[194:195], v[150:151] op_sel:[1,0,0] neg_lo:[1,0,0] neg_hi:[1,0,0]
	ds_read_b128 v[192:195], v1 offset:48912
	s_waitcnt lgkmcnt(10)
	v_pk_fma_f32 v[158:159], v[156:157], v[228:229], v[144:145] op_sel:[1,0,0] neg_lo:[1,0,0] neg_hi:[1,0,0]
	v_pk_fma_f32 v[152:153], v[156:157], v[224:225], v[152:153] op_sel:[1,0,0] neg_lo:[1,0,0] neg_hi:[1,0,0]
	v_pk_fma_f32 v[154:155], v[156:157], v[226:227], v[154:155] op_sel:[1,0,0] neg_lo:[1,0,0] neg_hi:[1,0,0]
	ds_read_b128 v[224:227], v1 offset:48928
	v_pk_fma_f32 v[156:157], v[156:157], v[230:231], v[146:147] op_sel:[1,0,0] neg_lo:[1,0,0] neg_hi:[1,0,0]
	ds_read_b128 v[228:231], v1 offset:49072
	s_waitcnt lgkmcnt(11)
	v_pk_fma_f32 v[140:141], v[150:151], v[232:233], v[148:149] op_sel_hi:[0,1,1] neg_lo:[1,0,0] neg_hi:[1,0,0]
	v_pk_fma_f32 v[142:143], v[150:151], v[234:235], v[150:151] op_sel_hi:[0,1,1] neg_lo:[1,0,0] neg_hi:[1,0,0]
	ds_read_b128 v[232:235], v1 offset:49216
	s_waitcnt lgkmcnt(11)
	v_pk_fma_f32 v[148:149], v[150:151], v[236:237], v[152:153] op_sel_hi:[0,1,1] neg_lo:[1,0,0] neg_hi:[1,0,0]
	v_pk_fma_f32 v[152:153], v[150:151], v[238:239], v[154:155] op_sel_hi:[0,1,1] neg_lo:[1,0,0] neg_hi:[1,0,0]
	ds_read_b128 v[236:239], v1 offset:49360
	s_waitcnt lgkmcnt(11)
	v_pk_fma_f32 v[144:145], v[150:151], v[240:241], v[158:159] op_sel_hi:[0,1,1] neg_lo:[1,0,0] neg_hi:[1,0,0]
	v_pk_fma_f32 v[146:147], v[150:151], v[242:243], v[156:157] op_sel_hi:[0,1,1] neg_lo:[1,0,0] neg_hi:[1,0,0]
	ds_read_b128 v[240:243], v1 offset:49504
	s_waitcnt lgkmcnt(11)
	v_pk_fma_f32 v[148:149], v[142:143], v[64:65], v[148:149] op_sel:[1,0,0] neg_lo:[1,0,0] neg_hi:[1,0,0]
	s_waitcnt lgkmcnt(10)
	v_pk_fma_f32 v[144:145], v[142:143], v[60:61], v[144:145] op_sel:[1,0,0] neg_lo:[1,0,0] neg_hi:[1,0,0]
	v_pk_fma_f32 v[150:151], v[142:143], v[66:67], v[152:153] op_sel:[1,0,0] neg_lo:[1,0,0] neg_hi:[1,0,0]
	v_pk_fma_f32 v[146:147], v[142:143], v[62:63], v[146:147] op_sel:[1,0,0] neg_lo:[1,0,0] neg_hi:[1,0,0]
	s_waitcnt lgkmcnt(9)
	v_pk_fma_f32 v[152:153], v[148:149], v[220:221], v[148:149] op_sel_hi:[0,1,1] neg_lo:[1,0,0] neg_hi:[1,0,0]
	s_waitcnt lgkmcnt(8)
	v_pk_fma_f32 v[144:145], v[148:149], v[244:245], v[144:145] op_sel_hi:[0,1,1] neg_lo:[1,0,0] neg_hi:[1,0,0]
	v_pk_fma_f32 v[150:151], v[148:149], v[222:223], v[150:151] op_sel_hi:[0,1,1] neg_lo:[1,0,0] neg_hi:[1,0,0]
	v_pk_fma_f32 v[146:147], v[148:149], v[246:247], v[146:147] op_sel_hi:[0,1,1] neg_lo:[1,0,0] neg_hi:[1,0,0]
	s_waitcnt lgkmcnt(7)
	v_pk_fma_f32 v[148:149], v[152:153], v[188:189], v[152:153] op_sel:[1,0,0] neg_lo:[1,0,0] neg_hi:[1,0,0]
	v_pk_fma_f32 v[154:155], v[152:153], v[190:191], v[150:151] op_sel:[1,0,0] neg_lo:[1,0,0] neg_hi:[1,0,0]
	s_waitcnt lgkmcnt(6)
	v_pk_fma_f32 v[144:145], v[152:153], v[248:249], v[144:145] op_sel:[1,0,0] neg_lo:[1,0,0] neg_hi:[1,0,0]
	v_pk_fma_f32 v[146:147], v[152:153], v[250:251], v[146:147] op_sel:[1,0,0] neg_lo:[1,0,0] neg_hi:[1,0,0]
	s_waitcnt lgkmcnt(5)
	v_pk_fma_f32 v[148:149], v[154:155], v[192:193], v[148:149] op_sel_hi:[0,1,1] neg_lo:[1,0,0] neg_hi:[1,0,0]
	v_pk_fma_f32 v[150:151], v[154:155], v[194:195], v[154:155] op_sel_hi:[0,1,1] neg_lo:[1,0,0] neg_hi:[1,0,0]
	s_waitcnt lgkmcnt(4)
	v_pk_fma_f32 v[64:65], v[154:155], v[224:225], v[144:145] op_sel_hi:[0,1,1] neg_lo:[1,0,0] neg_hi:[1,0,0]
	v_pk_fma_f32 v[66:67], v[154:155], v[226:227], v[146:147] op_sel_hi:[0,1,1] neg_lo:[1,0,0] neg_hi:[1,0,0]
	s_waitcnt lgkmcnt(3)
	v_pk_fma_f32 v[64:65], v[150:151], v[228:229], v[64:65] op_sel:[1,0,0] neg_lo:[1,0,0] neg_hi:[1,0,0]
	v_pk_fma_f32 v[66:67], v[150:151], v[230:231], v[66:67] op_sel:[1,0,0] neg_lo:[1,0,0] neg_hi:[1,0,0]
	s_waitcnt lgkmcnt(2)
	v_pk_fma_f32 v[144:145], v[64:65], v[232:233], v[64:65] op_sel_hi:[0,1,1] neg_lo:[1,0,0] neg_hi:[1,0,0]
	v_pk_fma_f32 v[64:65], v[64:65], v[234:235], v[66:67] op_sel_hi:[0,1,1] neg_lo:[1,0,0] neg_hi:[1,0,0]
	s_waitcnt lgkmcnt(1)
	v_pk_fma_f32 v[66:67], v[144:145], v[236:237], v[144:145] op_sel:[1,0,0] neg_lo:[1,0,0] neg_hi:[1,0,0]
	v_pk_fma_f32 v[64:65], v[144:145], v[238:239], v[64:65] op_sel:[1,0,0] neg_lo:[1,0,0] neg_hi:[1,0,0]
	s_waitcnt lgkmcnt(0)
	v_pk_fma_f32 v[144:145], v[64:65], v[240:241], v[66:67] op_sel_hi:[0,1,1] neg_lo:[1,0,0] neg_hi:[1,0,0]
	v_pk_fma_f32 v[146:147], v[64:65], v[242:243], v[64:65] op_sel_hi:[0,1,1] neg_lo:[1,0,0] neg_hi:[1,0,0]
	s_or_b64 exec, exec, s[2:3]
	s_and_saveexec_b64 s[2:3], s[14:15]
	s_xor_b64 s[2:3], exec, s[2:3]
	s_cbranch_execz .LBB0_600

.Lg6p5_loop:
	s_waitcnt vmcnt(0) lgkmcnt(0)
	s_barrier
	s_add_u32 m0, s8, 0
	ds_read_b128 v[120:123], v248 offset:40960
	global_load_lds_dwordx4 v240, s[98:99]
	s_add_u32 m0, s8, 4096
	ds_read_b128 v[124:127], v248 offset:43008
	global_load_lds_dwordx4 v241, s[98:99]
	s_add_u32 m0, s8, 8192
	ds_read_b128 v[128:131], v248 offset:45056
	global_load_lds_dwordx4 v242, s[98:99]
	s_add_u32 m0, s8, 12288
	ds_read_b128 v[132:135], v248 offset:47104
	global_load_lds_dwordx4 v243, s[98:99]
	s_add_u32 m0, s8, 16384
	ds_read_b128 v[96:99], v246 offset:40960
	global_load_lds_dwordx4 v244, s[98:99]
	s_add_u32 m0, s8, 20480
	ds_read_b128 v[100:103], v246 offset:43008
	global_load_lds_dwordx4 v245, s[98:99]
	s_add_u32 m0, s8, 24576
	ds_read_b128 v[104:107], v246 offset:45056
	global_load_lds_dwordx4 v240, s[100:101]
	s_add_u32 m0, s8, 28672
	ds_read_b128 v[108:111], v246 offset:47104
	global_load_lds_dwordx4 v241, s[100:101]
	s_add_u32 m0, s8, 32768
	ds_read_b128 v[112:115], v246 offset:49152
	global_load_lds_dwordx4 v242, s[100:101]
	s_add_u32 m0, s8, 36864
	ds_read_b128 v[116:119], v246 offset:51200
	global_load_lds_dwordx4 v243, s[100:101]
	s_add_u32 s98, s98, 0x80
	s_addc_u32 s99, s99, 0
	s_add_u32 s100, s100, 0x80
	s_addc_u32 s101, s101, 0
	v_mfma_f32_16x16x32_bf16 v[92:95], v[224:227], v[200:203], v[92:95]
	v_mfma_f32_16x16x32_bf16 v[88:91], v[228:231], v[200:203], v[88:91]
	v_mfma_f32_16x16x32_bf16 v[84:87], v[232:235], v[200:203], v[84:87]
	v_mfma_f32_16x16x32_bf16 v[80:83], v[236:239], v[200:203], v[80:83]
	v_mfma_f32_16x16x32_bf16 v[76:79], v[224:227], v[204:207], v[76:79]
	v_mfma_f32_16x16x32_bf16 v[72:75], v[228:231], v[204:207], v[72:75]
	v_mfma_f32_16x16x32_bf16 v[68:71], v[232:235], v[204:207], v[68:71]
	v_mfma_f32_16x16x32_bf16 v[60:63], v[236:239], v[204:207], v[60:63]
	v_mfma_f32_16x16x32_bf16 v[56:59], v[224:227], v[208:211], v[56:59]
	v_mfma_f32_16x16x32_bf16 v[52:55], v[228:231], v[208:211], v[52:55]
	v_mfma_f32_16x16x32_bf16 v[48:51], v[232:235], v[208:211], v[48:51]
	v_mfma_f32_16x16x32_bf16 v[44:47], v[236:239], v[208:211], v[44:47]
	v_mfma_f32_16x16x32_bf16 v[40:43], v[224:227], v[212:215], v[40:43]
	v_mfma_f32_16x16x32_bf16 v[36:39], v[228:231], v[212:215], v[36:39]
	v_mfma_f32_16x16x32_bf16 v[32:35], v[232:235], v[212:215], v[32:35]
	v_mfma_f32_16x16x32_bf16 v[28:31], v[236:239], v[212:215], v[28:31]
	v_mfma_f32_16x16x32_bf16 v[24:27], v[224:227], v[216:219], v[24:27]
	v_mfma_f32_16x16x32_bf16 v[20:23], v[228:231], v[216:219], v[20:23]
	v_mfma_f32_16x16x32_bf16 v[16:19], v[232:235], v[216:219], v[16:19]
	v_mfma_f32_16x16x32_bf16 v[12:15], v[236:239], v[216:219], v[12:15]
	v_mfma_f32_16x16x32_bf16 v[8:11], v[224:227], v[220:223], v[8:11]
	v_mfma_f32_16x16x32_bf16 v[4:7], v[228:231], v[220:223], v[4:7]
	v_mfma_f32_16x16x32_bf16 v[0:3], v[232:235], v[220:223], v[0:3]
	v_mfma_f32_16x16x32_bf16 v[64:67], v[236:239], v[220:223], v[64:67]
	s_waitcnt lgkmcnt(0)
	v_mfma_f32_16x16x32_bf16 v[92:95], v[120:123], v[96:99], v[92:95]
	v_mfma_f32_16x16x32_bf16 v[88:91], v[124:127], v[96:99], v[88:91]
	ds_read_b128 v[224:227], v249 offset:40960
	v_mfma_f32_16x16x32_bf16 v[84:87], v[128:131], v[96:99], v[84:87]
	v_mfma_f32_16x16x32_bf16 v[80:83], v[132:135], v[96:99], v[80:83]
	ds_read_b128 v[228:231], v249 offset:43008
	v_mfma_f32_16x16x32_bf16 v[76:79], v[120:123], v[100:103], v[76:79]
	v_mfma_f32_16x16x32_bf16 v[72:75], v[124:127], v[100:103], v[72:75]
	ds_read_b128 v[232:235], v249 offset:45056
	v_mfma_f32_16x16x32_bf16 v[68:71], v[128:131], v[100:103], v[68:71]
	v_mfma_f32_16x16x32_bf16 v[60:63], v[132:135], v[100:103], v[60:63]
	ds_read_b128 v[236:239], v249 offset:47104
	v_mfma_f32_16x16x32_bf16 v[56:59], v[120:123], v[104:107], v[56:59]
	v_mfma_f32_16x16x32_bf16 v[52:55], v[124:127], v[104:107], v[52:55]
	ds_read_b128 v[200:203], v247 offset:40960
	v_mfma_f32_16x16x32_bf16 v[48:51], v[128:131], v[104:107], v[48:51]
	v_mfma_f32_16x16x32_bf16 v[44:47], v[132:135], v[104:107], v[44:47]
	ds_read_b128 v[204:207], v247 offset:43008
	v_mfma_f32_16x16x32_bf16 v[40:43], v[120:123], v[108:111], v[40:43]
	v_mfma_f32_16x16x32_bf16 v[36:39], v[124:127], v[108:111], v[36:39]
	ds_read_b128 v[208:211], v247 offset:45056
	v_mfma_f32_16x16x32_bf16 v[32:35], v[128:131], v[108:111], v[32:35]
	v_mfma_f32_16x16x32_bf16 v[28:31], v[132:135], v[108:111], v[28:31]
	ds_read_b128 v[212:215], v247 offset:47104
	v_mfma_f32_16x16x32_bf16 v[24:27], v[120:123], v[112:115], v[24:27]
	v_mfma_f32_16x16x32_bf16 v[20:23], v[124:127], v[112:115], v[20:23]
	ds_read_b128 v[216:219], v247 offset:49152
	v_mfma_f32_16x16x32_bf16 v[16:19], v[128:131], v[112:115], v[16:19]
	v_mfma_f32_16x16x32_bf16 v[12:15], v[132:135], v[112:115], v[12:15]
	ds_read_b128 v[220:223], v247 offset:51200
	v_mfma_f32_16x16x32_bf16 v[8:11], v[120:123], v[116:119], v[8:11]
	v_mfma_f32_16x16x32_bf16 v[4:7], v[124:127], v[116:119], v[4:7]
	v_mfma_f32_16x16x32_bf16 v[0:3], v[128:131], v[116:119], v[0:3]
	v_mfma_f32_16x16x32_bf16 v[64:67], v[132:135], v[116:119], v[64:67]
	s_waitcnt vmcnt(0) lgkmcnt(0)
	s_barrier
	s_add_u32 m0, s8, 40960
	ds_read_b128 v[120:123], v248 offset:0
	global_load_lds_dwordx4 v240, s[98:99]
	s_add_u32 m0, s8, 45056
	ds_read_b128 v[124:127], v248 offset:2048
	global_load_lds_dwordx4 v241, s[98:99]
	s_add_u32 m0, s8, 49152
	ds_read_b128 v[128:131], v248 offset:4096
	global_load_lds_dwordx4 v242, s[98:99]
	s_add_u32 m0, s8, 53248
	ds_read_b128 v[132:135], v248 offset:6144
	global_load_lds_dwordx4 v243, s[98:99]
	s_add_u32 m0, s8, 57344
	ds_read_b128 v[96:99], v246 offset:0
	global_load_lds_dwordx4 v244, s[98:99]
	s_add_u32 m0, s8, 61440
	ds_read_b128 v[100:103], v246 offset:2048
	global_load_lds_dwordx4 v245, s[98:99]
	s_add_u32 m0, s8, 65536
	ds_read_b128 v[104:107], v246 offset:4096
	global_load_lds_dwordx4 v240, s[100:101]
	s_add_u32 m0, s8, 69632
	ds_read_b128 v[108:111], v246 offset:6144
	global_load_lds_dwordx4 v241, s[100:101]
	s_add_u32 m0, s8, 73728
	ds_read_b128 v[112:115], v246 offset:8192
	global_load_lds_dwordx4 v242, s[100:101]
	s_add_u32 m0, s8, 77824
	ds_read_b128 v[116:119], v246 offset:10240
	global_load_lds_dwordx4 v243, s[100:101]
	s_add_u32 s98, s98, 0x80
	s_addc_u32 s99, s99, 0
	s_add_u32 s100, s100, 0x80
	s_addc_u32 s101, s101, 0
	v_mfma_f32_16x16x32_bf16 v[92:95], v[224:227], v[200:203], v[92:95]
	v_mfma_f32_16x16x32_bf16 v[88:91], v[228:231], v[200:203], v[88:91]
	v_mfma_f32_16x16x32_bf16 v[84:87], v[232:235], v[200:203], v[84:87]
	v_mfma_f32_16x16x32_bf16 v[80:83], v[236:239], v[200:203], v[80:83]
	v_mfma_f32_16x16x32_bf16 v[76:79], v[224:227], v[204:207], v[76:79]
	v_mfma_f32_16x16x32_bf16 v[72:75], v[228:231], v[204:207], v[72:75]
	v_mfma_f32_16x16x32_bf16 v[68:71], v[232:235], v[204:207], v[68:71]
	v_mfma_f32_16x16x32_bf16 v[60:63], v[236:239], v[204:207], v[60:63]
	v_mfma_f32_16x16x32_bf16 v[56:59], v[224:227], v[208:211], v[56:59]
	v_mfma_f32_16x16x32_bf16 v[52:55], v[228:231], v[208:211], v[52:55]
	v_mfma_f32_16x16x32_bf16 v[48:51], v[232:235], v[208:211], v[48:51]
	v_mfma_f32_16x16x32_bf16 v[44:47], v[236:239], v[208:211], v[44:47]
	v_mfma_f32_16x16x32_bf16 v[40:43], v[224:227], v[212:215], v[40:43]
	v_mfma_f32_16x16x32_bf16 v[36:39], v[228:231], v[212:215], v[36:39]
	v_mfma_f32_16x16x32_bf16 v[32:35], v[232:235], v[212:215], v[32:35]
	v_mfma_f32_16x16x32_bf16 v[28:31], v[236:239], v[212:215], v[28:31]
	v_mfma_f32_16x16x32_bf16 v[24:27], v[224:227], v[216:219], v[24:27]
	v_mfma_f32_16x16x32_bf16 v[20:23], v[228:231], v[216:219], v[20:23]
	v_mfma_f32_16x16x32_bf16 v[16:19], v[232:235], v[216:219], v[16:19]
	v_mfma_f32_16x16x32_bf16 v[12:15], v[236:239], v[216:219], v[12:15]
	v_mfma_f32_16x16x32_bf16 v[8:11], v[224:227], v[220:223], v[8:11]
	v_mfma_f32_16x16x32_bf16 v[4:7], v[228:231], v[220:223], v[4:7]
	v_mfma_f32_16x16x32_bf16 v[0:3], v[232:235], v[220:223], v[0:3]
	v_mfma_f32_16x16x32_bf16 v[64:67], v[236:239], v[220:223], v[64:67]
	s_waitcnt lgkmcnt(0)
	v_mfma_f32_16x16x32_bf16 v[92:95], v[120:123], v[96:99], v[92:95]
	v_mfma_f32_16x16x32_bf16 v[88:91], v[124:127], v[96:99], v[88:91]
	ds_read_b128 v[224:227], v249 offset:0
	v_mfma_f32_16x16x32_bf16 v[84:87], v[128:131], v[96:99], v[84:87]
	v_mfma_f32_16x16x32_bf16 v[80:83], v[132:135], v[96:99], v[80:83]
	ds_read_b128 v[228:231], v249 offset:2048
	v_mfma_f32_16x16x32_bf16 v[76:79], v[120:123], v[100:103], v[76:79]
	v_mfma_f32_16x16x32_bf16 v[72:75], v[124:127], v[100:103], v[72:75]
	ds_read_b128 v[232:235], v249 offset:4096
	v_mfma_f32_16x16x32_bf16 v[68:71], v[128:131], v[100:103], v[68:71]
	v_mfma_f32_16x16x32_bf16 v[60:63], v[132:135], v[100:103], v[60:63]
	ds_read_b128 v[236:239], v249 offset:6144
	v_mfma_f32_16x16x32_bf16 v[56:59], v[120:123], v[104:107], v[56:59]
	v_mfma_f32_16x16x32_bf16 v[52:55], v[124:127], v[104:107], v[52:55]
	ds_read_b128 v[200:203], v247 offset:0
	v_mfma_f32_16x16x32_bf16 v[48:51], v[128:131], v[104:107], v[48:51]
	v_mfma_f32_16x16x32_bf16 v[44:47], v[132:135], v[104:107], v[44:47]
	ds_read_b128 v[204:207], v247 offset:2048
	v_mfma_f32_16x16x32_bf16 v[40:43], v[120:123], v[108:111], v[40:43]
	v_mfma_f32_16x16x32_bf16 v[36:39], v[124:127], v[108:111], v[36:39]
	ds_read_b128 v[208:211], v247 offset:4096
	v_mfma_f32_16x16x32_bf16 v[32:35], v[128:131], v[108:111], v[32:35]
	v_mfma_f32_16x16x32_bf16 v[28:31], v[132:135], v[108:111], v[28:31]
	ds_read_b128 v[212:215], v247 offset:6144
	v_mfma_f32_16x16x32_bf16 v[24:27], v[120:123], v[112:115], v[24:27]
	v_mfma_f32_16x16x32_bf16 v[20:23], v[124:127], v[112:115], v[20:23]
	ds_read_b128 v[216:219], v247 offset:8192
	v_mfma_f32_16x16x32_bf16 v[16:19], v[128:131], v[112:115], v[16:19]
	v_mfma_f32_16x16x32_bf16 v[12:15], v[132:135], v[112:115], v[12:15]
	ds_read_b128 v[220:223], v247 offset:10240
	v_mfma_f32_16x16x32_bf16 v[8:11], v[120:123], v[116:119], v[8:11]
	v_mfma_f32_16x16x32_bf16 v[4:7], v[124:127], v[116:119], v[4:7]
	v_mfma_f32_16x16x32_bf16 v[0:3], v[128:131], v[116:119], v[0:3]
	v_mfma_f32_16x16x32_bf16 v[64:67], v[132:135], v[116:119], v[64:67]
	s_sub_u32 s9, s9, 1
	s_cmp_lg_u32 s9, 0
	s_cbranch_scc1 .Lg6p5_loop
	s_waitcnt vmcnt(0) lgkmcnt(0)
	s_barrier
	ds_read_b128 v[120:123], v248 offset:40960
	ds_read_b128 v[124:127], v248 offset:43008
	ds_read_b128 v[128:131], v248 offset:45056
	ds_read_b128 v[132:135], v248 offset:47104
	ds_read_b128 v[96:99], v246 offset:40960
	ds_read_b128 v[100:103], v246 offset:43008
	ds_read_b128 v[104:107], v246 offset:45056
	ds_read_b128 v[108:111], v246 offset:47104
	ds_read_b128 v[112:115], v246 offset:49152
	ds_read_b128 v[116:119], v246 offset:51200
	v_mfma_f32_16x16x32_bf16 v[92:95], v[224:227], v[200:203], v[92:95]
	v_mfma_f32_16x16x32_bf16 v[88:91], v[228:231], v[200:203], v[88:91]
	v_mfma_f32_16x16x32_bf16 v[84:87], v[232:235], v[200:203], v[84:87]
	v_mfma_f32_16x16x32_bf16 v[80:83], v[236:239], v[200:203], v[80:83]
	v_mfma_f32_16x16x32_bf16 v[76:79], v[224:227], v[204:207], v[76:79]
	v_mfma_f32_16x16x32_bf16 v[72:75], v[228:231], v[204:207], v[72:75]
	v_mfma_f32_16x16x32_bf16 v[68:71], v[232:235], v[204:207], v[68:71]
	v_mfma_f32_16x16x32_bf16 v[60:63], v[236:239], v[204:207], v[60:63]
	v_mfma_f32_16x16x32_bf16 v[56:59], v[224:227], v[208:211], v[56:59]
	v_mfma_f32_16x16x32_bf16 v[52:55], v[228:231], v[208:211], v[52:55]
	v_mfma_f32_16x16x32_bf16 v[48:51], v[232:235], v[208:211], v[48:51]
	v_mfma_f32_16x16x32_bf16 v[44:47], v[236:239], v[208:211], v[44:47]
	v_mfma_f32_16x16x32_bf16 v[40:43], v[224:227], v[212:215], v[40:43]
	v_mfma_f32_16x16x32_bf16 v[36:39], v[228:231], v[212:215], v[36:39]
	v_mfma_f32_16x16x32_bf16 v[32:35], v[232:235], v[212:215], v[32:35]
	v_mfma_f32_16x16x32_bf16 v[28:31], v[236:239], v[212:215], v[28:31]
	v_mfma_f32_16x16x32_bf16 v[24:27], v[224:227], v[216:219], v[24:27]
	v_mfma_f32_16x16x32_bf16 v[20:23], v[228:231], v[216:219], v[20:23]
	v_mfma_f32_16x16x32_bf16 v[16:19], v[232:235], v[216:219], v[16:19]
	v_mfma_f32_16x16x32_bf16 v[12:15], v[236:239], v[216:219], v[12:15]
	v_mfma_f32_16x16x32_bf16 v[8:11], v[224:227], v[220:223], v[8:11]
	v_mfma_f32_16x16x32_bf16 v[4:7], v[228:231], v[220:223], v[4:7]
	v_mfma_f32_16x16x32_bf16 v[0:3], v[232:235], v[220:223], v[0:3]
	v_mfma_f32_16x16x32_bf16 v[64:67], v[236:239], v[220:223], v[64:67]
	s_waitcnt lgkmcnt(0)
	v_mfma_f32_16x16x32_bf16 v[92:95], v[120:123], v[96:99], v[92:95]
	v_mfma_f32_16x16x32_bf16 v[88:91], v[124:127], v[96:99], v[88:91]
	ds_read_b128 v[224:227], v249 offset:40960
	v_mfma_f32_16x16x32_bf16 v[84:87], v[128:131], v[96:99], v[84:87]
	v_mfma_f32_16x16x32_bf16 v[80:83], v[132:135], v[96:99], v[80:83]
	ds_read_b128 v[228:231], v249 offset:43008
	v_mfma_f32_16x16x32_bf16 v[76:79], v[120:123], v[100:103], v[76:79]
	v_mfma_f32_16x16x32_bf16 v[72:75], v[124:127], v[100:103], v[72:75]
	ds_read_b128 v[232:235], v249 offset:45056
	v_mfma_f32_16x16x32_bf16 v[68:71], v[128:131], v[100:103], v[68:71]
	v_mfma_f32_16x16x32_bf16 v[60:63], v[132:135], v[100:103], v[60:63]
	ds_read_b128 v[236:239], v249 offset:47104
	v_mfma_f32_16x16x32_bf16 v[56:59], v[120:123], v[104:107], v[56:59]
	v_mfma_f32_16x16x32_bf16 v[52:55], v[124:127], v[104:107], v[52:55]
	ds_read_b128 v[200:203], v247 offset:40960
	v_mfma_f32_16x16x32_bf16 v[48:51], v[128:131], v[104:107], v[48:51]
	v_mfma_f32_16x16x32_bf16 v[44:47], v[132:135], v[104:107], v[44:47]
	ds_read_b128 v[204:207], v247 offset:43008
	v_mfma_f32_16x16x32_bf16 v[40:43], v[120:123], v[108:111], v[40:43]
	v_mfma_f32_16x16x32_bf16 v[36:39], v[124:127], v[108:111], v[36:39]
	ds_read_b128 v[208:211], v247 offset:45056
	v_mfma_f32_16x16x32_bf16 v[32:35], v[128:131], v[108:111], v[32:35]
	v_mfma_f32_16x16x32_bf16 v[28:31], v[132:135], v[108:111], v[28:31]
	ds_read_b128 v[212:215], v247 offset:47104
	v_mfma_f32_16x16x32_bf16 v[24:27], v[120:123], v[112:115], v[24:27]
	v_mfma_f32_16x16x32_bf16 v[20:23], v[124:127], v[112:115], v[20:23]
	ds_read_b128 v[216:219], v247 offset:49152
	v_mfma_f32_16x16x32_bf16 v[16:19], v[128:131], v[112:115], v[16:19]
	v_mfma_f32_16x16x32_bf16 v[12:15], v[132:135], v[112:115], v[12:15]
	ds_read_b128 v[220:223], v247 offset:51200
	v_mfma_f32_16x16x32_bf16 v[8:11], v[120:123], v[116:119], v[8:11]
	v_mfma_f32_16x16x32_bf16 v[4:7], v[124:127], v[116:119], v[4:7]
	v_mfma_f32_16x16x32_bf16 v[0:3], v[128:131], v[116:119], v[0:3]
	v_mfma_f32_16x16x32_bf16 v[64:67], v[132:135], v[116:119], v[64:67]
	s_waitcnt lgkmcnt(0)
	v_mfma_f32_16x16x32_bf16 v[92:95], v[224:227], v[200:203], v[92:95]
	v_mfma_f32_16x16x32_bf16 v[88:91], v[228:231], v[200:203], v[88:91]
	v_mfma_f32_16x16x32_bf16 v[84:87], v[232:235], v[200:203], v[84:87]
	v_mfma_f32_16x16x32_bf16 v[80:83], v[236:239], v[200:203], v[80:83]
	v_mfma_f32_16x16x32_bf16 v[76:79], v[224:227], v[204:207], v[76:79]
	v_mfma_f32_16x16x32_bf16 v[72:75], v[228:231], v[204:207], v[72:75]
	v_mfma_f32_16x16x32_bf16 v[68:71], v[232:235], v[204:207], v[68:71]
	v_mfma_f32_16x16x32_bf16 v[60:63], v[236:239], v[204:207], v[60:63]
	v_mfma_f32_16x16x32_bf16 v[56:59], v[224:227], v[208:211], v[56:59]
	v_mfma_f32_16x16x32_bf16 v[52:55], v[228:231], v[208:211], v[52:55]
	v_mfma_f32_16x16x32_bf16 v[48:51], v[232:235], v[208:211], v[48:51]
	v_mfma_f32_16x16x32_bf16 v[44:47], v[236:239], v[208:211], v[44:47]
	v_mfma_f32_16x16x32_bf16 v[40:43], v[224:227], v[212:215], v[40:43]
	v_mfma_f32_16x16x32_bf16 v[36:39], v[228:231], v[212:215], v[36:39]
	v_mfma_f32_16x16x32_bf16 v[32:35], v[232:235], v[212:215], v[32:35]
	v_mfma_f32_16x16x32_bf16 v[28:31], v[236:239], v[212:215], v[28:31]
	v_mfma_f32_16x16x32_bf16 v[24:27], v[224:227], v[216:219], v[24:27]
	v_mfma_f32_16x16x32_bf16 v[20:23], v[228:231], v[216:219], v[20:23]
	v_mfma_f32_16x16x32_bf16 v[16:19], v[232:235], v[216:219], v[16:19]
	v_mfma_f32_16x16x32_bf16 v[12:15], v[236:239], v[216:219], v[12:15]
	v_mfma_f32_16x16x32_bf16 v[8:11], v[224:227], v[220:223], v[8:11]
	v_mfma_f32_16x16x32_bf16 v[4:7], v[228:231], v[220:223], v[4:7]
	v_mfma_f32_16x16x32_bf16 v[0:3], v[232:235], v[220:223], v[0:3]
	v_mfma_f32_16x16x32_bf16 v[64:67], v[236:239], v[220:223], v[64:67]
	s_nop 7
	s_nop 7
	s_barrier
	ds_write_b64 v252, v[250:251]
	s_add_i32 s13, s13, s12
	s_ashr_i32 s4, s13, 6
	s_mul_i32 s4, s4, s11
	s_add_i32 s8, s4, s10
	s_add_i32 s14, s14, s15
	s_add_i32 s16, s16, s17
	s_cmp_lt_i32 s8, 8
	v_cvt_pk_bf16_f32 v8, v8, v9
	v_cvt_pk_bf16_f32 v9, v10, v11
	v_cvt_pk_bf16_f32 v4, v4, v5
	v_cvt_pk_bf16_f32 v5, v6, v7
	v_add_u32_e32 v6, 0x2800, v164
	ds_write2_b64 v6, v[8:9], v[4:5] offset0:160 offset1:164
	v_cvt_pk_bf16_f32 v4, v0, v1
	v_cvt_pk_bf16_f32 v5, v2, v3
	v_cvt_pk_bf16_f32 v92, v92, v93
	v_cvt_pk_bf16_f32 v93, v94, v95
	v_cvt_pk_bf16_f32 v88, v88, v89
	v_cvt_pk_bf16_f32 v89, v90, v91
	ds_write2_b64 v164, v[92:93], v[88:89] offset1:4
	v_cvt_pk_bf16_f32 v84, v84, v85
	v_cvt_pk_bf16_f32 v85, v86, v87
	v_cvt_pk_bf16_f32 v80, v80, v81
	v_cvt_pk_bf16_f32 v81, v82, v83
	v_cvt_pk_bf16_f32 v76, v76, v77
	v_cvt_pk_bf16_f32 v77, v78, v79
	v_cvt_pk_bf16_f32 v72, v72, v73
	v_cvt_pk_bf16_f32 v73, v74, v75
	v_add_u32_e32 v74, 0x800, v164
	v_cvt_pk_bf16_f32 v68, v68, v69
	v_cvt_pk_bf16_f32 v69, v70, v71
	ds_write2_b64 v164, v[84:85], v[80:81] offset0:8 offset1:12
	v_cvt_pk_bf16_f32 v60, v60, v61
	v_cvt_pk_bf16_f32 v61, v62, v63
	ds_write2_b64 v74, v[76:77], v[72:73] offset0:32 offset1:36
	v_cvt_pk_bf16_f32 v56, v56, v57
	v_cvt_pk_bf16_f32 v57, v58, v59
	ds_write2_b64 v74, v[68:69], v[60:61] offset0:40 offset1:44
	v_cvt_pk_bf16_f32 v52, v52, v53
	v_cvt_pk_bf16_f32 v53, v54, v55
	v_add_u32_e32 v54, 0x1000, v164
	v_cvt_pk_bf16_f32 v48, v48, v49
	v_cvt_pk_bf16_f32 v49, v50, v51
	ds_write2_b64 v54, v[56:57], v[52:53] offset0:64 offset1:68
	v_cvt_pk_bf16_f32 v44, v44, v45
	v_cvt_pk_bf16_f32 v45, v46, v47
	ds_write2_b64 v54, v[48:49], v[44:45] offset0:72 offset1:76
	v_cvt_pk_bf16_f32 v40, v40, v41
	v_cvt_pk_bf16_f32 v41, v42, v43
	v_cvt_pk_bf16_f32 v36, v36, v37
	v_cvt_pk_bf16_f32 v37, v38, v39
	v_add_u32_e32 v38, 0x1800, v164
	v_cvt_pk_bf16_f32 v32, v32, v33
	v_cvt_pk_bf16_f32 v33, v34, v35
	v_cvt_pk_bf16_f32 v28, v28, v29
	v_cvt_pk_bf16_f32 v29, v30, v31
	v_cvt_pk_bf16_f32 v24, v24, v25
	v_cvt_pk_bf16_f32 v25, v26, v27
	ds_write2_b64 v38, v[40:41], v[36:37] offset0:96 offset1:100
	v_cvt_pk_bf16_f32 v20, v20, v21
	v_cvt_pk_bf16_f32 v21, v22, v23
	v_add_u32_e32 v22, 0x2000, v164
	v_cvt_pk_bf16_f32 v16, v16, v17
	v_cvt_pk_bf16_f32 v17, v18, v19
	v_mov_b32_e32 v0, v64
	v_mov_b32_e32 v1, v65
	v_mov_b32_e32 v2, v66
	v_mov_b32_e32 v3, v67
	ds_write2_b64 v38, v[32:33], v[28:29] offset0:104 offset1:108
	s_nop 2
	v_cvt_pk_bf16_f32 v12, v12, v13
	v_cvt_pk_bf16_f32 v13, v14, v15
	ds_write2_b64 v22, v[24:25], v[20:21] offset0:128 offset1:132
	ds_write2_b64 v22, v[16:17], v[12:13] offset0:136 offset1:140
	v_cvt_pk_bf16_f32 v0, v0, v1
	v_cvt_pk_bf16_f32 v1, v2, v3
	ds_write2_b64 v6, v[4:5], v[0:1] offset0:168 offset1:172
	s_waitcnt lgkmcnt(0)
	v_or_b32_e32 v0, s33, v152
	v_add_u32_e32 v12, s6, v150
	v_lshlrev_b32_e32 v136, 1, v0
	ds_read_b128 v[0:3], v165
	v_or_b32_e32 v4, v12, v151
	v_ashrrev_i32_e32 v5, 31, v4
	v_lshl_add_u64 v[8:9], s[2:3], 0, v[136:137]
	v_lshlrev_b64 v[4:5], 11, v[4:5]
	v_lshl_add_u64 v[10:11], v[8:9], 0, v[4:5]
	ds_read_b128 v[4:7], v165 offset:1152
	s_waitcnt lgkmcnt(1)
	global_store_dwordx4 v[10:11], v[0:3], off
	s_nop 1
	v_or_b32_e32 v0, v12, v153
	v_ashrrev_i32_e32 v1, 31, v0
	v_lshlrev_b64 v[0:1], 11, v[0:1]
	v_lshl_add_u64 v[0:1], v[8:9], 0, v[0:1]
	s_waitcnt lgkmcnt(0)
	global_store_dwordx4 v[0:1], v[4:7], off
	ds_read_b128 v[0:3], v165 offset:2304
	s_nop 0
	v_or_b32_e32 v4, v12, v154
	v_ashrrev_i32_e32 v5, 31, v4
	v_lshlrev_b64 v[4:5], 11, v[4:5]
	v_lshl_add_u64 v[10:11], v[8:9], 0, v[4:5]
	ds_read_b128 v[4:7], v165 offset:3456
	s_waitcnt lgkmcnt(1)
	global_store_dwordx4 v[10:11], v[0:3], off
	s_nop 1
	v_or_b32_e32 v0, v12, v155
	v_ashrrev_i32_e32 v1, 31, v0
	v_lshlrev_b64 v[0:1], 11, v[0:1]
	v_lshl_add_u64 v[0:1], v[8:9], 0, v[0:1]
	s_waitcnt lgkmcnt(0)
	global_store_dwordx4 v[0:1], v[4:7], off
	ds_read_b128 v[0:3], v165 offset:4608
	s_nop 0
	v_add_u32_e32 v4, v12, v156
	v_ashrrev_i32_e32 v5, 31, v4
	v_lshlrev_b64 v[4:5], 11, v[4:5]
	v_lshl_add_u64 v[10:11], v[8:9], 0, v[4:5]
	ds_read_b128 v[4:7], v165 offset:5760
	s_waitcnt lgkmcnt(1)
	global_store_dwordx4 v[10:11], v[0:3], off
	s_nop 1
	v_add_u32_e32 v0, v12, v157
	v_ashrrev_i32_e32 v1, 31, v0
	v_lshlrev_b64 v[0:1], 11, v[0:1]
	v_lshl_add_u64 v[0:1], v[8:9], 0, v[0:1]
	s_waitcnt lgkmcnt(0)
	global_store_dwordx4 v[0:1], v[4:7], off
	ds_read_b128 v[0:3], v165 offset:6912
	s_nop 0
	v_add_u32_e32 v4, v12, v158
	v_ashrrev_i32_e32 v5, 31, v4
	v_lshlrev_b64 v[4:5], 11, v[4:5]
	v_lshl_add_u64 v[10:11], v[8:9], 0, v[4:5]
	ds_read_b128 v[4:7], v165 offset:8064
	s_waitcnt lgkmcnt(1)
	global_store_dwordx4 v[10:11], v[0:3], off
	s_nop 1
	v_add_u32_e32 v0, v12, v159
	v_ashrrev_i32_e32 v1, 31, v0
	v_lshlrev_b64 v[0:1], 11, v[0:1]
	v_lshl_add_u64 v[0:1], v[8:9], 0, v[0:1]
	s_waitcnt lgkmcnt(0)
	global_store_dwordx4 v[0:1], v[4:7], off
	ds_read_b128 v[0:3], v165 offset:9216
	s_nop 0
	v_add_u32_e32 v4, v12, v160
	v_ashrrev_i32_e32 v5, 31, v4
	v_lshlrev_b64 v[4:5], 11, v[4:5]
	v_lshl_add_u64 v[10:11], v[8:9], 0, v[4:5]
	ds_read_b128 v[4:7], v165 offset:10368
	s_waitcnt lgkmcnt(1)
	global_store_dwordx4 v[10:11], v[0:3], off
	s_nop 1
	v_add_u32_e32 v0, v12, v161
	v_ashrrev_i32_e32 v1, 31, v0
	v_lshlrev_b64 v[0:1], 11, v[0:1]
	v_lshl_add_u64 v[0:1], v[8:9], 0, v[0:1]
	s_waitcnt lgkmcnt(0)
	global_store_dwordx4 v[0:1], v[4:7], off
	ds_read_b128 v[0:3], v165 offset:11520
	s_nop 0
	v_add_u32_e32 v4, v12, v162
	v_ashrrev_i32_e32 v5, 31, v4
	v_lshlrev_b64 v[4:5], 11, v[4:5]
	v_lshl_add_u64 v[10:11], v[8:9], 0, v[4:5]
	ds_read_b128 v[4:7], v165 offset:12672
	s_waitcnt lgkmcnt(1)
	global_store_dwordx4 v[10:11], v[0:3], off
	s_nop 1
	v_add_u32_e32 v0, v12, v163
	v_ashrrev_i32_e32 v1, 31, v0
	v_lshlrev_b64 v[0:1], 11, v[0:1]
	v_lshl_add_u64 v[0:1], v[8:9], 0, v[0:1]
	s_waitcnt lgkmcnt(0)
	global_store_dwordx4 v[0:1], v[4:7], off
	s_cbranch_scc1 .LBB0_819

.Lg6p7_loop:
	s_waitcnt vmcnt(0) lgkmcnt(0)
	s_barrier
	s_add_u32 m0, s8, 0
	ds_read_b128 v[120:123], v248 offset:40960
	global_load_lds_dwordx4 v240, s[98:99]
	s_add_u32 m0, s8, 4096
	ds_read_b128 v[124:127], v248 offset:43008
	global_load_lds_dwordx4 v241, s[98:99]
	s_add_u32 m0, s8, 8192
	ds_read_b128 v[128:131], v248 offset:45056
	global_load_lds_dwordx4 v242, s[98:99]
	s_add_u32 m0, s8, 12288
	ds_read_b128 v[132:135], v248 offset:47104
	global_load_lds_dwordx4 v243, s[98:99]
	s_add_u32 m0, s8, 16384
	ds_read_b128 v[96:99], v246 offset:40960
	global_load_lds_dwordx4 v244, s[98:99]
	s_add_u32 m0, s8, 20480
	ds_read_b128 v[100:103], v246 offset:43008
	global_load_lds_dwordx4 v245, s[98:99]
	s_add_u32 m0, s8, 24576
	ds_read_b128 v[104:107], v246 offset:45056
	global_load_lds_dwordx4 v240, s[100:101]
	s_add_u32 m0, s8, 28672
	ds_read_b128 v[108:111], v246 offset:47104
	global_load_lds_dwordx4 v241, s[100:101]
	s_add_u32 m0, s8, 32768
	ds_read_b128 v[112:115], v246 offset:49152
	global_load_lds_dwordx4 v242, s[100:101]
	s_add_u32 m0, s8, 36864
	ds_read_b128 v[116:119], v246 offset:51200
	global_load_lds_dwordx4 v243, s[100:101]
	s_add_u32 s98, s98, 0x80
	s_addc_u32 s99, s99, 0
	s_add_u32 s100, s100, 0x80
	s_addc_u32 s101, s101, 0
	v_mfma_f32_16x16x32_bf16 v[92:95], v[224:227], v[200:203], v[92:95]
	v_mfma_f32_16x16x32_bf16 v[88:91], v[228:231], v[200:203], v[88:91]
	v_mfma_f32_16x16x32_bf16 v[84:87], v[232:235], v[200:203], v[84:87]
	v_mfma_f32_16x16x32_bf16 v[80:83], v[236:239], v[200:203], v[80:83]
	v_mfma_f32_16x16x32_bf16 v[76:79], v[224:227], v[204:207], v[76:79]
	v_mfma_f32_16x16x32_bf16 v[72:75], v[228:231], v[204:207], v[72:75]
	v_mfma_f32_16x16x32_bf16 v[68:71], v[232:235], v[204:207], v[68:71]
	v_mfma_f32_16x16x32_bf16 v[64:67], v[236:239], v[204:207], v[64:67]
	v_mfma_f32_16x16x32_bf16 v[56:59], v[224:227], v[208:211], v[56:59]
	v_mfma_f32_16x16x32_bf16 v[52:55], v[228:231], v[208:211], v[52:55]
	v_mfma_f32_16x16x32_bf16 v[48:51], v[232:235], v[208:211], v[48:51]
	v_mfma_f32_16x16x32_bf16 v[44:47], v[236:239], v[208:211], v[44:47]
	v_mfma_f32_16x16x32_bf16 v[40:43], v[224:227], v[212:215], v[40:43]
	v_mfma_f32_16x16x32_bf16 v[36:39], v[228:231], v[212:215], v[36:39]
	v_mfma_f32_16x16x32_bf16 v[32:35], v[232:235], v[212:215], v[32:35]
	v_mfma_f32_16x16x32_bf16 v[28:31], v[236:239], v[212:215], v[28:31]
	v_mfma_f32_16x16x32_bf16 v[24:27], v[224:227], v[216:219], v[24:27]
	v_mfma_f32_16x16x32_bf16 v[20:23], v[228:231], v[216:219], v[20:23]
	v_mfma_f32_16x16x32_bf16 v[16:19], v[232:235], v[216:219], v[16:19]
	v_mfma_f32_16x16x32_bf16 v[12:15], v[236:239], v[216:219], v[12:15]
	v_mfma_f32_16x16x32_bf16 v[8:11], v[224:227], v[220:223], v[8:11]
	v_mfma_f32_16x16x32_bf16 v[4:7], v[228:231], v[220:223], v[4:7]
	v_mfma_f32_16x16x32_bf16 v[0:3], v[232:235], v[220:223], v[0:3]
	v_mfma_f32_16x16x32_bf16 v[60:63], v[236:239], v[220:223], v[60:63]
	s_waitcnt lgkmcnt(0)
	v_mfma_f32_16x16x32_bf16 v[92:95], v[120:123], v[96:99], v[92:95]
	v_mfma_f32_16x16x32_bf16 v[88:91], v[124:127], v[96:99], v[88:91]
	ds_read_b128 v[224:227], v249 offset:40960
	v_mfma_f32_16x16x32_bf16 v[84:87], v[128:131], v[96:99], v[84:87]
	v_mfma_f32_16x16x32_bf16 v[80:83], v[132:135], v[96:99], v[80:83]
	ds_read_b128 v[228:231], v249 offset:43008
	v_mfma_f32_16x16x32_bf16 v[76:79], v[120:123], v[100:103], v[76:79]
	v_mfma_f32_16x16x32_bf16 v[72:75], v[124:127], v[100:103], v[72:75]
	ds_read_b128 v[232:235], v249 offset:45056
	v_mfma_f32_16x16x32_bf16 v[68:71], v[128:131], v[100:103], v[68:71]
	v_mfma_f32_16x16x32_bf16 v[64:67], v[132:135], v[100:103], v[64:67]
	ds_read_b128 v[236:239], v249 offset:47104
	v_mfma_f32_16x16x32_bf16 v[56:59], v[120:123], v[104:107], v[56:59]
	v_mfma_f32_16x16x32_bf16 v[52:55], v[124:127], v[104:107], v[52:55]
	ds_read_b128 v[200:203], v247 offset:40960
	v_mfma_f32_16x16x32_bf16 v[48:51], v[128:131], v[104:107], v[48:51]
	v_mfma_f32_16x16x32_bf16 v[44:47], v[132:135], v[104:107], v[44:47]
	ds_read_b128 v[204:207], v247 offset:43008
	v_mfma_f32_16x16x32_bf16 v[40:43], v[120:123], v[108:111], v[40:43]
	v_mfma_f32_16x16x32_bf16 v[36:39], v[124:127], v[108:111], v[36:39]
	ds_read_b128 v[208:211], v247 offset:45056
	v_mfma_f32_16x16x32_bf16 v[32:35], v[128:131], v[108:111], v[32:35]
	v_mfma_f32_16x16x32_bf16 v[28:31], v[132:135], v[108:111], v[28:31]
	ds_read_b128 v[212:215], v247 offset:47104
	v_mfma_f32_16x16x32_bf16 v[24:27], v[120:123], v[112:115], v[24:27]
	v_mfma_f32_16x16x32_bf16 v[20:23], v[124:127], v[112:115], v[20:23]
	ds_read_b128 v[216:219], v247 offset:49152
	v_mfma_f32_16x16x32_bf16 v[16:19], v[128:131], v[112:115], v[16:19]
	v_mfma_f32_16x16x32_bf16 v[12:15], v[132:135], v[112:115], v[12:15]
	ds_read_b128 v[220:223], v247 offset:51200
	v_mfma_f32_16x16x32_bf16 v[8:11], v[120:123], v[116:119], v[8:11]
	v_mfma_f32_16x16x32_bf16 v[4:7], v[124:127], v[116:119], v[4:7]
	v_mfma_f32_16x16x32_bf16 v[0:3], v[128:131], v[116:119], v[0:3]
	v_mfma_f32_16x16x32_bf16 v[60:63], v[132:135], v[116:119], v[60:63]
	s_waitcnt vmcnt(0) lgkmcnt(0)
	s_barrier
	s_add_u32 m0, s8, 40960
	ds_read_b128 v[120:123], v248 offset:0
	global_load_lds_dwordx4 v240, s[98:99]
	s_add_u32 m0, s8, 45056
	ds_read_b128 v[124:127], v248 offset:2048
	global_load_lds_dwordx4 v241, s[98:99]
	s_add_u32 m0, s8, 49152
	ds_read_b128 v[128:131], v248 offset:4096
	global_load_lds_dwordx4 v242, s[98:99]
	s_add_u32 m0, s8, 53248
	ds_read_b128 v[132:135], v248 offset:6144
	global_load_lds_dwordx4 v243, s[98:99]
	s_add_u32 m0, s8, 57344
	ds_read_b128 v[96:99], v246 offset:0
	global_load_lds_dwordx4 v244, s[98:99]
	s_add_u32 m0, s8, 61440
	ds_read_b128 v[100:103], v246 offset:2048
	global_load_lds_dwordx4 v245, s[98:99]
	s_add_u32 m0, s8, 65536
	ds_read_b128 v[104:107], v246 offset:4096
	global_load_lds_dwordx4 v240, s[100:101]
	s_add_u32 m0, s8, 69632
	ds_read_b128 v[108:111], v246 offset:6144
	global_load_lds_dwordx4 v241, s[100:101]
	s_add_u32 m0, s8, 73728
	ds_read_b128 v[112:115], v246 offset:8192
	global_load_lds_dwordx4 v242, s[100:101]
	s_add_u32 m0, s8, 77824
	ds_read_b128 v[116:119], v246 offset:10240
	global_load_lds_dwordx4 v243, s[100:101]
	s_add_u32 s98, s98, 0x80
	s_addc_u32 s99, s99, 0
	s_add_u32 s100, s100, 0x80
	s_addc_u32 s101, s101, 0
	v_mfma_f32_16x16x32_bf16 v[92:95], v[224:227], v[200:203], v[92:95]
	v_mfma_f32_16x16x32_bf16 v[88:91], v[228:231], v[200:203], v[88:91]
	v_mfma_f32_16x16x32_bf16 v[84:87], v[232:235], v[200:203], v[84:87]
	v_mfma_f32_16x16x32_bf16 v[80:83], v[236:239], v[200:203], v[80:83]
	v_mfma_f32_16x16x32_bf16 v[76:79], v[224:227], v[204:207], v[76:79]
	v_mfma_f32_16x16x32_bf16 v[72:75], v[228:231], v[204:207], v[72:75]
	v_mfma_f32_16x16x32_bf16 v[68:71], v[232:235], v[204:207], v[68:71]
	v_mfma_f32_16x16x32_bf16 v[64:67], v[236:239], v[204:207], v[64:67]
	v_mfma_f32_16x16x32_bf16 v[56:59], v[224:227], v[208:211], v[56:59]
	v_mfma_f32_16x16x32_bf16 v[52:55], v[228:231], v[208:211], v[52:55]
	v_mfma_f32_16x16x32_bf16 v[48:51], v[232:235], v[208:211], v[48:51]
	v_mfma_f32_16x16x32_bf16 v[44:47], v[236:239], v[208:211], v[44:47]
	v_mfma_f32_16x16x32_bf16 v[40:43], v[224:227], v[212:215], v[40:43]
	v_mfma_f32_16x16x32_bf16 v[36:39], v[228:231], v[212:215], v[36:39]
	v_mfma_f32_16x16x32_bf16 v[32:35], v[232:235], v[212:215], v[32:35]
	v_mfma_f32_16x16x32_bf16 v[28:31], v[236:239], v[212:215], v[28:31]
	v_mfma_f32_16x16x32_bf16 v[24:27], v[224:227], v[216:219], v[24:27]
	v_mfma_f32_16x16x32_bf16 v[20:23], v[228:231], v[216:219], v[20:23]
	v_mfma_f32_16x16x32_bf16 v[16:19], v[232:235], v[216:219], v[16:19]
	v_mfma_f32_16x16x32_bf16 v[12:15], v[236:239], v[216:219], v[12:15]
	v_mfma_f32_16x16x32_bf16 v[8:11], v[224:227], v[220:223], v[8:11]
	v_mfma_f32_16x16x32_bf16 v[4:7], v[228:231], v[220:223], v[4:7]
	v_mfma_f32_16x16x32_bf16 v[0:3], v[232:235], v[220:223], v[0:3]
	v_mfma_f32_16x16x32_bf16 v[60:63], v[236:239], v[220:223], v[60:63]
	s_waitcnt lgkmcnt(0)
	v_mfma_f32_16x16x32_bf16 v[92:95], v[120:123], v[96:99], v[92:95]
	v_mfma_f32_16x16x32_bf16 v[88:91], v[124:127], v[96:99], v[88:91]
	ds_read_b128 v[224:227], v249 offset:0
	v_mfma_f32_16x16x32_bf16 v[84:87], v[128:131], v[96:99], v[84:87]
	v_mfma_f32_16x16x32_bf16 v[80:83], v[132:135], v[96:99], v[80:83]
	ds_read_b128 v[228:231], v249 offset:2048
	v_mfma_f32_16x16x32_bf16 v[76:79], v[120:123], v[100:103], v[76:79]
	v_mfma_f32_16x16x32_bf16 v[72:75], v[124:127], v[100:103], v[72:75]
	ds_read_b128 v[232:235], v249 offset:4096
	v_mfma_f32_16x16x32_bf16 v[68:71], v[128:131], v[100:103], v[68:71]
	v_mfma_f32_16x16x32_bf16 v[64:67], v[132:135], v[100:103], v[64:67]
	ds_read_b128 v[236:239], v249 offset:6144
	v_mfma_f32_16x16x32_bf16 v[56:59], v[120:123], v[104:107], v[56:59]
	v_mfma_f32_16x16x32_bf16 v[52:55], v[124:127], v[104:107], v[52:55]
	ds_read_b128 v[200:203], v247 offset:0
	v_mfma_f32_16x16x32_bf16 v[48:51], v[128:131], v[104:107], v[48:51]
	v_mfma_f32_16x16x32_bf16 v[44:47], v[132:135], v[104:107], v[44:47]
	ds_read_b128 v[204:207], v247 offset:2048
	v_mfma_f32_16x16x32_bf16 v[40:43], v[120:123], v[108:111], v[40:43]
	v_mfma_f32_16x16x32_bf16 v[36:39], v[124:127], v[108:111], v[36:39]
	ds_read_b128 v[208:211], v247 offset:4096
	v_mfma_f32_16x16x32_bf16 v[32:35], v[128:131], v[108:111], v[32:35]
	v_mfma_f32_16x16x32_bf16 v[28:31], v[132:135], v[108:111], v[28:31]
	ds_read_b128 v[212:215], v247 offset:6144
	v_mfma_f32_16x16x32_bf16 v[24:27], v[120:123], v[112:115], v[24:27]
	v_mfma_f32_16x16x32_bf16 v[20:23], v[124:127], v[112:115], v[20:23]
	ds_read_b128 v[216:219], v247 offset:8192
	v_mfma_f32_16x16x32_bf16 v[16:19], v[128:131], v[112:115], v[16:19]
	v_mfma_f32_16x16x32_bf16 v[12:15], v[132:135], v[112:115], v[12:15]
	ds_read_b128 v[220:223], v247 offset:10240
	v_mfma_f32_16x16x32_bf16 v[8:11], v[120:123], v[116:119], v[8:11]
	v_mfma_f32_16x16x32_bf16 v[4:7], v[124:127], v[116:119], v[4:7]
	v_mfma_f32_16x16x32_bf16 v[0:3], v[128:131], v[116:119], v[0:3]
	v_mfma_f32_16x16x32_bf16 v[60:63], v[132:135], v[116:119], v[60:63]
	s_sub_u32 s9, s9, 1
	s_cmp_lg_u32 s9, 0
	s_cbranch_scc1 .Lg6p7_loop
	s_waitcnt vmcnt(0) lgkmcnt(0)
	s_barrier
	ds_read_b128 v[120:123], v248 offset:40960
	ds_read_b128 v[124:127], v248 offset:43008
	ds_read_b128 v[128:131], v248 offset:45056
	ds_read_b128 v[132:135], v248 offset:47104
	ds_read_b128 v[96:99], v246 offset:40960
	ds_read_b128 v[100:103], v246 offset:43008
	ds_read_b128 v[104:107], v246 offset:45056
	ds_read_b128 v[108:111], v246 offset:47104
	ds_read_b128 v[112:115], v246 offset:49152
	ds_read_b128 v[116:119], v246 offset:51200
	v_mfma_f32_16x16x32_bf16 v[92:95], v[224:227], v[200:203], v[92:95]
	v_mfma_f32_16x16x32_bf16 v[88:91], v[228:231], v[200:203], v[88:91]
	v_mfma_f32_16x16x32_bf16 v[84:87], v[232:235], v[200:203], v[84:87]
	v_mfma_f32_16x16x32_bf16 v[80:83], v[236:239], v[200:203], v[80:83]
	v_mfma_f32_16x16x32_bf16 v[76:79], v[224:227], v[204:207], v[76:79]
	v_mfma_f32_16x16x32_bf16 v[72:75], v[228:231], v[204:207], v[72:75]
	v_mfma_f32_16x16x32_bf16 v[68:71], v[232:235], v[204:207], v[68:71]
	v_mfma_f32_16x16x32_bf16 v[64:67], v[236:239], v[204:207], v[64:67]
	v_mfma_f32_16x16x32_bf16 v[56:59], v[224:227], v[208:211], v[56:59]
	v_mfma_f32_16x16x32_bf16 v[52:55], v[228:231], v[208:211], v[52:55]
	v_mfma_f32_16x16x32_bf16 v[48:51], v[232:235], v[208:211], v[48:51]
	v_mfma_f32_16x16x32_bf16 v[44:47], v[236:239], v[208:211], v[44:47]
	v_mfma_f32_16x16x32_bf16 v[40:43], v[224:227], v[212:215], v[40:43]
	v_mfma_f32_16x16x32_bf16 v[36:39], v[228:231], v[212:215], v[36:39]
	v_mfma_f32_16x16x32_bf16 v[32:35], v[232:235], v[212:215], v[32:35]
	v_mfma_f32_16x16x32_bf16 v[28:31], v[236:239], v[212:215], v[28:31]
	v_mfma_f32_16x16x32_bf16 v[24:27], v[224:227], v[216:219], v[24:27]
	v_mfma_f32_16x16x32_bf16 v[20:23], v[228:231], v[216:219], v[20:23]
	v_mfma_f32_16x16x32_bf16 v[16:19], v[232:235], v[216:219], v[16:19]
	v_mfma_f32_16x16x32_bf16 v[12:15], v[236:239], v[216:219], v[12:15]
	v_mfma_f32_16x16x32_bf16 v[8:11], v[224:227], v[220:223], v[8:11]
	v_mfma_f32_16x16x32_bf16 v[4:7], v[228:231], v[220:223], v[4:7]
	v_mfma_f32_16x16x32_bf16 v[0:3], v[232:235], v[220:223], v[0:3]
	v_mfma_f32_16x16x32_bf16 v[60:63], v[236:239], v[220:223], v[60:63]
	s_waitcnt lgkmcnt(0)
	v_mfma_f32_16x16x32_bf16 v[92:95], v[120:123], v[96:99], v[92:95]
	v_mfma_f32_16x16x32_bf16 v[88:91], v[124:127], v[96:99], v[88:91]
	ds_read_b128 v[224:227], v249 offset:40960
	v_mfma_f32_16x16x32_bf16 v[84:87], v[128:131], v[96:99], v[84:87]
	v_mfma_f32_16x16x32_bf16 v[80:83], v[132:135], v[96:99], v[80:83]
	ds_read_b128 v[228:231], v249 offset:43008
	v_mfma_f32_16x16x32_bf16 v[76:79], v[120:123], v[100:103], v[76:79]
	v_mfma_f32_16x16x32_bf16 v[72:75], v[124:127], v[100:103], v[72:75]
	ds_read_b128 v[232:235], v249 offset:45056
	v_mfma_f32_16x16x32_bf16 v[68:71], v[128:131], v[100:103], v[68:71]
	v_mfma_f32_16x16x32_bf16 v[64:67], v[132:135], v[100:103], v[64:67]
	ds_read_b128 v[236:239], v249 offset:47104
	v_mfma_f32_16x16x32_bf16 v[56:59], v[120:123], v[104:107], v[56:59]
	v_mfma_f32_16x16x32_bf16 v[52:55], v[124:127], v[104:107], v[52:55]
	ds_read_b128 v[200:203], v247 offset:40960
	v_mfma_f32_16x16x32_bf16 v[48:51], v[128:131], v[104:107], v[48:51]
	v_mfma_f32_16x16x32_bf16 v[44:47], v[132:135], v[104:107], v[44:47]
	ds_read_b128 v[204:207], v247 offset:43008
	v_mfma_f32_16x16x32_bf16 v[40:43], v[120:123], v[108:111], v[40:43]
	v_mfma_f32_16x16x32_bf16 v[36:39], v[124:127], v[108:111], v[36:39]
	ds_read_b128 v[208:211], v247 offset:45056
	v_mfma_f32_16x16x32_bf16 v[32:35], v[128:131], v[108:111], v[32:35]
	v_mfma_f32_16x16x32_bf16 v[28:31], v[132:135], v[108:111], v[28:31]
	ds_read_b128 v[212:215], v247 offset:47104
	v_mfma_f32_16x16x32_bf16 v[24:27], v[120:123], v[112:115], v[24:27]
	v_mfma_f32_16x16x32_bf16 v[20:23], v[124:127], v[112:115], v[20:23]
	ds_read_b128 v[216:219], v247 offset:49152
	v_mfma_f32_16x16x32_bf16 v[16:19], v[128:131], v[112:115], v[16:19]
	v_mfma_f32_16x16x32_bf16 v[12:15], v[132:135], v[112:115], v[12:15]
	ds_read_b128 v[220:223], v247 offset:51200
	v_mfma_f32_16x16x32_bf16 v[8:11], v[120:123], v[116:119], v[8:11]
	v_mfma_f32_16x16x32_bf16 v[4:7], v[124:127], v[116:119], v[4:7]
	v_mfma_f32_16x16x32_bf16 v[0:3], v[128:131], v[116:119], v[0:3]
	v_mfma_f32_16x16x32_bf16 v[60:63], v[132:135], v[116:119], v[60:63]
	s_waitcnt lgkmcnt(0)
	v_mfma_f32_16x16x32_bf16 v[92:95], v[224:227], v[200:203], v[92:95]
	v_mfma_f32_16x16x32_bf16 v[88:91], v[228:231], v[200:203], v[88:91]
	v_mfma_f32_16x16x32_bf16 v[84:87], v[232:235], v[200:203], v[84:87]
	v_mfma_f32_16x16x32_bf16 v[80:83], v[236:239], v[200:203], v[80:83]
	v_mfma_f32_16x16x32_bf16 v[76:79], v[224:227], v[204:207], v[76:79]
	v_mfma_f32_16x16x32_bf16 v[72:75], v[228:231], v[204:207], v[72:75]
	v_mfma_f32_16x16x32_bf16 v[68:71], v[232:235], v[204:207], v[68:71]
	v_mfma_f32_16x16x32_bf16 v[64:67], v[236:239], v[204:207], v[64:67]
	v_mfma_f32_16x16x32_bf16 v[56:59], v[224:227], v[208:211], v[56:59]
	v_mfma_f32_16x16x32_bf16 v[52:55], v[228:231], v[208:211], v[52:55]
	v_mfma_f32_16x16x32_bf16 v[48:51], v[232:235], v[208:211], v[48:51]
	v_mfma_f32_16x16x32_bf16 v[44:47], v[236:239], v[208:211], v[44:47]
	v_mfma_f32_16x16x32_bf16 v[40:43], v[224:227], v[212:215], v[40:43]
	v_mfma_f32_16x16x32_bf16 v[36:39], v[228:231], v[212:215], v[36:39]
	v_mfma_f32_16x16x32_bf16 v[32:35], v[232:235], v[212:215], v[32:35]
	v_mfma_f32_16x16x32_bf16 v[28:31], v[236:239], v[212:215], v[28:31]
	v_mfma_f32_16x16x32_bf16 v[24:27], v[224:227], v[216:219], v[24:27]
	v_mfma_f32_16x16x32_bf16 v[20:23], v[228:231], v[216:219], v[20:23]
	v_mfma_f32_16x16x32_bf16 v[16:19], v[232:235], v[216:219], v[16:19]
	v_mfma_f32_16x16x32_bf16 v[12:15], v[236:239], v[216:219], v[12:15]
	v_mfma_f32_16x16x32_bf16 v[8:11], v[224:227], v[220:223], v[8:11]
	v_mfma_f32_16x16x32_bf16 v[4:7], v[228:231], v[220:223], v[4:7]
	v_mfma_f32_16x16x32_bf16 v[0:3], v[232:235], v[220:223], v[0:3]
	v_mfma_f32_16x16x32_bf16 v[60:63], v[236:239], v[220:223], v[60:63]
	s_nop 7
	s_nop 7
	s_barrier
	ds_write_b64 v252, v[250:251]
	s_mov_b32 s34, 0
	v_cvt_pk_bf16_f32 v8, v8, v9
	v_cvt_pk_bf16_f32 v9, v10, v11
	v_cvt_pk_bf16_f32 v4, v4, v5
	v_cvt_pk_bf16_f32 v5, v6, v7
	v_add_u32_e32 v6, 0x2800, v160
	ds_write2_b64 v6, v[8:9], v[4:5] offset0:160 offset1:164
	v_cvt_pk_bf16_f32 v4, v0, v1
	v_cvt_pk_bf16_f32 v5, v2, v3
	v_cvt_pk_bf16_f32 v92, v92, v93
	v_cvt_pk_bf16_f32 v93, v94, v95
	v_cvt_pk_bf16_f32 v88, v88, v89
	v_cvt_pk_bf16_f32 v89, v90, v91
	ds_write2_b64 v160, v[92:93], v[88:89] offset1:4
	v_cvt_pk_bf16_f32 v84, v84, v85
	v_cvt_pk_bf16_f32 v85, v86, v87
	v_cvt_pk_bf16_f32 v80, v80, v81
	v_cvt_pk_bf16_f32 v81, v82, v83
	v_cvt_pk_bf16_f32 v76, v76, v77
	v_cvt_pk_bf16_f32 v77, v78, v79
	v_cvt_pk_bf16_f32 v72, v72, v73
	v_cvt_pk_bf16_f32 v73, v74, v75
	v_add_u32_e32 v74, 0x800, v160
	v_cvt_pk_bf16_f32 v68, v68, v69
	v_cvt_pk_bf16_f32 v69, v70, v71
	ds_write2_b64 v160, v[84:85], v[80:81] offset0:8 offset1:12
	v_cvt_pk_bf16_f32 v64, v64, v65
	v_cvt_pk_bf16_f32 v65, v66, v67
	ds_write2_b64 v74, v[76:77], v[72:73] offset0:32 offset1:36
	v_cvt_pk_bf16_f32 v56, v56, v57
	v_cvt_pk_bf16_f32 v57, v58, v59
	ds_write2_b64 v74, v[68:69], v[64:65] offset0:40 offset1:44
	v_cvt_pk_bf16_f32 v52, v52, v53
	v_cvt_pk_bf16_f32 v53, v54, v55
	v_add_u32_e32 v54, 0x1000, v160
	v_cvt_pk_bf16_f32 v48, v48, v49
	v_cvt_pk_bf16_f32 v49, v50, v51
	ds_write2_b64 v54, v[56:57], v[52:53] offset0:64 offset1:68
	v_cvt_pk_bf16_f32 v44, v44, v45
	v_cvt_pk_bf16_f32 v45, v46, v47
	ds_write2_b64 v54, v[48:49], v[44:45] offset0:72 offset1:76
	v_cvt_pk_bf16_f32 v40, v40, v41
	v_cvt_pk_bf16_f32 v41, v42, v43
	v_cvt_pk_bf16_f32 v36, v36, v37
	v_cvt_pk_bf16_f32 v37, v38, v39
	v_add_u32_e32 v38, 0x1800, v160
	v_cvt_pk_bf16_f32 v32, v32, v33
	v_cvt_pk_bf16_f32 v33, v34, v35
	v_cvt_pk_bf16_f32 v28, v28, v29
	v_cvt_pk_bf16_f32 v29, v30, v31
	v_cvt_pk_bf16_f32 v24, v24, v25
	v_cvt_pk_bf16_f32 v25, v26, v27
	ds_write2_b64 v38, v[40:41], v[36:37] offset0:96 offset1:100
	v_cvt_pk_bf16_f32 v20, v20, v21
	v_cvt_pk_bf16_f32 v21, v22, v23
	v_add_u32_e32 v22, 0x2000, v160
	v_cvt_pk_bf16_f32 v16, v16, v17
	v_cvt_pk_bf16_f32 v17, v18, v19
	v_mov_b32_e32 v0, v60
	v_mov_b32_e32 v1, v61
	v_mov_b32_e32 v2, v62
	v_mov_b32_e32 v3, v63
	ds_write2_b64 v38, v[32:33], v[28:29] offset0:104 offset1:108
	s_nop 2
	v_cvt_pk_bf16_f32 v12, v12, v13
	v_cvt_pk_bf16_f32 v13, v14, v15
	ds_write2_b64 v22, v[24:25], v[20:21] offset0:128 offset1:132
	ds_write2_b64 v22, v[16:17], v[12:13] offset0:136 offset1:140
	v_cvt_pk_bf16_f32 v0, v0, v1
	v_cvt_pk_bf16_f32 v1, v2, v3
	ds_write2_b64 v6, v[4:5], v[0:1] offset0:168 offset1:172
	v_or_b32_e32 v0, s6, v148
	s_waitcnt lgkmcnt(0)
	v_ashrrev_i32_e32 v1, 31, v0
	v_add_u32_e32 v12, s4, v146
	v_lshl_add_u64 v[8:9], v[0:1], 1, s[2:3]
	ds_read_b128 v[0:3], v161
	v_or_b32_e32 v4, v12, v147
	v_mad_i64_i32 v[10:11], s[4:5], v4, s31, v[8:9]
	ds_read_b128 v[4:7], v161 offset:1152
	s_waitcnt lgkmcnt(1)
	global_store_dwordx4 v[10:11], v[0:3], off
	s_nop 1
	v_or_b32_e32 v0, v12, v149
	v_mad_i64_i32 v[0:1], s[4:5], v0, s31, v[8:9]
	s_waitcnt lgkmcnt(0)
	global_store_dwordx4 v[0:1], v[4:7], off
	ds_read_b128 v[0:3], v161 offset:2304
	s_nop 0
	v_or_b32_e32 v4, v12, v150
	v_mad_i64_i32 v[10:11], s[4:5], v4, s31, v[8:9]
	ds_read_b128 v[4:7], v161 offset:3456
	s_waitcnt lgkmcnt(1)
	global_store_dwordx4 v[10:11], v[0:3], off
	s_nop 1
	v_or_b32_e32 v0, v12, v151
	v_mad_i64_i32 v[0:1], s[4:5], v0, s31, v[8:9]
	s_waitcnt lgkmcnt(0)
	global_store_dwordx4 v[0:1], v[4:7], off
	ds_read_b128 v[0:3], v161 offset:4608
	s_nop 0
	v_add_u32_e32 v4, v12, v152
	v_mad_i64_i32 v[10:11], s[4:5], v4, s31, v[8:9]
	ds_read_b128 v[4:7], v161 offset:5760
	s_waitcnt lgkmcnt(1)
	global_store_dwordx4 v[10:11], v[0:3], off
	s_nop 1
	v_add_u32_e32 v0, v12, v153
	v_mad_i64_i32 v[0:1], s[4:5], v0, s31, v[8:9]
	s_waitcnt lgkmcnt(0)
	global_store_dwordx4 v[0:1], v[4:7], off
	ds_read_b128 v[0:3], v161 offset:6912
	s_nop 0
	v_add_u32_e32 v4, v12, v154
	v_mad_i64_i32 v[10:11], s[4:5], v4, s31, v[8:9]
	ds_read_b128 v[4:7], v161 offset:8064
	s_waitcnt lgkmcnt(1)
	global_store_dwordx4 v[10:11], v[0:3], off
	s_nop 1
	v_add_u32_e32 v0, v12, v155
	v_mad_i64_i32 v[0:1], s[4:5], v0, s31, v[8:9]
	s_waitcnt lgkmcnt(0)
	global_store_dwordx4 v[0:1], v[4:7], off
	ds_read_b128 v[0:3], v161 offset:9216
	s_nop 0
	v_add_u32_e32 v4, v12, v156
	v_mad_i64_i32 v[10:11], s[4:5], v4, s31, v[8:9]
	ds_read_b128 v[4:7], v161 offset:10368
	s_waitcnt lgkmcnt(1)
	global_store_dwordx4 v[10:11], v[0:3], off
	s_nop 1
	v_add_u32_e32 v0, v12, v157
	v_mad_i64_i32 v[0:1], s[4:5], v0, s31, v[8:9]
	s_waitcnt lgkmcnt(0)
	global_store_dwordx4 v[0:1], v[4:7], off
	ds_read_b128 v[0:3], v161 offset:11520
	s_nop 0
	v_add_u32_e32 v4, v12, v158
	v_mad_i64_i32 v[10:11], s[4:5], v4, s31, v[8:9]
	ds_read_b128 v[4:7], v161 offset:12672
	s_waitcnt lgkmcnt(1)
	global_store_dwordx4 v[10:11], v[0:3], off
	s_nop 1
	v_add_u32_e32 v0, v12, v159
	v_mad_i64_i32 v[0:1], s[4:5], v0, s31, v[8:9]
	s_waitcnt lgkmcnt(0)
	global_store_dwordx4 v[0:1], v[4:7], off

.Lg6p9_loop:
	s_waitcnt vmcnt(0) lgkmcnt(0)
	s_barrier
	s_add_u32 m0, s6, 0
	ds_read_b128 v[120:123], v248 offset:40960
	global_load_lds_dwordx4 v240, s[98:99]
	s_add_u32 m0, s6, 4096
	ds_read_b128 v[124:127], v248 offset:43008
	global_load_lds_dwordx4 v241, s[98:99]
	s_add_u32 m0, s6, 8192
	ds_read_b128 v[128:131], v248 offset:45056
	global_load_lds_dwordx4 v242, s[98:99]
	s_add_u32 m0, s6, 12288
	ds_read_b128 v[132:135], v248 offset:47104
	global_load_lds_dwordx4 v243, s[98:99]
	s_add_u32 m0, s6, 16384
	ds_read_b128 v[96:99], v246 offset:40960
	global_load_lds_dwordx4 v244, s[98:99]
	s_add_u32 m0, s6, 20480
	ds_read_b128 v[100:103], v246 offset:43008
	global_load_lds_dwordx4 v245, s[98:99]
	s_add_u32 m0, s6, 24576
	ds_read_b128 v[104:107], v246 offset:45056
	global_load_lds_dwordx4 v240, s[100:101]
	s_add_u32 m0, s6, 28672
	ds_read_b128 v[108:111], v246 offset:47104
	global_load_lds_dwordx4 v241, s[100:101]
	s_add_u32 m0, s6, 32768
	ds_read_b128 v[112:115], v246 offset:49152
	global_load_lds_dwordx4 v242, s[100:101]
	s_add_u32 m0, s6, 36864
	ds_read_b128 v[116:119], v246 offset:51200
	global_load_lds_dwordx4 v243, s[100:101]
	s_add_u32 s98, s98, 0x80
	s_addc_u32 s99, s99, 0
	s_add_u32 s100, s100, 0x80
	s_addc_u32 s101, s101, 0
	v_mfma_f32_16x16x32_bf16 v[92:95], v[224:227], v[200:203], v[92:95]
	v_mfma_f32_16x16x32_bf16 v[88:91], v[228:231], v[200:203], v[88:91]
	v_mfma_f32_16x16x32_bf16 v[84:87], v[232:235], v[200:203], v[84:87]
	v_mfma_f32_16x16x32_bf16 v[80:83], v[236:239], v[200:203], v[80:83]
	v_mfma_f32_16x16x32_bf16 v[76:79], v[224:227], v[204:207], v[76:79]
	v_mfma_f32_16x16x32_bf16 v[72:75], v[228:231], v[204:207], v[72:75]
	v_mfma_f32_16x16x32_bf16 v[68:71], v[232:235], v[204:207], v[68:71]
	v_mfma_f32_16x16x32_bf16 v[60:63], v[236:239], v[204:207], v[60:63]
	v_mfma_f32_16x16x32_bf16 v[56:59], v[224:227], v[208:211], v[56:59]
	v_mfma_f32_16x16x32_bf16 v[52:55], v[228:231], v[208:211], v[52:55]
	v_mfma_f32_16x16x32_bf16 v[48:51], v[232:235], v[208:211], v[48:51]
	v_mfma_f32_16x16x32_bf16 v[44:47], v[236:239], v[208:211], v[44:47]
	v_mfma_f32_16x16x32_bf16 v[40:43], v[224:227], v[212:215], v[40:43]
	v_mfma_f32_16x16x32_bf16 v[36:39], v[228:231], v[212:215], v[36:39]
	v_mfma_f32_16x16x32_bf16 v[32:35], v[232:235], v[212:215], v[32:35]
	v_mfma_f32_16x16x32_bf16 v[28:31], v[236:239], v[212:215], v[28:31]
	v_mfma_f32_16x16x32_bf16 v[24:27], v[224:227], v[216:219], v[24:27]
	v_mfma_f32_16x16x32_bf16 v[20:23], v[228:231], v[216:219], v[20:23]
	v_mfma_f32_16x16x32_bf16 v[16:19], v[232:235], v[216:219], v[16:19]
	v_mfma_f32_16x16x32_bf16 v[12:15], v[236:239], v[216:219], v[12:15]
	v_mfma_f32_16x16x32_bf16 v[8:11], v[224:227], v[220:223], v[8:11]
	v_mfma_f32_16x16x32_bf16 v[4:7], v[228:231], v[220:223], v[4:7]
	v_mfma_f32_16x16x32_bf16 v[0:3], v[232:235], v[220:223], v[0:3]
	v_mfma_f32_16x16x32_bf16 v[64:67], v[236:239], v[220:223], v[64:67]
	s_waitcnt lgkmcnt(0)
	v_mfma_f32_16x16x32_bf16 v[92:95], v[120:123], v[96:99], v[92:95]
	v_mfma_f32_16x16x32_bf16 v[88:91], v[124:127], v[96:99], v[88:91]
	ds_read_b128 v[224:227], v249 offset:40960
	v_mfma_f32_16x16x32_bf16 v[84:87], v[128:131], v[96:99], v[84:87]
	v_mfma_f32_16x16x32_bf16 v[80:83], v[132:135], v[96:99], v[80:83]
	ds_read_b128 v[228:231], v249 offset:43008
	v_mfma_f32_16x16x32_bf16 v[76:79], v[120:123], v[100:103], v[76:79]
	v_mfma_f32_16x16x32_bf16 v[72:75], v[124:127], v[100:103], v[72:75]
	ds_read_b128 v[232:235], v249 offset:45056
	v_mfma_f32_16x16x32_bf16 v[68:71], v[128:131], v[100:103], v[68:71]
	v_mfma_f32_16x16x32_bf16 v[60:63], v[132:135], v[100:103], v[60:63]
	ds_read_b128 v[236:239], v249 offset:47104
	v_mfma_f32_16x16x32_bf16 v[56:59], v[120:123], v[104:107], v[56:59]
	v_mfma_f32_16x16x32_bf16 v[52:55], v[124:127], v[104:107], v[52:55]
	ds_read_b128 v[200:203], v247 offset:40960
	v_mfma_f32_16x16x32_bf16 v[48:51], v[128:131], v[104:107], v[48:51]
	v_mfma_f32_16x16x32_bf16 v[44:47], v[132:135], v[104:107], v[44:47]
	ds_read_b128 v[204:207], v247 offset:43008
	v_mfma_f32_16x16x32_bf16 v[40:43], v[120:123], v[108:111], v[40:43]
	v_mfma_f32_16x16x32_bf16 v[36:39], v[124:127], v[108:111], v[36:39]
	ds_read_b128 v[208:211], v247 offset:45056
	v_mfma_f32_16x16x32_bf16 v[32:35], v[128:131], v[108:111], v[32:35]
	v_mfma_f32_16x16x32_bf16 v[28:31], v[132:135], v[108:111], v[28:31]
	ds_read_b128 v[212:215], v247 offset:47104
	v_mfma_f32_16x16x32_bf16 v[24:27], v[120:123], v[112:115], v[24:27]
	v_mfma_f32_16x16x32_bf16 v[20:23], v[124:127], v[112:115], v[20:23]
	ds_read_b128 v[216:219], v247 offset:49152
	v_mfma_f32_16x16x32_bf16 v[16:19], v[128:131], v[112:115], v[16:19]
	v_mfma_f32_16x16x32_bf16 v[12:15], v[132:135], v[112:115], v[12:15]
	ds_read_b128 v[220:223], v247 offset:51200
	v_mfma_f32_16x16x32_bf16 v[8:11], v[120:123], v[116:119], v[8:11]
	v_mfma_f32_16x16x32_bf16 v[4:7], v[124:127], v[116:119], v[4:7]
	v_mfma_f32_16x16x32_bf16 v[0:3], v[128:131], v[116:119], v[0:3]
	v_mfma_f32_16x16x32_bf16 v[64:67], v[132:135], v[116:119], v[64:67]
	s_waitcnt vmcnt(0) lgkmcnt(0)
	s_barrier
	s_add_u32 m0, s6, 40960
	ds_read_b128 v[120:123], v248 offset:0
	global_load_lds_dwordx4 v240, s[98:99]
	s_add_u32 m0, s6, 45056
	ds_read_b128 v[124:127], v248 offset:2048
	global_load_lds_dwordx4 v241, s[98:99]
	s_add_u32 m0, s6, 49152
	ds_read_b128 v[128:131], v248 offset:4096
	global_load_lds_dwordx4 v242, s[98:99]
	s_add_u32 m0, s6, 53248
	ds_read_b128 v[132:135], v248 offset:6144
	global_load_lds_dwordx4 v243, s[98:99]
	s_add_u32 m0, s6, 57344
	ds_read_b128 v[96:99], v246 offset:0
	global_load_lds_dwordx4 v244, s[98:99]
	s_add_u32 m0, s6, 61440
	ds_read_b128 v[100:103], v246 offset:2048
	global_load_lds_dwordx4 v245, s[98:99]
	s_add_u32 m0, s6, 65536
	ds_read_b128 v[104:107], v246 offset:4096
	global_load_lds_dwordx4 v240, s[100:101]
	s_add_u32 m0, s6, 69632
	ds_read_b128 v[108:111], v246 offset:6144
	global_load_lds_dwordx4 v241, s[100:101]
	s_add_u32 m0, s6, 73728
	ds_read_b128 v[112:115], v246 offset:8192
	global_load_lds_dwordx4 v242, s[100:101]
	s_add_u32 m0, s6, 77824
	ds_read_b128 v[116:119], v246 offset:10240
	global_load_lds_dwordx4 v243, s[100:101]
	s_add_u32 s98, s98, 0x80
	s_addc_u32 s99, s99, 0
	s_add_u32 s100, s100, 0x80
	s_addc_u32 s101, s101, 0
	v_mfma_f32_16x16x32_bf16 v[92:95], v[224:227], v[200:203], v[92:95]
	v_mfma_f32_16x16x32_bf16 v[88:91], v[228:231], v[200:203], v[88:91]
	v_mfma_f32_16x16x32_bf16 v[84:87], v[232:235], v[200:203], v[84:87]
	v_mfma_f32_16x16x32_bf16 v[80:83], v[236:239], v[200:203], v[80:83]
	v_mfma_f32_16x16x32_bf16 v[76:79], v[224:227], v[204:207], v[76:79]
	v_mfma_f32_16x16x32_bf16 v[72:75], v[228:231], v[204:207], v[72:75]
	v_mfma_f32_16x16x32_bf16 v[68:71], v[232:235], v[204:207], v[68:71]
	v_mfma_f32_16x16x32_bf16 v[60:63], v[236:239], v[204:207], v[60:63]
	v_mfma_f32_16x16x32_bf16 v[56:59], v[224:227], v[208:211], v[56:59]
	v_mfma_f32_16x16x32_bf16 v[52:55], v[228:231], v[208:211], v[52:55]
	v_mfma_f32_16x16x32_bf16 v[48:51], v[232:235], v[208:211], v[48:51]
	v_mfma_f32_16x16x32_bf16 v[44:47], v[236:239], v[208:211], v[44:47]
	v_mfma_f32_16x16x32_bf16 v[40:43], v[224:227], v[212:215], v[40:43]
	v_mfma_f32_16x16x32_bf16 v[36:39], v[228:231], v[212:215], v[36:39]
	v_mfma_f32_16x16x32_bf16 v[32:35], v[232:235], v[212:215], v[32:35]
	v_mfma_f32_16x16x32_bf16 v[28:31], v[236:239], v[212:215], v[28:31]
	v_mfma_f32_16x16x32_bf16 v[24:27], v[224:227], v[216:219], v[24:27]
	v_mfma_f32_16x16x32_bf16 v[20:23], v[228:231], v[216:219], v[20:23]
	v_mfma_f32_16x16x32_bf16 v[16:19], v[232:235], v[216:219], v[16:19]
	v_mfma_f32_16x16x32_bf16 v[12:15], v[236:239], v[216:219], v[12:15]
	v_mfma_f32_16x16x32_bf16 v[8:11], v[224:227], v[220:223], v[8:11]
	v_mfma_f32_16x16x32_bf16 v[4:7], v[228:231], v[220:223], v[4:7]
	v_mfma_f32_16x16x32_bf16 v[0:3], v[232:235], v[220:223], v[0:3]
	v_mfma_f32_16x16x32_bf16 v[64:67], v[236:239], v[220:223], v[64:67]
	s_waitcnt lgkmcnt(0)
	v_mfma_f32_16x16x32_bf16 v[92:95], v[120:123], v[96:99], v[92:95]
	v_mfma_f32_16x16x32_bf16 v[88:91], v[124:127], v[96:99], v[88:91]
	ds_read_b128 v[224:227], v249 offset:0
	v_mfma_f32_16x16x32_bf16 v[84:87], v[128:131], v[96:99], v[84:87]
	v_mfma_f32_16x16x32_bf16 v[80:83], v[132:135], v[96:99], v[80:83]
	ds_read_b128 v[228:231], v249 offset:2048
	v_mfma_f32_16x16x32_bf16 v[76:79], v[120:123], v[100:103], v[76:79]
	v_mfma_f32_16x16x32_bf16 v[72:75], v[124:127], v[100:103], v[72:75]
	ds_read_b128 v[232:235], v249 offset:4096
	v_mfma_f32_16x16x32_bf16 v[68:71], v[128:131], v[100:103], v[68:71]
	v_mfma_f32_16x16x32_bf16 v[60:63], v[132:135], v[100:103], v[60:63]
	ds_read_b128 v[236:239], v249 offset:6144
	v_mfma_f32_16x16x32_bf16 v[56:59], v[120:123], v[104:107], v[56:59]
	v_mfma_f32_16x16x32_bf16 v[52:55], v[124:127], v[104:107], v[52:55]
	ds_read_b128 v[200:203], v247 offset:0
	v_mfma_f32_16x16x32_bf16 v[48:51], v[128:131], v[104:107], v[48:51]
	v_mfma_f32_16x16x32_bf16 v[44:47], v[132:135], v[104:107], v[44:47]
	ds_read_b128 v[204:207], v247 offset:2048
	v_mfma_f32_16x16x32_bf16 v[40:43], v[120:123], v[108:111], v[40:43]
	v_mfma_f32_16x16x32_bf16 v[36:39], v[124:127], v[108:111], v[36:39]
	ds_read_b128 v[208:211], v247 offset:4096
	v_mfma_f32_16x16x32_bf16 v[32:35], v[128:131], v[108:111], v[32:35]
	v_mfma_f32_16x16x32_bf16 v[28:31], v[132:135], v[108:111], v[28:31]
	ds_read_b128 v[212:215], v247 offset:6144
	v_mfma_f32_16x16x32_bf16 v[24:27], v[120:123], v[112:115], v[24:27]
	v_mfma_f32_16x16x32_bf16 v[20:23], v[124:127], v[112:115], v[20:23]
	ds_read_b128 v[216:219], v247 offset:8192
	v_mfma_f32_16x16x32_bf16 v[16:19], v[128:131], v[112:115], v[16:19]
	v_mfma_f32_16x16x32_bf16 v[12:15], v[132:135], v[112:115], v[12:15]
	ds_read_b128 v[220:223], v247 offset:10240
	v_mfma_f32_16x16x32_bf16 v[8:11], v[120:123], v[116:119], v[8:11]
	v_mfma_f32_16x16x32_bf16 v[4:7], v[124:127], v[116:119], v[4:7]
	v_mfma_f32_16x16x32_bf16 v[0:3], v[128:131], v[116:119], v[0:3]
	v_mfma_f32_16x16x32_bf16 v[64:67], v[132:135], v[116:119], v[64:67]
	s_sub_u32 s7, s7, 1
	s_cmp_lg_u32 s7, 0
	s_cbranch_scc1 .Lg6p9_loop
	s_waitcnt vmcnt(0) lgkmcnt(0)
	s_barrier
	ds_read_b128 v[120:123], v248 offset:40960
	ds_read_b128 v[124:127], v248 offset:43008
	ds_read_b128 v[128:131], v248 offset:45056
	ds_read_b128 v[132:135], v248 offset:47104
	ds_read_b128 v[96:99], v246 offset:40960
	ds_read_b128 v[100:103], v246 offset:43008
	ds_read_b128 v[104:107], v246 offset:45056
	ds_read_b128 v[108:111], v246 offset:47104
	ds_read_b128 v[112:115], v246 offset:49152
	ds_read_b128 v[116:119], v246 offset:51200
	v_mfma_f32_16x16x32_bf16 v[92:95], v[224:227], v[200:203], v[92:95]
	v_mfma_f32_16x16x32_bf16 v[88:91], v[228:231], v[200:203], v[88:91]
	v_mfma_f32_16x16x32_bf16 v[84:87], v[232:235], v[200:203], v[84:87]
	v_mfma_f32_16x16x32_bf16 v[80:83], v[236:239], v[200:203], v[80:83]
	v_mfma_f32_16x16x32_bf16 v[76:79], v[224:227], v[204:207], v[76:79]
	v_mfma_f32_16x16x32_bf16 v[72:75], v[228:231], v[204:207], v[72:75]
	v_mfma_f32_16x16x32_bf16 v[68:71], v[232:235], v[204:207], v[68:71]
	v_mfma_f32_16x16x32_bf16 v[60:63], v[236:239], v[204:207], v[60:63]
	v_mfma_f32_16x16x32_bf16 v[56:59], v[224:227], v[208:211], v[56:59]
	v_mfma_f32_16x16x32_bf16 v[52:55], v[228:231], v[208:211], v[52:55]
	v_mfma_f32_16x16x32_bf16 v[48:51], v[232:235], v[208:211], v[48:51]
	v_mfma_f32_16x16x32_bf16 v[44:47], v[236:239], v[208:211], v[44:47]
	v_mfma_f32_16x16x32_bf16 v[40:43], v[224:227], v[212:215], v[40:43]
	v_mfma_f32_16x16x32_bf16 v[36:39], v[228:231], v[212:215], v[36:39]
	v_mfma_f32_16x16x32_bf16 v[32:35], v[232:235], v[212:215], v[32:35]
	v_mfma_f32_16x16x32_bf16 v[28:31], v[236:239], v[212:215], v[28:31]
	v_mfma_f32_16x16x32_bf16 v[24:27], v[224:227], v[216:219], v[24:27]
	v_mfma_f32_16x16x32_bf16 v[20:23], v[228:231], v[216:219], v[20:23]
	v_mfma_f32_16x16x32_bf16 v[16:19], v[232:235], v[216:219], v[16:19]
	v_mfma_f32_16x16x32_bf16 v[12:15], v[236:239], v[216:219], v[12:15]
	v_mfma_f32_16x16x32_bf16 v[8:11], v[224:227], v[220:223], v[8:11]
	v_mfma_f32_16x16x32_bf16 v[4:7], v[228:231], v[220:223], v[4:7]
	v_mfma_f32_16x16x32_bf16 v[0:3], v[232:235], v[220:223], v[0:3]
	v_mfma_f32_16x16x32_bf16 v[64:67], v[236:239], v[220:223], v[64:67]
	s_waitcnt lgkmcnt(0)
	v_mfma_f32_16x16x32_bf16 v[92:95], v[120:123], v[96:99], v[92:95]
	v_mfma_f32_16x16x32_bf16 v[88:91], v[124:127], v[96:99], v[88:91]
	ds_read_b128 v[224:227], v249 offset:40960
	v_mfma_f32_16x16x32_bf16 v[84:87], v[128:131], v[96:99], v[84:87]
	v_mfma_f32_16x16x32_bf16 v[80:83], v[132:135], v[96:99], v[80:83]
	ds_read_b128 v[228:231], v249 offset:43008
	v_mfma_f32_16x16x32_bf16 v[76:79], v[120:123], v[100:103], v[76:79]
	v_mfma_f32_16x16x32_bf16 v[72:75], v[124:127], v[100:103], v[72:75]
	ds_read_b128 v[232:235], v249 offset:45056
	v_mfma_f32_16x16x32_bf16 v[68:71], v[128:131], v[100:103], v[68:71]
	v_mfma_f32_16x16x32_bf16 v[60:63], v[132:135], v[100:103], v[60:63]
	ds_read_b128 v[236:239], v249 offset:47104
	v_mfma_f32_16x16x32_bf16 v[56:59], v[120:123], v[104:107], v[56:59]
	v_mfma_f32_16x16x32_bf16 v[52:55], v[124:127], v[104:107], v[52:55]
	ds_read_b128 v[200:203], v247 offset:40960
	v_mfma_f32_16x16x32_bf16 v[48:51], v[128:131], v[104:107], v[48:51]
	v_mfma_f32_16x16x32_bf16 v[44:47], v[132:135], v[104:107], v[44:47]
	ds_read_b128 v[204:207], v247 offset:43008
	v_mfma_f32_16x16x32_bf16 v[40:43], v[120:123], v[108:111], v[40:43]
	v_mfma_f32_16x16x32_bf16 v[36:39], v[124:127], v[108:111], v[36:39]
	ds_read_b128 v[208:211], v247 offset:45056
	v_mfma_f32_16x16x32_bf16 v[32:35], v[128:131], v[108:111], v[32:35]
	v_mfma_f32_16x16x32_bf16 v[28:31], v[132:135], v[108:111], v[28:31]
	ds_read_b128 v[212:215], v247 offset:47104
	v_mfma_f32_16x16x32_bf16 v[24:27], v[120:123], v[112:115], v[24:27]
	v_mfma_f32_16x16x32_bf16 v[20:23], v[124:127], v[112:115], v[20:23]
	ds_read_b128 v[216:219], v247 offset:49152
	v_mfma_f32_16x16x32_bf16 v[16:19], v[128:131], v[112:115], v[16:19]
	v_mfma_f32_16x16x32_bf16 v[12:15], v[132:135], v[112:115], v[12:15]
	ds_read_b128 v[220:223], v247 offset:51200
	v_mfma_f32_16x16x32_bf16 v[8:11], v[120:123], v[116:119], v[8:11]
	v_mfma_f32_16x16x32_bf16 v[4:7], v[124:127], v[116:119], v[4:7]
	v_mfma_f32_16x16x32_bf16 v[0:3], v[128:131], v[116:119], v[0:3]
	v_mfma_f32_16x16x32_bf16 v[64:67], v[132:135], v[116:119], v[64:67]
	s_waitcnt lgkmcnt(0)
	v_mfma_f32_16x16x32_bf16 v[92:95], v[224:227], v[200:203], v[92:95]
	v_mfma_f32_16x16x32_bf16 v[88:91], v[228:231], v[200:203], v[88:91]
	v_mfma_f32_16x16x32_bf16 v[84:87], v[232:235], v[200:203], v[84:87]
	v_mfma_f32_16x16x32_bf16 v[80:83], v[236:239], v[200:203], v[80:83]
	v_mfma_f32_16x16x32_bf16 v[76:79], v[224:227], v[204:207], v[76:79]
	v_mfma_f32_16x16x32_bf16 v[72:75], v[228:231], v[204:207], v[72:75]
	v_mfma_f32_16x16x32_bf16 v[68:71], v[232:235], v[204:207], v[68:71]
	v_mfma_f32_16x16x32_bf16 v[60:63], v[236:239], v[204:207], v[60:63]
	v_mfma_f32_16x16x32_bf16 v[56:59], v[224:227], v[208:211], v[56:59]
	v_mfma_f32_16x16x32_bf16 v[52:55], v[228:231], v[208:211], v[52:55]
	v_mfma_f32_16x16x32_bf16 v[48:51], v[232:235], v[208:211], v[48:51]
	v_mfma_f32_16x16x32_bf16 v[44:47], v[236:239], v[208:211], v[44:47]
	v_mfma_f32_16x16x32_bf16 v[40:43], v[224:227], v[212:215], v[40:43]
	v_mfma_f32_16x16x32_bf16 v[36:39], v[228:231], v[212:215], v[36:39]
	v_mfma_f32_16x16x32_bf16 v[32:35], v[232:235], v[212:215], v[32:35]
	v_mfma_f32_16x16x32_bf16 v[28:31], v[236:239], v[212:215], v[28:31]
	v_mfma_f32_16x16x32_bf16 v[24:27], v[224:227], v[216:219], v[24:27]
	v_mfma_f32_16x16x32_bf16 v[20:23], v[228:231], v[216:219], v[20:23]
	v_mfma_f32_16x16x32_bf16 v[16:19], v[232:235], v[216:219], v[16:19]
	v_mfma_f32_16x16x32_bf16 v[12:15], v[236:239], v[216:219], v[12:15]
	v_mfma_f32_16x16x32_bf16 v[8:11], v[224:227], v[220:223], v[8:11]
	v_mfma_f32_16x16x32_bf16 v[4:7], v[228:231], v[220:223], v[4:7]
	v_mfma_f32_16x16x32_bf16 v[0:3], v[232:235], v[220:223], v[0:3]
	v_mfma_f32_16x16x32_bf16 v[64:67], v[236:239], v[220:223], v[64:67]
	s_nop 7
	s_nop 7
	s_barrier
	ds_write_b64 v252, v[250:251]
	s_add_i32 s11, s11, s10
	s_ashr_i32 s4, s11, 6
	s_mul_i32 s4, s4, s9
	s_add_i32 s6, s4, s8
	s_add_i32 s12, s12, s13
	s_add_i32 s14, s14, s15
	s_cmp_lt_i32 s6, 8
	v_cvt_pk_bf16_f32 v8, v8, v9
	v_cvt_pk_bf16_f32 v9, v10, v11
	v_cvt_pk_bf16_f32 v4, v4, v5
	v_cvt_pk_bf16_f32 v5, v6, v7
	v_add_u32_e32 v6, 0x2800, v164
	ds_write2_b64 v6, v[8:9], v[4:5] offset0:160 offset1:164
	v_cvt_pk_bf16_f32 v4, v0, v1
	v_cvt_pk_bf16_f32 v5, v2, v3
	v_cvt_pk_bf16_f32 v92, v92, v93
	v_cvt_pk_bf16_f32 v93, v94, v95
	v_cvt_pk_bf16_f32 v88, v88, v89
	v_cvt_pk_bf16_f32 v89, v90, v91
	ds_write2_b64 v164, v[92:93], v[88:89] offset1:4
	v_cvt_pk_bf16_f32 v84, v84, v85
	v_cvt_pk_bf16_f32 v85, v86, v87
	v_cvt_pk_bf16_f32 v80, v80, v81
	v_cvt_pk_bf16_f32 v81, v82, v83
	v_cvt_pk_bf16_f32 v76, v76, v77
	v_cvt_pk_bf16_f32 v77, v78, v79
	v_cvt_pk_bf16_f32 v72, v72, v73
	v_cvt_pk_bf16_f32 v73, v74, v75
	v_add_u32_e32 v74, 0x800, v164
	v_cvt_pk_bf16_f32 v68, v68, v69
	v_cvt_pk_bf16_f32 v69, v70, v71
	ds_write2_b64 v164, v[84:85], v[80:81] offset0:8 offset1:12
	v_cvt_pk_bf16_f32 v60, v60, v61
	v_cvt_pk_bf16_f32 v61, v62, v63
	ds_write2_b64 v74, v[76:77], v[72:73] offset0:32 offset1:36
	v_cvt_pk_bf16_f32 v56, v56, v57
	v_cvt_pk_bf16_f32 v57, v58, v59
	ds_write2_b64 v74, v[68:69], v[60:61] offset0:40 offset1:44
	v_cvt_pk_bf16_f32 v52, v52, v53
	v_cvt_pk_bf16_f32 v53, v54, v55
	v_add_u32_e32 v54, 0x1000, v164
	v_cvt_pk_bf16_f32 v48, v48, v49
	v_cvt_pk_bf16_f32 v49, v50, v51
	ds_write2_b64 v54, v[56:57], v[52:53] offset0:64 offset1:68
	v_cvt_pk_bf16_f32 v44, v44, v45
	v_cvt_pk_bf16_f32 v45, v46, v47
	ds_write2_b64 v54, v[48:49], v[44:45] offset0:72 offset1:76
	v_cvt_pk_bf16_f32 v40, v40, v41
	v_cvt_pk_bf16_f32 v41, v42, v43
	v_cvt_pk_bf16_f32 v36, v36, v37
	v_cvt_pk_bf16_f32 v37, v38, v39
	v_add_u32_e32 v38, 0x1800, v164
	v_cvt_pk_bf16_f32 v32, v32, v33
	v_cvt_pk_bf16_f32 v33, v34, v35
	v_cvt_pk_bf16_f32 v28, v28, v29
	v_cvt_pk_bf16_f32 v29, v30, v31
	v_cvt_pk_bf16_f32 v24, v24, v25
	v_cvt_pk_bf16_f32 v25, v26, v27
	ds_write2_b64 v38, v[40:41], v[36:37] offset0:96 offset1:100
	v_cvt_pk_bf16_f32 v20, v20, v21
	v_cvt_pk_bf16_f32 v21, v22, v23
	v_add_u32_e32 v22, 0x2000, v164
	v_cvt_pk_bf16_f32 v16, v16, v17
	v_cvt_pk_bf16_f32 v17, v18, v19
	v_mov_b32_e32 v0, v64
	v_mov_b32_e32 v1, v65
	v_mov_b32_e32 v2, v66
	v_mov_b32_e32 v3, v67
	ds_write2_b64 v38, v[32:33], v[28:29] offset0:104 offset1:108
	s_nop 2
	v_cvt_pk_bf16_f32 v12, v12, v13
	v_cvt_pk_bf16_f32 v13, v14, v15
	ds_write2_b64 v22, v[24:25], v[20:21] offset0:128 offset1:132
	ds_write2_b64 v22, v[16:17], v[12:13] offset0:136 offset1:140
	v_cvt_pk_bf16_f32 v0, v0, v1
	v_cvt_pk_bf16_f32 v1, v2, v3
	ds_write2_b64 v6, v[4:5], v[0:1] offset0:168 offset1:172
	s_waitcnt lgkmcnt(0)
	v_or_b32_e32 v0, s31, v150
	v_add_u32_e32 v12, s30, v148
	v_lshlrev_b32_e32 v136, 1, v0
	ds_read_b128 v[0:3], v165
	v_or_b32_e32 v4, v12, v149
	v_ashrrev_i32_e32 v5, 31, v4
	v_lshl_add_u64 v[8:9], s[2:3], 0, v[136:137]
	v_lshlrev_b64 v[4:5], 11, v[4:5]
	v_lshl_add_u64 v[10:11], v[8:9], 0, v[4:5]
	ds_read_b128 v[4:7], v165 offset:1152
	s_waitcnt lgkmcnt(1)
	global_store_dwordx4 v[10:11], v[0:3], off
	s_nop 1
	v_or_b32_e32 v0, v12, v151
	v_ashrrev_i32_e32 v1, 31, v0
	v_lshlrev_b64 v[0:1], 11, v[0:1]
	v_lshl_add_u64 v[0:1], v[8:9], 0, v[0:1]
	s_waitcnt lgkmcnt(0)
	global_store_dwordx4 v[0:1], v[4:7], off
	ds_read_b128 v[0:3], v165 offset:2304
	s_nop 0
	v_or_b32_e32 v4, v12, v152
	v_ashrrev_i32_e32 v5, 31, v4
	v_lshlrev_b64 v[4:5], 11, v[4:5]
	v_lshl_add_u64 v[10:11], v[8:9], 0, v[4:5]
	ds_read_b128 v[4:7], v165 offset:3456
	s_waitcnt lgkmcnt(1)
	global_store_dwordx4 v[10:11], v[0:3], off
	s_nop 1
	v_or_b32_e32 v0, v12, v153
	v_ashrrev_i32_e32 v1, 31, v0
	v_lshlrev_b64 v[0:1], 11, v[0:1]
	v_lshl_add_u64 v[0:1], v[8:9], 0, v[0:1]
	s_waitcnt lgkmcnt(0)
	global_store_dwordx4 v[0:1], v[4:7], off
	ds_read_b128 v[0:3], v165 offset:4608
	s_nop 0
	v_add_u32_e32 v4, v12, v154
	v_ashrrev_i32_e32 v5, 31, v4
	v_lshlrev_b64 v[4:5], 11, v[4:5]
	v_lshl_add_u64 v[10:11], v[8:9], 0, v[4:5]
	ds_read_b128 v[4:7], v165 offset:5760
	s_waitcnt lgkmcnt(1)
	global_store_dwordx4 v[10:11], v[0:3], off
	s_nop 1
	v_add_u32_e32 v0, v12, v155
	v_ashrrev_i32_e32 v1, 31, v0
	v_lshlrev_b64 v[0:1], 11, v[0:1]
	v_lshl_add_u64 v[0:1], v[8:9], 0, v[0:1]
	s_waitcnt lgkmcnt(0)
	global_store_dwordx4 v[0:1], v[4:7], off
	ds_read_b128 v[0:3], v165 offset:6912
	s_nop 0
	v_add_u32_e32 v4, v12, v156
	v_ashrrev_i32_e32 v5, 31, v4
	v_lshlrev_b64 v[4:5], 11, v[4:5]
	v_lshl_add_u64 v[10:11], v[8:9], 0, v[4:5]
	ds_read_b128 v[4:7], v165 offset:8064
	s_waitcnt lgkmcnt(1)
	global_store_dwordx4 v[10:11], v[0:3], off
	s_nop 1
	v_add_u32_e32 v0, v12, v157
	v_ashrrev_i32_e32 v1, 31, v0
	v_lshlrev_b64 v[0:1], 11, v[0:1]
	v_lshl_add_u64 v[0:1], v[8:9], 0, v[0:1]
	s_waitcnt lgkmcnt(0)
	global_store_dwordx4 v[0:1], v[4:7], off
	ds_read_b128 v[0:3], v165 offset:9216
	s_nop 0
	v_add_u32_e32 v4, v12, v158
	v_ashrrev_i32_e32 v5, 31, v4
	v_lshlrev_b64 v[4:5], 11, v[4:5]
	v_lshl_add_u64 v[10:11], v[8:9], 0, v[4:5]
	ds_read_b128 v[4:7], v165 offset:10368
	s_waitcnt lgkmcnt(1)
	global_store_dwordx4 v[10:11], v[0:3], off
	s_nop 1
	v_add_u32_e32 v0, v12, v159
	v_ashrrev_i32_e32 v1, 31, v0
	v_lshlrev_b64 v[0:1], 11, v[0:1]
	v_lshl_add_u64 v[0:1], v[8:9], 0, v[0:1]
	s_waitcnt lgkmcnt(0)
	global_store_dwordx4 v[0:1], v[4:7], off
	ds_read_b128 v[0:3], v165 offset:11520
	s_nop 0
	v_add_u32_e32 v4, v12, v160
	v_ashrrev_i32_e32 v5, 31, v4
	v_lshlrev_b64 v[4:5], 11, v[4:5]
	v_lshl_add_u64 v[10:11], v[8:9], 0, v[4:5]
	ds_read_b128 v[4:7], v165 offset:12672
	s_waitcnt lgkmcnt(1)
	global_store_dwordx4 v[10:11], v[0:3], off
	s_nop 1
	v_add_u32_e32 v0, v12, v161
	v_ashrrev_i32_e32 v1, 31, v0
	v_lshlrev_b64 v[0:1], 11, v[0:1]
	v_lshl_add_u64 v[0:1], v[8:9], 0, v[0:1]
	s_waitcnt lgkmcnt(0)
	global_store_dwordx4 v[0:1], v[4:7], off
	s_cbranch_scc1 .LBB0_1118

.Lg6p13_loop:
	s_waitcnt vmcnt(0) lgkmcnt(0)
	s_barrier
	s_add_u32 m0, s8, 0
	ds_read_b128 v[120:123], v248 offset:40960
	global_load_lds_dwordx4 v240, s[98:99]
	s_add_u32 m0, s8, 4096
	ds_read_b128 v[124:127], v248 offset:43008
	global_load_lds_dwordx4 v241, s[98:99]
	s_add_u32 m0, s8, 8192
	ds_read_b128 v[128:131], v248 offset:45056
	global_load_lds_dwordx4 v242, s[98:99]
	s_add_u32 m0, s8, 12288
	ds_read_b128 v[132:135], v248 offset:47104
	global_load_lds_dwordx4 v243, s[98:99]
	s_add_u32 m0, s8, 16384
	ds_read_b128 v[96:99], v246 offset:40960
	global_load_lds_dwordx4 v244, s[98:99]
	s_add_u32 m0, s8, 20480
	ds_read_b128 v[100:103], v246 offset:43008
	global_load_lds_dwordx4 v245, s[98:99]
	s_add_u32 m0, s8, 24576
	ds_read_b128 v[104:107], v246 offset:45056
	global_load_lds_dwordx4 v240, s[100:101]
	s_add_u32 m0, s8, 28672
	ds_read_b128 v[108:111], v246 offset:47104
	global_load_lds_dwordx4 v241, s[100:101]
	s_add_u32 m0, s8, 32768
	ds_read_b128 v[112:115], v246 offset:49152
	global_load_lds_dwordx4 v242, s[100:101]
	s_add_u32 m0, s8, 36864
	ds_read_b128 v[116:119], v246 offset:51200
	global_load_lds_dwordx4 v243, s[100:101]
	s_add_u32 s98, s98, 0x80
	s_addc_u32 s99, s99, 0
	s_add_u32 s100, s100, 0x80
	s_addc_u32 s101, s101, 0
	v_mfma_f32_16x16x32_bf16 v[92:95], v[224:227], v[200:203], v[92:95]
	v_mfma_f32_16x16x32_bf16 v[88:91], v[228:231], v[200:203], v[88:91]
	v_mfma_f32_16x16x32_bf16 v[84:87], v[232:235], v[200:203], v[84:87]
	v_mfma_f32_16x16x32_bf16 v[80:83], v[236:239], v[200:203], v[80:83]
	v_mfma_f32_16x16x32_bf16 v[76:79], v[224:227], v[204:207], v[76:79]
	v_mfma_f32_16x16x32_bf16 v[72:75], v[228:231], v[204:207], v[72:75]
	v_mfma_f32_16x16x32_bf16 v[68:71], v[232:235], v[204:207], v[68:71]
	v_mfma_f32_16x16x32_bf16 v[60:63], v[236:239], v[204:207], v[60:63]
	v_mfma_f32_16x16x32_bf16 v[56:59], v[224:227], v[208:211], v[56:59]
	v_mfma_f32_16x16x32_bf16 v[52:55], v[228:231], v[208:211], v[52:55]
	v_mfma_f32_16x16x32_bf16 v[48:51], v[232:235], v[208:211], v[48:51]
	v_mfma_f32_16x16x32_bf16 v[44:47], v[236:239], v[208:211], v[44:47]
	v_mfma_f32_16x16x32_bf16 v[40:43], v[224:227], v[212:215], v[40:43]
	v_mfma_f32_16x16x32_bf16 v[36:39], v[228:231], v[212:215], v[36:39]
	v_mfma_f32_16x16x32_bf16 v[32:35], v[232:235], v[212:215], v[32:35]
	v_mfma_f32_16x16x32_bf16 v[28:31], v[236:239], v[212:215], v[28:31]
	v_mfma_f32_16x16x32_bf16 v[24:27], v[224:227], v[216:219], v[24:27]
	v_mfma_f32_16x16x32_bf16 v[20:23], v[228:231], v[216:219], v[20:23]
	v_mfma_f32_16x16x32_bf16 v[16:19], v[232:235], v[216:219], v[16:19]
	v_mfma_f32_16x16x32_bf16 v[12:15], v[236:239], v[216:219], v[12:15]
	v_mfma_f32_16x16x32_bf16 v[8:11], v[224:227], v[220:223], v[8:11]
	v_mfma_f32_16x16x32_bf16 v[4:7], v[228:231], v[220:223], v[4:7]
	v_mfma_f32_16x16x32_bf16 v[0:3], v[232:235], v[220:223], v[0:3]
	v_mfma_f32_16x16x32_bf16 v[64:67], v[236:239], v[220:223], v[64:67]
	s_waitcnt lgkmcnt(0)
	v_mfma_f32_16x16x32_bf16 v[92:95], v[120:123], v[96:99], v[92:95]
	v_mfma_f32_16x16x32_bf16 v[88:91], v[124:127], v[96:99], v[88:91]
	ds_read_b128 v[224:227], v249 offset:40960
	v_mfma_f32_16x16x32_bf16 v[84:87], v[128:131], v[96:99], v[84:87]
	v_mfma_f32_16x16x32_bf16 v[80:83], v[132:135], v[96:99], v[80:83]
	ds_read_b128 v[228:231], v249 offset:43008
	v_mfma_f32_16x16x32_bf16 v[76:79], v[120:123], v[100:103], v[76:79]
	v_mfma_f32_16x16x32_bf16 v[72:75], v[124:127], v[100:103], v[72:75]
	ds_read_b128 v[232:235], v249 offset:45056
	v_mfma_f32_16x16x32_bf16 v[68:71], v[128:131], v[100:103], v[68:71]
	v_mfma_f32_16x16x32_bf16 v[60:63], v[132:135], v[100:103], v[60:63]
	ds_read_b128 v[236:239], v249 offset:47104
	v_mfma_f32_16x16x32_bf16 v[56:59], v[120:123], v[104:107], v[56:59]
	v_mfma_f32_16x16x32_bf16 v[52:55], v[124:127], v[104:107], v[52:55]
	ds_read_b128 v[200:203], v247 offset:40960
	v_mfma_f32_16x16x32_bf16 v[48:51], v[128:131], v[104:107], v[48:51]
	v_mfma_f32_16x16x32_bf16 v[44:47], v[132:135], v[104:107], v[44:47]
	ds_read_b128 v[204:207], v247 offset:43008
	v_mfma_f32_16x16x32_bf16 v[40:43], v[120:123], v[108:111], v[40:43]
	v_mfma_f32_16x16x32_bf16 v[36:39], v[124:127], v[108:111], v[36:39]
	ds_read_b128 v[208:211], v247 offset:45056
	v_mfma_f32_16x16x32_bf16 v[32:35], v[128:131], v[108:111], v[32:35]
	v_mfma_f32_16x16x32_bf16 v[28:31], v[132:135], v[108:111], v[28:31]
	ds_read_b128 v[212:215], v247 offset:47104
	v_mfma_f32_16x16x32_bf16 v[24:27], v[120:123], v[112:115], v[24:27]
	v_mfma_f32_16x16x32_bf16 v[20:23], v[124:127], v[112:115], v[20:23]
	ds_read_b128 v[216:219], v247 offset:49152
	v_mfma_f32_16x16x32_bf16 v[16:19], v[128:131], v[112:115], v[16:19]
	v_mfma_f32_16x16x32_bf16 v[12:15], v[132:135], v[112:115], v[12:15]
	ds_read_b128 v[220:223], v247 offset:51200
	v_mfma_f32_16x16x32_bf16 v[8:11], v[120:123], v[116:119], v[8:11]
	v_mfma_f32_16x16x32_bf16 v[4:7], v[124:127], v[116:119], v[4:7]
	v_mfma_f32_16x16x32_bf16 v[0:3], v[128:131], v[116:119], v[0:3]
	v_mfma_f32_16x16x32_bf16 v[64:67], v[132:135], v[116:119], v[64:67]
	s_waitcnt vmcnt(0) lgkmcnt(0)
	s_barrier
	s_add_u32 m0, s8, 40960
	ds_read_b128 v[120:123], v248 offset:0
	global_load_lds_dwordx4 v240, s[98:99]
	s_add_u32 m0, s8, 45056
	ds_read_b128 v[124:127], v248 offset:2048
	global_load_lds_dwordx4 v241, s[98:99]
	s_add_u32 m0, s8, 49152
	ds_read_b128 v[128:131], v248 offset:4096
	global_load_lds_dwordx4 v242, s[98:99]
	s_add_u32 m0, s8, 53248
	ds_read_b128 v[132:135], v248 offset:6144
	global_load_lds_dwordx4 v243, s[98:99]
	s_add_u32 m0, s8, 57344
	ds_read_b128 v[96:99], v246 offset:0
	global_load_lds_dwordx4 v244, s[98:99]
	s_add_u32 m0, s8, 61440
	ds_read_b128 v[100:103], v246 offset:2048
	global_load_lds_dwordx4 v245, s[98:99]
	s_add_u32 m0, s8, 65536
	ds_read_b128 v[104:107], v246 offset:4096
	global_load_lds_dwordx4 v240, s[100:101]
	s_add_u32 m0, s8, 69632
	ds_read_b128 v[108:111], v246 offset:6144
	global_load_lds_dwordx4 v241, s[100:101]
	s_add_u32 m0, s8, 73728
	ds_read_b128 v[112:115], v246 offset:8192
	global_load_lds_dwordx4 v242, s[100:101]
	s_add_u32 m0, s8, 77824
	ds_read_b128 v[116:119], v246 offset:10240
	global_load_lds_dwordx4 v243, s[100:101]
	s_add_u32 s98, s98, 0x80
	s_addc_u32 s99, s99, 0
	s_add_u32 s100, s100, 0x80
	s_addc_u32 s101, s101, 0
	v_mfma_f32_16x16x32_bf16 v[92:95], v[224:227], v[200:203], v[92:95]
	v_mfma_f32_16x16x32_bf16 v[88:91], v[228:231], v[200:203], v[88:91]
	v_mfma_f32_16x16x32_bf16 v[84:87], v[232:235], v[200:203], v[84:87]
	v_mfma_f32_16x16x32_bf16 v[80:83], v[236:239], v[200:203], v[80:83]
	v_mfma_f32_16x16x32_bf16 v[76:79], v[224:227], v[204:207], v[76:79]
	v_mfma_f32_16x16x32_bf16 v[72:75], v[228:231], v[204:207], v[72:75]
	v_mfma_f32_16x16x32_bf16 v[68:71], v[232:235], v[204:207], v[68:71]
	v_mfma_f32_16x16x32_bf16 v[60:63], v[236:239], v[204:207], v[60:63]
	v_mfma_f32_16x16x32_bf16 v[56:59], v[224:227], v[208:211], v[56:59]
	v_mfma_f32_16x16x32_bf16 v[52:55], v[228:231], v[208:211], v[52:55]
	v_mfma_f32_16x16x32_bf16 v[48:51], v[232:235], v[208:211], v[48:51]
	v_mfma_f32_16x16x32_bf16 v[44:47], v[236:239], v[208:211], v[44:47]
	v_mfma_f32_16x16x32_bf16 v[40:43], v[224:227], v[212:215], v[40:43]
	v_mfma_f32_16x16x32_bf16 v[36:39], v[228:231], v[212:215], v[36:39]
	v_mfma_f32_16x16x32_bf16 v[32:35], v[232:235], v[212:215], v[32:35]
	v_mfma_f32_16x16x32_bf16 v[28:31], v[236:239], v[212:215], v[28:31]
	v_mfma_f32_16x16x32_bf16 v[24:27], v[224:227], v[216:219], v[24:27]
	v_mfma_f32_16x16x32_bf16 v[20:23], v[228:231], v[216:219], v[20:23]
	v_mfma_f32_16x16x32_bf16 v[16:19], v[232:235], v[216:219], v[16:19]
	v_mfma_f32_16x16x32_bf16 v[12:15], v[236:239], v[216:219], v[12:15]
	v_mfma_f32_16x16x32_bf16 v[8:11], v[224:227], v[220:223], v[8:11]
	v_mfma_f32_16x16x32_bf16 v[4:7], v[228:231], v[220:223], v[4:7]
	v_mfma_f32_16x16x32_bf16 v[0:3], v[232:235], v[220:223], v[0:3]
	v_mfma_f32_16x16x32_bf16 v[64:67], v[236:239], v[220:223], v[64:67]
	s_waitcnt lgkmcnt(0)
	v_mfma_f32_16x16x32_bf16 v[92:95], v[120:123], v[96:99], v[92:95]
	v_mfma_f32_16x16x32_bf16 v[88:91], v[124:127], v[96:99], v[88:91]
	ds_read_b128 v[224:227], v249 offset:0
	v_mfma_f32_16x16x32_bf16 v[84:87], v[128:131], v[96:99], v[84:87]
	v_mfma_f32_16x16x32_bf16 v[80:83], v[132:135], v[96:99], v[80:83]
	ds_read_b128 v[228:231], v249 offset:2048
	v_mfma_f32_16x16x32_bf16 v[76:79], v[120:123], v[100:103], v[76:79]
	v_mfma_f32_16x16x32_bf16 v[72:75], v[124:127], v[100:103], v[72:75]
	ds_read_b128 v[232:235], v249 offset:4096
	v_mfma_f32_16x16x32_bf16 v[68:71], v[128:131], v[100:103], v[68:71]
	v_mfma_f32_16x16x32_bf16 v[60:63], v[132:135], v[100:103], v[60:63]
	ds_read_b128 v[236:239], v249 offset:6144
	v_mfma_f32_16x16x32_bf16 v[56:59], v[120:123], v[104:107], v[56:59]
	v_mfma_f32_16x16x32_bf16 v[52:55], v[124:127], v[104:107], v[52:55]
	ds_read_b128 v[200:203], v247 offset:0
	v_mfma_f32_16x16x32_bf16 v[48:51], v[128:131], v[104:107], v[48:51]
	v_mfma_f32_16x16x32_bf16 v[44:47], v[132:135], v[104:107], v[44:47]
	ds_read_b128 v[204:207], v247 offset:2048
	v_mfma_f32_16x16x32_bf16 v[40:43], v[120:123], v[108:111], v[40:43]
	v_mfma_f32_16x16x32_bf16 v[36:39], v[124:127], v[108:111], v[36:39]
	ds_read_b128 v[208:211], v247 offset:4096
	v_mfma_f32_16x16x32_bf16 v[32:35], v[128:131], v[108:111], v[32:35]
	v_mfma_f32_16x16x32_bf16 v[28:31], v[132:135], v[108:111], v[28:31]
	ds_read_b128 v[212:215], v247 offset:6144
	v_mfma_f32_16x16x32_bf16 v[24:27], v[120:123], v[112:115], v[24:27]
	v_mfma_f32_16x16x32_bf16 v[20:23], v[124:127], v[112:115], v[20:23]
	ds_read_b128 v[216:219], v247 offset:8192
	v_mfma_f32_16x16x32_bf16 v[16:19], v[128:131], v[112:115], v[16:19]
	v_mfma_f32_16x16x32_bf16 v[12:15], v[132:135], v[112:115], v[12:15]
	ds_read_b128 v[220:223], v247 offset:10240
	v_mfma_f32_16x16x32_bf16 v[8:11], v[120:123], v[116:119], v[8:11]
	v_mfma_f32_16x16x32_bf16 v[4:7], v[124:127], v[116:119], v[4:7]
	v_mfma_f32_16x16x32_bf16 v[0:3], v[128:131], v[116:119], v[0:3]
	v_mfma_f32_16x16x32_bf16 v[64:67], v[132:135], v[116:119], v[64:67]
	s_sub_u32 s9, s9, 1
	s_cmp_lg_u32 s9, 0
	s_cbranch_scc1 .Lg6p13_loop
	s_waitcnt vmcnt(0) lgkmcnt(0)
	s_barrier
	ds_read_b128 v[120:123], v248 offset:40960
	ds_read_b128 v[124:127], v248 offset:43008
	ds_read_b128 v[128:131], v248 offset:45056
	ds_read_b128 v[132:135], v248 offset:47104
	ds_read_b128 v[96:99], v246 offset:40960
	ds_read_b128 v[100:103], v246 offset:43008
	ds_read_b128 v[104:107], v246 offset:45056
	ds_read_b128 v[108:111], v246 offset:47104
	ds_read_b128 v[112:115], v246 offset:49152
	ds_read_b128 v[116:119], v246 offset:51200
	v_mfma_f32_16x16x32_bf16 v[92:95], v[224:227], v[200:203], v[92:95]
	v_mfma_f32_16x16x32_bf16 v[88:91], v[228:231], v[200:203], v[88:91]
	v_mfma_f32_16x16x32_bf16 v[84:87], v[232:235], v[200:203], v[84:87]
	v_mfma_f32_16x16x32_bf16 v[80:83], v[236:239], v[200:203], v[80:83]
	v_mfma_f32_16x16x32_bf16 v[76:79], v[224:227], v[204:207], v[76:79]
	v_mfma_f32_16x16x32_bf16 v[72:75], v[228:231], v[204:207], v[72:75]
	v_mfma_f32_16x16x32_bf16 v[68:71], v[232:235], v[204:207], v[68:71]
	v_mfma_f32_16x16x32_bf16 v[60:63], v[236:239], v[204:207], v[60:63]
	v_mfma_f32_16x16x32_bf16 v[56:59], v[224:227], v[208:211], v[56:59]
	v_mfma_f32_16x16x32_bf16 v[52:55], v[228:231], v[208:211], v[52:55]
	v_mfma_f32_16x16x32_bf16 v[48:51], v[232:235], v[208:211], v[48:51]
	v_mfma_f32_16x16x32_bf16 v[44:47], v[236:239], v[208:211], v[44:47]
	v_mfma_f32_16x16x32_bf16 v[40:43], v[224:227], v[212:215], v[40:43]
	v_mfma_f32_16x16x32_bf16 v[36:39], v[228:231], v[212:215], v[36:39]
	v_mfma_f32_16x16x32_bf16 v[32:35], v[232:235], v[212:215], v[32:35]
	v_mfma_f32_16x16x32_bf16 v[28:31], v[236:239], v[212:215], v[28:31]
	v_mfma_f32_16x16x32_bf16 v[24:27], v[224:227], v[216:219], v[24:27]
	v_mfma_f32_16x16x32_bf16 v[20:23], v[228:231], v[216:219], v[20:23]
	v_mfma_f32_16x16x32_bf16 v[16:19], v[232:235], v[216:219], v[16:19]
	v_mfma_f32_16x16x32_bf16 v[12:15], v[236:239], v[216:219], v[12:15]
	v_mfma_f32_16x16x32_bf16 v[8:11], v[224:227], v[220:223], v[8:11]
	v_mfma_f32_16x16x32_bf16 v[4:7], v[228:231], v[220:223], v[4:7]
	v_mfma_f32_16x16x32_bf16 v[0:3], v[232:235], v[220:223], v[0:3]
	v_mfma_f32_16x16x32_bf16 v[64:67], v[236:239], v[220:223], v[64:67]
	s_waitcnt lgkmcnt(0)
	v_mfma_f32_16x16x32_bf16 v[92:95], v[120:123], v[96:99], v[92:95]
	v_mfma_f32_16x16x32_bf16 v[88:91], v[124:127], v[96:99], v[88:91]
	ds_read_b128 v[224:227], v249 offset:40960
	v_mfma_f32_16x16x32_bf16 v[84:87], v[128:131], v[96:99], v[84:87]
	v_mfma_f32_16x16x32_bf16 v[80:83], v[132:135], v[96:99], v[80:83]
	ds_read_b128 v[228:231], v249 offset:43008
	v_mfma_f32_16x16x32_bf16 v[76:79], v[120:123], v[100:103], v[76:79]
	v_mfma_f32_16x16x32_bf16 v[72:75], v[124:127], v[100:103], v[72:75]
	ds_read_b128 v[232:235], v249 offset:45056
	v_mfma_f32_16x16x32_bf16 v[68:71], v[128:131], v[100:103], v[68:71]
	v_mfma_f32_16x16x32_bf16 v[60:63], v[132:135], v[100:103], v[60:63]
	ds_read_b128 v[236:239], v249 offset:47104
	v_mfma_f32_16x16x32_bf16 v[56:59], v[120:123], v[104:107], v[56:59]
	v_mfma_f32_16x16x32_bf16 v[52:55], v[124:127], v[104:107], v[52:55]
	ds_read_b128 v[200:203], v247 offset:40960
	v_mfma_f32_16x16x32_bf16 v[48:51], v[128:131], v[104:107], v[48:51]
	v_mfma_f32_16x16x32_bf16 v[44:47], v[132:135], v[104:107], v[44:47]
	ds_read_b128 v[204:207], v247 offset:43008
	v_mfma_f32_16x16x32_bf16 v[40:43], v[120:123], v[108:111], v[40:43]
	v_mfma_f32_16x16x32_bf16 v[36:39], v[124:127], v[108:111], v[36:39]
	ds_read_b128 v[208:211], v247 offset:45056
	v_mfma_f32_16x16x32_bf16 v[32:35], v[128:131], v[108:111], v[32:35]
	v_mfma_f32_16x16x32_bf16 v[28:31], v[132:135], v[108:111], v[28:31]
	ds_read_b128 v[212:215], v247 offset:47104
	v_mfma_f32_16x16x32_bf16 v[24:27], v[120:123], v[112:115], v[24:27]
	v_mfma_f32_16x16x32_bf16 v[20:23], v[124:127], v[112:115], v[20:23]
	ds_read_b128 v[216:219], v247 offset:49152
	v_mfma_f32_16x16x32_bf16 v[16:19], v[128:131], v[112:115], v[16:19]
	v_mfma_f32_16x16x32_bf16 v[12:15], v[132:135], v[112:115], v[12:15]
	ds_read_b128 v[220:223], v247 offset:51200
	v_mfma_f32_16x16x32_bf16 v[8:11], v[120:123], v[116:119], v[8:11]
	v_mfma_f32_16x16x32_bf16 v[4:7], v[124:127], v[116:119], v[4:7]
	v_mfma_f32_16x16x32_bf16 v[0:3], v[128:131], v[116:119], v[0:3]
	v_mfma_f32_16x16x32_bf16 v[64:67], v[132:135], v[116:119], v[64:67]
	s_waitcnt lgkmcnt(0)
	v_mfma_f32_16x16x32_bf16 v[92:95], v[224:227], v[200:203], v[92:95]
	v_mfma_f32_16x16x32_bf16 v[88:91], v[228:231], v[200:203], v[88:91]
	v_mfma_f32_16x16x32_bf16 v[84:87], v[232:235], v[200:203], v[84:87]
	v_mfma_f32_16x16x32_bf16 v[80:83], v[236:239], v[200:203], v[80:83]
	v_mfma_f32_16x16x32_bf16 v[76:79], v[224:227], v[204:207], v[76:79]
	v_mfma_f32_16x16x32_bf16 v[72:75], v[228:231], v[204:207], v[72:75]
	v_mfma_f32_16x16x32_bf16 v[68:71], v[232:235], v[204:207], v[68:71]
	v_mfma_f32_16x16x32_bf16 v[60:63], v[236:239], v[204:207], v[60:63]
	v_mfma_f32_16x16x32_bf16 v[56:59], v[224:227], v[208:211], v[56:59]
	v_mfma_f32_16x16x32_bf16 v[52:55], v[228:231], v[208:211], v[52:55]
	v_mfma_f32_16x16x32_bf16 v[48:51], v[232:235], v[208:211], v[48:51]
	v_mfma_f32_16x16x32_bf16 v[44:47], v[236:239], v[208:211], v[44:47]
	v_mfma_f32_16x16x32_bf16 v[40:43], v[224:227], v[212:215], v[40:43]
	v_mfma_f32_16x16x32_bf16 v[36:39], v[228:231], v[212:215], v[36:39]
	v_mfma_f32_16x16x32_bf16 v[32:35], v[232:235], v[212:215], v[32:35]
	v_mfma_f32_16x16x32_bf16 v[28:31], v[236:239], v[212:215], v[28:31]
	v_mfma_f32_16x16x32_bf16 v[24:27], v[224:227], v[216:219], v[24:27]
	v_mfma_f32_16x16x32_bf16 v[20:23], v[228:231], v[216:219], v[20:23]
	v_mfma_f32_16x16x32_bf16 v[16:19], v[232:235], v[216:219], v[16:19]
	v_mfma_f32_16x16x32_bf16 v[12:15], v[236:239], v[216:219], v[12:15]
	v_mfma_f32_16x16x32_bf16 v[8:11], v[224:227], v[220:223], v[8:11]
	v_mfma_f32_16x16x32_bf16 v[4:7], v[228:231], v[220:223], v[4:7]
	v_mfma_f32_16x16x32_bf16 v[0:3], v[232:235], v[220:223], v[0:3]
	v_mfma_f32_16x16x32_bf16 v[64:67], v[236:239], v[220:223], v[64:67]
	s_nop 7
	s_nop 7
	s_barrier
	ds_write_b64 v252, v[250:251]
	s_add_i32 s13, s13, s12
	s_ashr_i32 s4, s13, 6
	s_mul_i32 s4, s4, s11
	s_add_i32 s8, s4, s10
	s_add_i32 s14, s14, s15
	s_add_i32 s16, s16, s17
	s_cmp_lt_i32 s8, 8
	v_cvt_pk_bf16_f32 v8, v8, v9
	v_cvt_pk_bf16_f32 v9, v10, v11
	v_cvt_pk_bf16_f32 v4, v4, v5
	v_cvt_pk_bf16_f32 v5, v6, v7
	v_add_u32_e32 v6, 0x2800, v162
	ds_write2_b64 v6, v[8:9], v[4:5] offset0:160 offset1:164
	v_cvt_pk_bf16_f32 v4, v0, v1
	v_cvt_pk_bf16_f32 v5, v2, v3
	v_cvt_pk_bf16_f32 v92, v92, v93
	v_cvt_pk_bf16_f32 v93, v94, v95
	v_cvt_pk_bf16_f32 v88, v88, v89
	v_cvt_pk_bf16_f32 v89, v90, v91
	ds_write2_b64 v162, v[92:93], v[88:89] offset1:4
	v_cvt_pk_bf16_f32 v84, v84, v85
	v_cvt_pk_bf16_f32 v85, v86, v87
	v_cvt_pk_bf16_f32 v80, v80, v81
	v_cvt_pk_bf16_f32 v81, v82, v83
	v_cvt_pk_bf16_f32 v76, v76, v77
	v_cvt_pk_bf16_f32 v77, v78, v79
	v_cvt_pk_bf16_f32 v72, v72, v73
	v_cvt_pk_bf16_f32 v73, v74, v75
	v_add_u32_e32 v74, 0x800, v162
	v_cvt_pk_bf16_f32 v68, v68, v69
	v_cvt_pk_bf16_f32 v69, v70, v71
	ds_write2_b64 v162, v[84:85], v[80:81] offset0:8 offset1:12
	v_cvt_pk_bf16_f32 v60, v60, v61
	v_cvt_pk_bf16_f32 v61, v62, v63
	ds_write2_b64 v74, v[76:77], v[72:73] offset0:32 offset1:36
	v_cvt_pk_bf16_f32 v56, v56, v57
	v_cvt_pk_bf16_f32 v57, v58, v59
	ds_write2_b64 v74, v[68:69], v[60:61] offset0:40 offset1:44
	v_cvt_pk_bf16_f32 v52, v52, v53
	v_cvt_pk_bf16_f32 v53, v54, v55
	v_add_u32_e32 v54, 0x1000, v162
	v_cvt_pk_bf16_f32 v48, v48, v49
	v_cvt_pk_bf16_f32 v49, v50, v51
	ds_write2_b64 v54, v[56:57], v[52:53] offset0:64 offset1:68
	v_cvt_pk_bf16_f32 v44, v44, v45
	v_cvt_pk_bf16_f32 v45, v46, v47
	ds_write2_b64 v54, v[48:49], v[44:45] offset0:72 offset1:76
	v_cvt_pk_bf16_f32 v40, v40, v41
	v_cvt_pk_bf16_f32 v41, v42, v43
	v_cvt_pk_bf16_f32 v36, v36, v37
	v_cvt_pk_bf16_f32 v37, v38, v39
	v_add_u32_e32 v38, 0x1800, v162
	v_cvt_pk_bf16_f32 v32, v32, v33
	v_cvt_pk_bf16_f32 v33, v34, v35
	v_cvt_pk_bf16_f32 v28, v28, v29
	v_cvt_pk_bf16_f32 v29, v30, v31
	v_cvt_pk_bf16_f32 v24, v24, v25
	v_cvt_pk_bf16_f32 v25, v26, v27
	ds_write2_b64 v38, v[40:41], v[36:37] offset0:96 offset1:100
	v_cvt_pk_bf16_f32 v20, v20, v21
	v_cvt_pk_bf16_f32 v21, v22, v23
	v_add_u32_e32 v22, 0x2000, v162
	v_cvt_pk_bf16_f32 v16, v16, v17
	v_cvt_pk_bf16_f32 v17, v18, v19
	v_mov_b32_e32 v0, v64
	v_mov_b32_e32 v1, v65
	v_mov_b32_e32 v2, v66
	v_mov_b32_e32 v3, v67
	ds_write2_b64 v38, v[32:33], v[28:29] offset0:104 offset1:108
	s_nop 2
	v_cvt_pk_bf16_f32 v12, v12, v13
	v_cvt_pk_bf16_f32 v13, v14, v15
	ds_write2_b64 v22, v[24:25], v[20:21] offset0:128 offset1:132
	ds_write2_b64 v22, v[16:17], v[12:13] offset0:136 offset1:140
	v_cvt_pk_bf16_f32 v0, v0, v1
	v_cvt_pk_bf16_f32 v1, v2, v3
	ds_write2_b64 v6, v[4:5], v[0:1] offset0:168 offset1:172
	s_waitcnt lgkmcnt(0)
	v_or_b32_e32 v0, s33, v150
	v_add_u32_e32 v12, s6, v148
	v_lshlrev_b32_e32 v136, 1, v0
	ds_read_b128 v[0:3], v163
	v_or_b32_e32 v4, v12, v149
	v_ashrrev_i32_e32 v5, 31, v4
	v_lshl_add_u64 v[8:9], s[2:3], 0, v[136:137]
	v_lshlrev_b64 v[4:5], 11, v[4:5]
	v_lshl_add_u64 v[10:11], v[8:9], 0, v[4:5]
	ds_read_b128 v[4:7], v163 offset:1152
	s_waitcnt lgkmcnt(1)
	global_store_dwordx4 v[10:11], v[0:3], off
	s_nop 1
	v_or_b32_e32 v0, v12, v151
	v_ashrrev_i32_e32 v1, 31, v0
	v_lshlrev_b64 v[0:1], 11, v[0:1]
	v_lshl_add_u64 v[0:1], v[8:9], 0, v[0:1]
	s_waitcnt lgkmcnt(0)
	global_store_dwordx4 v[0:1], v[4:7], off
	ds_read_b128 v[0:3], v163 offset:2304
	s_nop 0
	v_or_b32_e32 v4, v12, v152
	v_ashrrev_i32_e32 v5, 31, v4
	v_lshlrev_b64 v[4:5], 11, v[4:5]
	v_lshl_add_u64 v[10:11], v[8:9], 0, v[4:5]
	ds_read_b128 v[4:7], v163 offset:3456
	s_waitcnt lgkmcnt(1)
	global_store_dwordx4 v[10:11], v[0:3], off
	s_nop 1
	v_or_b32_e32 v0, v12, v153
	v_ashrrev_i32_e32 v1, 31, v0
	v_lshlrev_b64 v[0:1], 11, v[0:1]
	v_lshl_add_u64 v[0:1], v[8:9], 0, v[0:1]
	s_waitcnt lgkmcnt(0)
	global_store_dwordx4 v[0:1], v[4:7], off
	ds_read_b128 v[0:3], v163 offset:4608
	s_nop 0
	v_add_u32_e32 v4, v12, v154
	v_ashrrev_i32_e32 v5, 31, v4
	v_lshlrev_b64 v[4:5], 11, v[4:5]
	v_lshl_add_u64 v[10:11], v[8:9], 0, v[4:5]
	ds_read_b128 v[4:7], v163 offset:5760
	s_waitcnt lgkmcnt(1)
	global_store_dwordx4 v[10:11], v[0:3], off
	s_nop 1
	v_add_u32_e32 v0, v12, v155
	v_ashrrev_i32_e32 v1, 31, v0
	v_lshlrev_b64 v[0:1], 11, v[0:1]
	v_lshl_add_u64 v[0:1], v[8:9], 0, v[0:1]
	s_waitcnt lgkmcnt(0)
	global_store_dwordx4 v[0:1], v[4:7], off
	ds_read_b128 v[0:3], v163 offset:6912
	s_nop 0
	v_add_u32_e32 v4, v12, v156
	v_ashrrev_i32_e32 v5, 31, v4
	v_lshlrev_b64 v[4:5], 11, v[4:5]
	v_lshl_add_u64 v[10:11], v[8:9], 0, v[4:5]
	ds_read_b128 v[4:7], v163 offset:8064
	s_waitcnt lgkmcnt(1)
	global_store_dwordx4 v[10:11], v[0:3], off
	s_nop 1
	v_add_u32_e32 v0, v12, v157
	v_ashrrev_i32_e32 v1, 31, v0
	v_lshlrev_b64 v[0:1], 11, v[0:1]
	v_lshl_add_u64 v[0:1], v[8:9], 0, v[0:1]
	s_waitcnt lgkmcnt(0)
	global_store_dwordx4 v[0:1], v[4:7], off
	ds_read_b128 v[0:3], v163 offset:9216
	s_nop 0
	v_add_u32_e32 v4, v12, v158
	v_ashrrev_i32_e32 v5, 31, v4
	v_lshlrev_b64 v[4:5], 11, v[4:5]
	v_lshl_add_u64 v[10:11], v[8:9], 0, v[4:5]
	ds_read_b128 v[4:7], v163 offset:10368
	s_waitcnt lgkmcnt(1)
	global_store_dwordx4 v[10:11], v[0:3], off
	s_nop 1
	v_add_u32_e32 v0, v12, v159
	v_ashrrev_i32_e32 v1, 31, v0
	v_lshlrev_b64 v[0:1], 11, v[0:1]
	v_lshl_add_u64 v[0:1], v[8:9], 0, v[0:1]
	s_waitcnt lgkmcnt(0)
	global_store_dwordx4 v[0:1], v[4:7], off
	ds_read_b128 v[0:3], v163 offset:11520
	s_nop 0
	v_add_u32_e32 v4, v12, v160
	v_ashrrev_i32_e32 v5, 31, v4
	v_lshlrev_b64 v[4:5], 11, v[4:5]
	v_lshl_add_u64 v[10:11], v[8:9], 0, v[4:5]
	ds_read_b128 v[4:7], v163 offset:12672
	s_waitcnt lgkmcnt(1)
	global_store_dwordx4 v[10:11], v[0:3], off
	s_nop 1
	v_add_u32_e32 v0, v12, v161
	v_ashrrev_i32_e32 v1, 31, v0
	v_lshlrev_b64 v[0:1], 11, v[0:1]
	v_lshl_add_u64 v[0:1], v[8:9], 0, v[0:1]
	s_waitcnt lgkmcnt(0)
	global_store_dwordx4 v[0:1], v[4:7], off
	s_cbranch_scc1 .LBB0_1774
